# K loop: fragment reads of steps 0/2/6 left in flight across the step barrier (drained after it), step 4 still drains before
# baseline (speedup 1.0000x reference)
.Lp1_skew0:
	ds_read_b128 v[130:133], v200 offset:0
	ds_read_b128 v[134:137], v200 offset:2048
	ds_read_b128 v[138:141], v200 offset:4096
	ds_read_b128 v[142:145], v200 offset:6144
	ds_read_b128 v[162:165], v202 offset:32768
	ds_read_b128 v[166:169], v202 offset:34816
	ds_read_b128 v[170:173], v202 offset:36864
	ds_read_b128 v[174:177], v202 offset:38912
	s_add_i32 m0, s18, 0x14000
	s_add_u32 s16, s12, 0x40080
	s_addc_u32 s17, s13, 0
	global_load_lds_dwordx4 v1, s[16:17]
	s_add_i32 m0, s18, 0x1a000
	s_add_u32 s16, s14, 0x20080
	s_addc_u32 s17, s15, 0
	global_load_lds_dwordx4 v1, s[16:17]
	s_barrier
	s_waitcnt lgkmcnt(0)
	v_mfma_f32_16x16x32_f16 v[126:129], v[162:165], v[130:133], 0
	v_mfma_f32_16x16x32_f16 v[122:125], v[166:169], v[130:133], 0
	v_mfma_f32_16x16x32_f16 v[118:121], v[170:173], v[130:133], 0
	v_mfma_f32_16x16x32_f16 v[114:117], v[174:177], v[130:133], 0
	v_mfma_f32_16x16x32_f16 v[110:113], v[162:165], v[134:137], 0
	v_mfma_f32_16x16x32_f16 v[106:109], v[166:169], v[134:137], 0
	v_mfma_f32_16x16x32_f16 v[102:105], v[170:173], v[134:137], 0
	v_mfma_f32_16x16x32_f16 v[98:101], v[174:177], v[134:137], 0
	v_mfma_f32_16x16x32_f16 v[94:97], v[162:165], v[138:141], 0
	v_mfma_f32_16x16x32_f16 v[90:93], v[166:169], v[138:141], 0
	v_mfma_f32_16x16x32_f16 v[86:89], v[170:173], v[138:141], 0
	v_mfma_f32_16x16x32_f16 v[82:85], v[174:177], v[138:141], 0
	v_mfma_f32_16x16x32_f16 v[78:81], v[162:165], v[142:145], 0
	v_mfma_f32_16x16x32_f16 v[74:77], v[166:169], v[142:145], 0
	v_mfma_f32_16x16x32_f16 v[70:73], v[170:173], v[142:145], 0
	v_mfma_f32_16x16x32_f16 v[66:69], v[174:177], v[142:145], 0
	s_barrier
	ds_read_b128 v[146:149], v200 offset:8192
	ds_read_b128 v[150:153], v200 offset:10240
	ds_read_b128 v[154:157], v200 offset:12288
	ds_read_b128 v[158:161], v200 offset:14336
	s_add_i32 m0, s18, 0x1c000
	s_add_u32 s16, s14, 0x40080
	s_addc_u32 s17, s15, 0
	global_load_lds_dwordx4 v1, s[16:17]
	s_add_i32 m0, s18, 0x1e000
	s_add_u32 s16, s14, 0x60080
	s_addc_u32 s17, s15, 0
	global_load_lds_dwordx4 v1, s[16:17]
	s_barrier
	s_waitcnt lgkmcnt(0)
	v_mfma_f32_16x16x32_f16 v[62:65], v[162:165], v[146:149], 0
	v_mfma_f32_16x16x32_f16 v[58:61], v[166:169], v[146:149], 0
	v_mfma_f32_16x16x32_f16 v[54:57], v[170:173], v[146:149], 0
	v_mfma_f32_16x16x32_f16 v[50:53], v[174:177], v[146:149], 0
	v_mfma_f32_16x16x32_f16 v[46:49], v[162:165], v[150:153], 0
	v_mfma_f32_16x16x32_f16 v[42:45], v[166:169], v[150:153], 0
	v_mfma_f32_16x16x32_f16 v[38:41], v[170:173], v[150:153], 0
	v_mfma_f32_16x16x32_f16 v[34:37], v[174:177], v[150:153], 0
	v_mfma_f32_16x16x32_f16 v[30:33], v[162:165], v[154:157], 0
	v_mfma_f32_16x16x32_f16 v[26:29], v[166:169], v[154:157], 0
	v_mfma_f32_16x16x32_f16 v[22:25], v[170:173], v[154:157], 0
	v_mfma_f32_16x16x32_f16 v[18:21], v[174:177], v[154:157], 0
	v_mfma_f32_16x16x32_f16 v[14:17], v[162:165], v[158:161], 0
	v_mfma_f32_16x16x32_f16 v[10:13], v[166:169], v[158:161], 0
	v_mfma_f32_16x16x32_f16 v[6:9], v[170:173], v[158:161], 0
	v_mfma_f32_16x16x32_f16 v[2:5], v[174:177], v[158:161], 0
	s_barrier
	ds_read_b128 v[130:133], v201 offset:0
	ds_read_b128 v[134:137], v201 offset:2048
	ds_read_b128 v[138:141], v201 offset:4096
	ds_read_b128 v[142:145], v201 offset:6144
	ds_read_b128 v[162:165], v203 offset:32768
	ds_read_b128 v[166:169], v203 offset:34816
	ds_read_b128 v[170:173], v203 offset:36864
	ds_read_b128 v[174:177], v203 offset:38912
	s_add_i32 m0, s18, 0x12000
	s_add_u32 s16, s12, 0x20080
	s_addc_u32 s17, s13, 0
	global_load_lds_dwordx4 v1, s[16:17]
	s_add_i32 m0, s18, 0x16000
	s_add_u32 s16, s12, 0x60080
	s_addc_u32 s17, s13, 0
	global_load_lds_dwordx4 v1, s[16:17]
	s_waitcnt lgkmcnt(0)
	s_barrier
	v_mfma_f32_16x16x32_f16 v[126:129], v[162:165], v[130:133], v[126:129]
	v_mfma_f32_16x16x32_f16 v[122:125], v[166:169], v[130:133], v[122:125]
	v_mfma_f32_16x16x32_f16 v[118:121], v[170:173], v[130:133], v[118:121]
	v_mfma_f32_16x16x32_f16 v[114:117], v[174:177], v[130:133], v[114:117]
	v_mfma_f32_16x16x32_f16 v[110:113], v[162:165], v[134:137], v[110:113]
	v_mfma_f32_16x16x32_f16 v[106:109], v[166:169], v[134:137], v[106:109]
	v_mfma_f32_16x16x32_f16 v[102:105], v[170:173], v[134:137], v[102:105]
	v_mfma_f32_16x16x32_f16 v[98:101], v[174:177], v[134:137], v[98:101]
	v_mfma_f32_16x16x32_f16 v[94:97], v[162:165], v[138:141], v[94:97]
	v_mfma_f32_16x16x32_f16 v[90:93], v[166:169], v[138:141], v[90:93]
	v_mfma_f32_16x16x32_f16 v[86:89], v[170:173], v[138:141], v[86:89]
	v_mfma_f32_16x16x32_f16 v[82:85], v[174:177], v[138:141], v[82:85]
	v_mfma_f32_16x16x32_f16 v[78:81], v[162:165], v[142:145], v[78:81]
	v_mfma_f32_16x16x32_f16 v[74:77], v[166:169], v[142:145], v[74:77]
	v_mfma_f32_16x16x32_f16 v[70:73], v[170:173], v[142:145], v[70:73]
	v_mfma_f32_16x16x32_f16 v[66:69], v[174:177], v[142:145], v[66:69]
	s_barrier
	ds_read_b128 v[146:149], v201 offset:8192
	ds_read_b128 v[150:153], v201 offset:10240
	ds_read_b128 v[154:157], v201 offset:12288
	ds_read_b128 v[158:161], v201 offset:14336
	s_mov_b32 m0, s18
	s_add_u32 s16, s12, 0x100
	s_addc_u32 s17, s13, 0
	global_load_lds_dwordx4 v1, s[16:17]
	s_add_i32 m0, s18, 0x8000
	s_add_u32 s16, s14, 0x100
	s_addc_u32 s17, s15, 0
	global_load_lds_dwordx4 v1, s[16:17]
	s_waitcnt vmcnt(4)
	s_barrier
	s_waitcnt lgkmcnt(0)
	v_mfma_f32_16x16x32_f16 v[62:65], v[162:165], v[146:149], v[62:65]
	v_mfma_f32_16x16x32_f16 v[58:61], v[166:169], v[146:149], v[58:61]
	v_mfma_f32_16x16x32_f16 v[54:57], v[170:173], v[146:149], v[54:57]
	v_mfma_f32_16x16x32_f16 v[50:53], v[174:177], v[146:149], v[50:53]
	v_mfma_f32_16x16x32_f16 v[46:49], v[162:165], v[150:153], v[46:49]
	v_mfma_f32_16x16x32_f16 v[42:45], v[166:169], v[150:153], v[42:45]
	v_mfma_f32_16x16x32_f16 v[38:41], v[170:173], v[150:153], v[38:41]
	v_mfma_f32_16x16x32_f16 v[34:37], v[174:177], v[150:153], v[34:37]
	v_mfma_f32_16x16x32_f16 v[30:33], v[162:165], v[154:157], v[30:33]
	v_mfma_f32_16x16x32_f16 v[26:29], v[166:169], v[154:157], v[26:29]
	v_mfma_f32_16x16x32_f16 v[22:25], v[170:173], v[154:157], v[22:25]
	v_mfma_f32_16x16x32_f16 v[18:21], v[174:177], v[154:157], v[18:21]
	v_mfma_f32_16x16x32_f16 v[14:17], v[162:165], v[158:161], v[14:17]
	v_mfma_f32_16x16x32_f16 v[10:13], v[166:169], v[158:161], v[10:13]
	v_mfma_f32_16x16x32_f16 v[6:9], v[170:173], v[158:161], v[6:9]
	v_mfma_f32_16x16x32_f16 v[2:5], v[174:177], v[158:161], v[2:5]
	s_barrier
	s_add_u32 s12, s12, 0x80
	s_addc_u32 s13, s13, 0
	s_add_u32 s14, s14, 0x80
	s_addc_u32 s15, s15, 0
	ds_read_b128 v[130:133], v204 offset:0
	ds_read_b128 v[134:137], v204 offset:2048
	ds_read_b128 v[138:141], v204 offset:4096
	ds_read_b128 v[142:145], v204 offset:6144
	ds_read_b128 v[162:165], v206 offset:32768
	ds_read_b128 v[166:169], v206 offset:34816
	ds_read_b128 v[170:173], v206 offset:36864
	ds_read_b128 v[174:177], v206 offset:38912
	s_add_i32 m0, s18, 0x4000
	s_add_u32 s16, s12, 0x40080
	s_addc_u32 s17, s13, 0
	global_load_lds_dwordx4 v1, s[16:17]
	s_add_i32 m0, s18, 0xa000
	s_add_u32 s16, s14, 0x20080
	s_addc_u32 s17, s15, 0
	global_load_lds_dwordx4 v1, s[16:17]
	s_waitcnt vmcnt(4)
	s_barrier
	s_waitcnt lgkmcnt(0)
	v_mfma_f32_16x16x32_f16 v[126:129], v[162:165], v[130:133], v[126:129]
	v_mfma_f32_16x16x32_f16 v[122:125], v[166:169], v[130:133], v[122:125]
	v_mfma_f32_16x16x32_f16 v[118:121], v[170:173], v[130:133], v[118:121]
	v_mfma_f32_16x16x32_f16 v[114:117], v[174:177], v[130:133], v[114:117]
	v_mfma_f32_16x16x32_f16 v[110:113], v[162:165], v[134:137], v[110:113]
	v_mfma_f32_16x16x32_f16 v[106:109], v[166:169], v[134:137], v[106:109]
	v_mfma_f32_16x16x32_f16 v[102:105], v[170:173], v[134:137], v[102:105]
	v_mfma_f32_16x16x32_f16 v[98:101], v[174:177], v[134:137], v[98:101]
	v_mfma_f32_16x16x32_f16 v[94:97], v[162:165], v[138:141], v[94:97]
	v_mfma_f32_16x16x32_f16 v[90:93], v[166:169], v[138:141], v[90:93]
	v_mfma_f32_16x16x32_f16 v[86:89], v[170:173], v[138:141], v[86:89]
	v_mfma_f32_16x16x32_f16 v[82:85], v[174:177], v[138:141], v[82:85]
	v_mfma_f32_16x16x32_f16 v[78:81], v[162:165], v[142:145], v[78:81]
	v_mfma_f32_16x16x32_f16 v[74:77], v[166:169], v[142:145], v[74:77]
	v_mfma_f32_16x16x32_f16 v[70:73], v[170:173], v[142:145], v[70:73]
	v_mfma_f32_16x16x32_f16 v[66:69], v[174:177], v[142:145], v[66:69]
	s_barrier
	ds_read_b128 v[146:149], v204 offset:8192
	ds_read_b128 v[150:153], v204 offset:10240
	ds_read_b128 v[154:157], v204 offset:12288
	ds_read_b128 v[158:161], v204 offset:14336
	s_add_i32 m0, s18, 0xc000
	s_add_u32 s16, s14, 0x40080
	s_addc_u32 s17, s15, 0
	global_load_lds_dwordx4 v1, s[16:17]
	s_add_i32 m0, s18, 0xe000
	s_add_u32 s16, s14, 0x60080
	s_addc_u32 s17, s15, 0
	global_load_lds_dwordx4 v1, s[16:17]
	s_barrier
	s_waitcnt lgkmcnt(0)
	v_mfma_f32_16x16x32_f16 v[62:65], v[162:165], v[146:149], v[62:65]
	v_mfma_f32_16x16x32_f16 v[58:61], v[166:169], v[146:149], v[58:61]
	v_mfma_f32_16x16x32_f16 v[54:57], v[170:173], v[146:149], v[54:57]
	v_mfma_f32_16x16x32_f16 v[50:53], v[174:177], v[146:149], v[50:53]
	v_mfma_f32_16x16x32_f16 v[46:49], v[162:165], v[150:153], v[46:49]
	v_mfma_f32_16x16x32_f16 v[42:45], v[166:169], v[150:153], v[42:45]
	v_mfma_f32_16x16x32_f16 v[38:41], v[170:173], v[150:153], v[38:41]
	v_mfma_f32_16x16x32_f16 v[34:37], v[174:177], v[150:153], v[34:37]
	v_mfma_f32_16x16x32_f16 v[30:33], v[162:165], v[154:157], v[30:33]
	v_mfma_f32_16x16x32_f16 v[26:29], v[166:169], v[154:157], v[26:29]
	v_mfma_f32_16x16x32_f16 v[22:25], v[170:173], v[154:157], v[22:25]
	v_mfma_f32_16x16x32_f16 v[18:21], v[174:177], v[154:157], v[18:21]
	v_mfma_f32_16x16x32_f16 v[14:17], v[162:165], v[158:161], v[14:17]
	v_mfma_f32_16x16x32_f16 v[10:13], v[166:169], v[158:161], v[10:13]
	v_mfma_f32_16x16x32_f16 v[6:9], v[170:173], v[158:161], v[6:9]
	v_mfma_f32_16x16x32_f16 v[2:5], v[174:177], v[158:161], v[2:5]
	s_barrier
	ds_read_b128 v[130:133], v205 offset:0
	ds_read_b128 v[134:137], v205 offset:2048
	ds_read_b128 v[138:141], v205 offset:4096
	ds_read_b128 v[142:145], v205 offset:6144
	ds_read_b128 v[162:165], v207 offset:32768
	ds_read_b128 v[166:169], v207 offset:34816
	ds_read_b128 v[170:173], v207 offset:36864
	ds_read_b128 v[174:177], v207 offset:38912
	s_add_i32 m0, s18, 0x2000
	s_add_u32 s16, s12, 0x20080
	s_addc_u32 s17, s13, 0
	global_load_lds_dwordx4 v1, s[16:17]
	s_add_i32 m0, s18, 0x6000
	s_add_u32 s16, s12, 0x60080
	s_addc_u32 s17, s13, 0
	global_load_lds_dwordx4 v1, s[16:17]
	s_waitcnt lgkmcnt(0)
	s_barrier
	v_mfma_f32_16x16x32_f16 v[126:129], v[162:165], v[130:133], v[126:129]
	v_mfma_f32_16x16x32_f16 v[122:125], v[166:169], v[130:133], v[122:125]
	v_mfma_f32_16x16x32_f16 v[118:121], v[170:173], v[130:133], v[118:121]
	v_mfma_f32_16x16x32_f16 v[114:117], v[174:177], v[130:133], v[114:117]
	v_mfma_f32_16x16x32_f16 v[110:113], v[162:165], v[134:137], v[110:113]
	v_mfma_f32_16x16x32_f16 v[106:109], v[166:169], v[134:137], v[106:109]
	v_mfma_f32_16x16x32_f16 v[102:105], v[170:173], v[134:137], v[102:105]
	v_mfma_f32_16x16x32_f16 v[98:101], v[174:177], v[134:137], v[98:101]
	v_mfma_f32_16x16x32_f16 v[94:97], v[162:165], v[138:141], v[94:97]
	v_mfma_f32_16x16x32_f16 v[90:93], v[166:169], v[138:141], v[90:93]
	v_mfma_f32_16x16x32_f16 v[86:89], v[170:173], v[138:141], v[86:89]
	v_mfma_f32_16x16x32_f16 v[82:85], v[174:177], v[138:141], v[82:85]
	v_mfma_f32_16x16x32_f16 v[78:81], v[162:165], v[142:145], v[78:81]
	v_mfma_f32_16x16x32_f16 v[74:77], v[166:169], v[142:145], v[74:77]
	v_mfma_f32_16x16x32_f16 v[70:73], v[170:173], v[142:145], v[70:73]
	v_mfma_f32_16x16x32_f16 v[66:69], v[174:177], v[142:145], v[66:69]
	s_barrier
	ds_read_b128 v[146:149], v205 offset:8192
	ds_read_b128 v[150:153], v205 offset:10240
	ds_read_b128 v[154:157], v205 offset:12288
	ds_read_b128 v[158:161], v205 offset:14336
	s_add_i32 m0, s18, 0x10000
	s_add_u32 s16, s12, 0x100
	s_addc_u32 s17, s13, 0
	global_load_lds_dwordx4 v1, s[16:17]
	s_add_i32 m0, s18, 0x18000
	s_add_u32 s16, s14, 0x100
	s_addc_u32 s17, s15, 0
	global_load_lds_dwordx4 v1, s[16:17]
	s_waitcnt vmcnt(4)
	s_barrier
	s_waitcnt lgkmcnt(0)
	v_mfma_f32_16x16x32_f16 v[62:65], v[162:165], v[146:149], v[62:65]
	v_mfma_f32_16x16x32_f16 v[58:61], v[166:169], v[146:149], v[58:61]
	v_mfma_f32_16x16x32_f16 v[54:57], v[170:173], v[146:149], v[54:57]
	v_mfma_f32_16x16x32_f16 v[50:53], v[174:177], v[146:149], v[50:53]
	v_mfma_f32_16x16x32_f16 v[46:49], v[162:165], v[150:153], v[46:49]
	v_mfma_f32_16x16x32_f16 v[42:45], v[166:169], v[150:153], v[42:45]
	v_mfma_f32_16x16x32_f16 v[38:41], v[170:173], v[150:153], v[38:41]
	v_mfma_f32_16x16x32_f16 v[34:37], v[174:177], v[150:153], v[34:37]
	v_mfma_f32_16x16x32_f16 v[30:33], v[162:165], v[154:157], v[30:33]
	v_mfma_f32_16x16x32_f16 v[26:29], v[166:169], v[154:157], v[26:29]
	v_mfma_f32_16x16x32_f16 v[22:25], v[170:173], v[154:157], v[22:25]
	v_mfma_f32_16x16x32_f16 v[18:21], v[174:177], v[154:157], v[18:21]
	v_mfma_f32_16x16x32_f16 v[14:17], v[162:165], v[158:161], v[14:17]
	v_mfma_f32_16x16x32_f16 v[10:13], v[166:169], v[158:161], v[10:13]
	v_mfma_f32_16x16x32_f16 v[6:9], v[170:173], v[158:161], v[6:9]
	v_mfma_f32_16x16x32_f16 v[2:5], v[174:177], v[158:161], v[2:5]
	s_barrier
	s_add_u32 s12, s12, 0x80
	s_addc_u32 s13, s13, 0
	s_add_u32 s14, s14, 0x80
	s_addc_u32 s15, s15, 0
	s_movk_i32 s20, 6
.Lp1_loop:
	ds_read_b128 v[130:133], v200 offset:0
	ds_read_b128 v[134:137], v200 offset:2048
	ds_read_b128 v[138:141], v200 offset:4096
	ds_read_b128 v[142:145], v200 offset:6144
	ds_read_b128 v[162:165], v202 offset:32768
	ds_read_b128 v[166:169], v202 offset:34816
	ds_read_b128 v[170:173], v202 offset:36864
	ds_read_b128 v[174:177], v202 offset:38912
	s_add_i32 m0, s18, 0x14000
	s_add_u32 s16, s12, 0x40080
	s_addc_u32 s17, s13, 0
	global_load_lds_dwordx4 v1, s[16:17]
	s_add_i32 m0, s18, 0x1a000
	s_add_u32 s16, s14, 0x20080
	s_addc_u32 s17, s15, 0
	global_load_lds_dwordx4 v1, s[16:17]
	s_waitcnt vmcnt(4)
	s_barrier
	s_waitcnt lgkmcnt(0)
	v_mfma_f32_16x16x32_f16 v[126:129], v[162:165], v[130:133], v[126:129]
	v_mfma_f32_16x16x32_f16 v[122:125], v[166:169], v[130:133], v[122:125]
	v_mfma_f32_16x16x32_f16 v[118:121], v[170:173], v[130:133], v[118:121]
	v_mfma_f32_16x16x32_f16 v[114:117], v[174:177], v[130:133], v[114:117]
	v_mfma_f32_16x16x32_f16 v[110:113], v[162:165], v[134:137], v[110:113]
	v_mfma_f32_16x16x32_f16 v[106:109], v[166:169], v[134:137], v[106:109]
	v_mfma_f32_16x16x32_f16 v[102:105], v[170:173], v[134:137], v[102:105]
	v_mfma_f32_16x16x32_f16 v[98:101], v[174:177], v[134:137], v[98:101]
	v_mfma_f32_16x16x32_f16 v[94:97], v[162:165], v[138:141], v[94:97]
	v_mfma_f32_16x16x32_f16 v[90:93], v[166:169], v[138:141], v[90:93]
	v_mfma_f32_16x16x32_f16 v[86:89], v[170:173], v[138:141], v[86:89]
	v_mfma_f32_16x16x32_f16 v[82:85], v[174:177], v[138:141], v[82:85]
	v_mfma_f32_16x16x32_f16 v[78:81], v[162:165], v[142:145], v[78:81]
	v_mfma_f32_16x16x32_f16 v[74:77], v[166:169], v[142:145], v[74:77]
	v_mfma_f32_16x16x32_f16 v[70:73], v[170:173], v[142:145], v[70:73]
	v_mfma_f32_16x16x32_f16 v[66:69], v[174:177], v[142:145], v[66:69]
	s_barrier
	ds_read_b128 v[146:149], v200 offset:8192
	ds_read_b128 v[150:153], v200 offset:10240
	ds_read_b128 v[154:157], v200 offset:12288
	ds_read_b128 v[158:161], v200 offset:14336
	s_add_i32 m0, s18, 0x1c000
	s_add_u32 s16, s14, 0x40080
	s_addc_u32 s17, s15, 0
	global_load_lds_dwordx4 v1, s[16:17]
	s_add_i32 m0, s18, 0x1e000
	s_add_u32 s16, s14, 0x60080
	s_addc_u32 s17, s15, 0
	global_load_lds_dwordx4 v1, s[16:17]
	s_barrier
	s_waitcnt lgkmcnt(0)
	v_mfma_f32_16x16x32_f16 v[62:65], v[162:165], v[146:149], v[62:65]
	v_mfma_f32_16x16x32_f16 v[58:61], v[166:169], v[146:149], v[58:61]
	v_mfma_f32_16x16x32_f16 v[54:57], v[170:173], v[146:149], v[54:57]
	v_mfma_f32_16x16x32_f16 v[50:53], v[174:177], v[146:149], v[50:53]
	v_mfma_f32_16x16x32_f16 v[46:49], v[162:165], v[150:153], v[46:49]
	v_mfma_f32_16x16x32_f16 v[42:45], v[166:169], v[150:153], v[42:45]
	v_mfma_f32_16x16x32_f16 v[38:41], v[170:173], v[150:153], v[38:41]
	v_mfma_f32_16x16x32_f16 v[34:37], v[174:177], v[150:153], v[34:37]
	v_mfma_f32_16x16x32_f16 v[30:33], v[162:165], v[154:157], v[30:33]
	v_mfma_f32_16x16x32_f16 v[26:29], v[166:169], v[154:157], v[26:29]
	v_mfma_f32_16x16x32_f16 v[22:25], v[170:173], v[154:157], v[22:25]
	v_mfma_f32_16x16x32_f16 v[18:21], v[174:177], v[154:157], v[18:21]
	v_mfma_f32_16x16x32_f16 v[14:17], v[162:165], v[158:161], v[14:17]
	v_mfma_f32_16x16x32_f16 v[10:13], v[166:169], v[158:161], v[10:13]
	v_mfma_f32_16x16x32_f16 v[6:9], v[170:173], v[158:161], v[6:9]
	v_mfma_f32_16x16x32_f16 v[2:5], v[174:177], v[158:161], v[2:5]
	s_barrier
	ds_read_b128 v[130:133], v201 offset:0
	ds_read_b128 v[134:137], v201 offset:2048
	ds_read_b128 v[138:141], v201 offset:4096
	ds_read_b128 v[142:145], v201 offset:6144
	ds_read_b128 v[162:165], v203 offset:32768
	ds_read_b128 v[166:169], v203 offset:34816
	ds_read_b128 v[170:173], v203 offset:36864
	ds_read_b128 v[174:177], v203 offset:38912
	s_add_i32 m0, s18, 0x12000
	s_add_u32 s16, s12, 0x20080
	s_addc_u32 s17, s13, 0
	global_load_lds_dwordx4 v1, s[16:17]
	s_add_i32 m0, s18, 0x16000
	s_add_u32 s16, s12, 0x60080
	s_addc_u32 s17, s13, 0
	global_load_lds_dwordx4 v1, s[16:17]
	s_waitcnt lgkmcnt(0)
	s_barrier
	v_mfma_f32_16x16x32_f16 v[126:129], v[162:165], v[130:133], v[126:129]
	v_mfma_f32_16x16x32_f16 v[122:125], v[166:169], v[130:133], v[122:125]
	v_mfma_f32_16x16x32_f16 v[118:121], v[170:173], v[130:133], v[118:121]
	v_mfma_f32_16x16x32_f16 v[114:117], v[174:177], v[130:133], v[114:117]
	v_mfma_f32_16x16x32_f16 v[110:113], v[162:165], v[134:137], v[110:113]
	v_mfma_f32_16x16x32_f16 v[106:109], v[166:169], v[134:137], v[106:109]
	v_mfma_f32_16x16x32_f16 v[102:105], v[170:173], v[134:137], v[102:105]
	v_mfma_f32_16x16x32_f16 v[98:101], v[174:177], v[134:137], v[98:101]
	v_mfma_f32_16x16x32_f16 v[94:97], v[162:165], v[138:141], v[94:97]
	v_mfma_f32_16x16x32_f16 v[90:93], v[166:169], v[138:141], v[90:93]
	v_mfma_f32_16x16x32_f16 v[86:89], v[170:173], v[138:141], v[86:89]
	v_mfma_f32_16x16x32_f16 v[82:85], v[174:177], v[138:141], v[82:85]
	v_mfma_f32_16x16x32_f16 v[78:81], v[162:165], v[142:145], v[78:81]
	v_mfma_f32_16x16x32_f16 v[74:77], v[166:169], v[142:145], v[74:77]
	v_mfma_f32_16x16x32_f16 v[70:73], v[170:173], v[142:145], v[70:73]
	v_mfma_f32_16x16x32_f16 v[66:69], v[174:177], v[142:145], v[66:69]
	s_barrier
	ds_read_b128 v[146:149], v201 offset:8192
	ds_read_b128 v[150:153], v201 offset:10240
	ds_read_b128 v[154:157], v201 offset:12288
	ds_read_b128 v[158:161], v201 offset:14336
	s_mov_b32 m0, s18
	s_add_u32 s16, s12, 0x100
	s_addc_u32 s17, s13, 0
	global_load_lds_dwordx4 v1, s[16:17]
	s_add_i32 m0, s18, 0x8000
	s_add_u32 s16, s14, 0x100
	s_addc_u32 s17, s15, 0
	global_load_lds_dwordx4 v1, s[16:17]
	s_waitcnt vmcnt(4)
	s_barrier
	s_waitcnt lgkmcnt(0)
	v_mfma_f32_16x16x32_f16 v[62:65], v[162:165], v[146:149], v[62:65]
	v_mfma_f32_16x16x32_f16 v[58:61], v[166:169], v[146:149], v[58:61]
	v_mfma_f32_16x16x32_f16 v[54:57], v[170:173], v[146:149], v[54:57]
	v_mfma_f32_16x16x32_f16 v[50:53], v[174:177], v[146:149], v[50:53]
	v_mfma_f32_16x16x32_f16 v[46:49], v[162:165], v[150:153], v[46:49]
	v_mfma_f32_16x16x32_f16 v[42:45], v[166:169], v[150:153], v[42:45]
	v_mfma_f32_16x16x32_f16 v[38:41], v[170:173], v[150:153], v[38:41]
	v_mfma_f32_16x16x32_f16 v[34:37], v[174:177], v[150:153], v[34:37]
	v_mfma_f32_16x16x32_f16 v[30:33], v[162:165], v[154:157], v[30:33]
	v_mfma_f32_16x16x32_f16 v[26:29], v[166:169], v[154:157], v[26:29]
	v_mfma_f32_16x16x32_f16 v[22:25], v[170:173], v[154:157], v[22:25]
	v_mfma_f32_16x16x32_f16 v[18:21], v[174:177], v[154:157], v[18:21]
	v_mfma_f32_16x16x32_f16 v[14:17], v[162:165], v[158:161], v[14:17]
	v_mfma_f32_16x16x32_f16 v[10:13], v[166:169], v[158:161], v[10:13]
	v_mfma_f32_16x16x32_f16 v[6:9], v[170:173], v[158:161], v[6:9]
	v_mfma_f32_16x16x32_f16 v[2:5], v[174:177], v[158:161], v[2:5]
	s_barrier
	s_add_u32 s12, s12, 0x80
	s_addc_u32 s13, s13, 0
	s_add_u32 s14, s14, 0x80
	s_addc_u32 s15, s15, 0
	ds_read_b128 v[130:133], v204 offset:0
	ds_read_b128 v[134:137], v204 offset:2048
	ds_read_b128 v[138:141], v204 offset:4096
	ds_read_b128 v[142:145], v204 offset:6144
	ds_read_b128 v[162:165], v206 offset:32768
	ds_read_b128 v[166:169], v206 offset:34816
	ds_read_b128 v[170:173], v206 offset:36864
	ds_read_b128 v[174:177], v206 offset:38912
	s_add_i32 m0, s18, 0x4000
	s_add_u32 s16, s12, 0x40080
	s_addc_u32 s17, s13, 0
	global_load_lds_dwordx4 v1, s[16:17]
	s_add_i32 m0, s18, 0xa000
	s_add_u32 s16, s14, 0x20080
	s_addc_u32 s17, s15, 0
	global_load_lds_dwordx4 v1, s[16:17]
	s_waitcnt vmcnt(4)
	s_barrier
	s_waitcnt lgkmcnt(0)
	v_mfma_f32_16x16x32_f16 v[126:129], v[162:165], v[130:133], v[126:129]
	v_mfma_f32_16x16x32_f16 v[122:125], v[166:169], v[130:133], v[122:125]
	v_mfma_f32_16x16x32_f16 v[118:121], v[170:173], v[130:133], v[118:121]
	v_mfma_f32_16x16x32_f16 v[114:117], v[174:177], v[130:133], v[114:117]
	v_mfma_f32_16x16x32_f16 v[110:113], v[162:165], v[134:137], v[110:113]
	v_mfma_f32_16x16x32_f16 v[106:109], v[166:169], v[134:137], v[106:109]
	v_mfma_f32_16x16x32_f16 v[102:105], v[170:173], v[134:137], v[102:105]
	v_mfma_f32_16x16x32_f16 v[98:101], v[174:177], v[134:137], v[98:101]
	v_mfma_f32_16x16x32_f16 v[94:97], v[162:165], v[138:141], v[94:97]
	v_mfma_f32_16x16x32_f16 v[90:93], v[166:169], v[138:141], v[90:93]
	v_mfma_f32_16x16x32_f16 v[86:89], v[170:173], v[138:141], v[86:89]
	v_mfma_f32_16x16x32_f16 v[82:85], v[174:177], v[138:141], v[82:85]
	v_mfma_f32_16x16x32_f16 v[78:81], v[162:165], v[142:145], v[78:81]
	v_mfma_f32_16x16x32_f16 v[74:77], v[166:169], v[142:145], v[74:77]
	v_mfma_f32_16x16x32_f16 v[70:73], v[170:173], v[142:145], v[70:73]
	v_mfma_f32_16x16x32_f16 v[66:69], v[174:177], v[142:145], v[66:69]
	s_barrier
	ds_read_b128 v[146:149], v204 offset:8192
	ds_read_b128 v[150:153], v204 offset:10240
	ds_read_b128 v[154:157], v204 offset:12288
	ds_read_b128 v[158:161], v204 offset:14336
	s_add_i32 m0, s18, 0xc000
	s_add_u32 s16, s14, 0x40080
	s_addc_u32 s17, s15, 0
	global_load_lds_dwordx4 v1, s[16:17]
	s_add_i32 m0, s18, 0xe000
	s_add_u32 s16, s14, 0x60080
	s_addc_u32 s17, s15, 0
	global_load_lds_dwordx4 v1, s[16:17]
	s_barrier
	s_waitcnt lgkmcnt(0)
	v_mfma_f32_16x16x32_f16 v[62:65], v[162:165], v[146:149], v[62:65]
	v_mfma_f32_16x16x32_f16 v[58:61], v[166:169], v[146:149], v[58:61]
	v_mfma_f32_16x16x32_f16 v[54:57], v[170:173], v[146:149], v[54:57]
	v_mfma_f32_16x16x32_f16 v[50:53], v[174:177], v[146:149], v[50:53]
	v_mfma_f32_16x16x32_f16 v[46:49], v[162:165], v[150:153], v[46:49]
	v_mfma_f32_16x16x32_f16 v[42:45], v[166:169], v[150:153], v[42:45]
	v_mfma_f32_16x16x32_f16 v[38:41], v[170:173], v[150:153], v[38:41]
	v_mfma_f32_16x16x32_f16 v[34:37], v[174:177], v[150:153], v[34:37]
	v_mfma_f32_16x16x32_f16 v[30:33], v[162:165], v[154:157], v[30:33]
	v_mfma_f32_16x16x32_f16 v[26:29], v[166:169], v[154:157], v[26:29]
	v_mfma_f32_16x16x32_f16 v[22:25], v[170:173], v[154:157], v[22:25]
	v_mfma_f32_16x16x32_f16 v[18:21], v[174:177], v[154:157], v[18:21]
	v_mfma_f32_16x16x32_f16 v[14:17], v[162:165], v[158:161], v[14:17]
	v_mfma_f32_16x16x32_f16 v[10:13], v[166:169], v[158:161], v[10:13]
	v_mfma_f32_16x16x32_f16 v[6:9], v[170:173], v[158:161], v[6:9]
	v_mfma_f32_16x16x32_f16 v[2:5], v[174:177], v[158:161], v[2:5]
	s_barrier
	ds_read_b128 v[130:133], v205 offset:0
	ds_read_b128 v[134:137], v205 offset:2048
	ds_read_b128 v[138:141], v205 offset:4096
	ds_read_b128 v[142:145], v205 offset:6144
	ds_read_b128 v[162:165], v207 offset:32768
	ds_read_b128 v[166:169], v207 offset:34816
	ds_read_b128 v[170:173], v207 offset:36864
	ds_read_b128 v[174:177], v207 offset:38912
	s_add_i32 m0, s18, 0x2000
	s_add_u32 s16, s12, 0x20080
	s_addc_u32 s17, s13, 0
	global_load_lds_dwordx4 v1, s[16:17]
	s_add_i32 m0, s18, 0x6000
	s_add_u32 s16, s12, 0x60080
	s_addc_u32 s17, s13, 0
	global_load_lds_dwordx4 v1, s[16:17]
	s_waitcnt lgkmcnt(0)
	s_barrier
	v_mfma_f32_16x16x32_f16 v[126:129], v[162:165], v[130:133], v[126:129]
	v_mfma_f32_16x16x32_f16 v[122:125], v[166:169], v[130:133], v[122:125]
	v_mfma_f32_16x16x32_f16 v[118:121], v[170:173], v[130:133], v[118:121]
	v_mfma_f32_16x16x32_f16 v[114:117], v[174:177], v[130:133], v[114:117]
	v_mfma_f32_16x16x32_f16 v[110:113], v[162:165], v[134:137], v[110:113]
	v_mfma_f32_16x16x32_f16 v[106:109], v[166:169], v[134:137], v[106:109]
	v_mfma_f32_16x16x32_f16 v[102:105], v[170:173], v[134:137], v[102:105]
	v_mfma_f32_16x16x32_f16 v[98:101], v[174:177], v[134:137], v[98:101]
	v_mfma_f32_16x16x32_f16 v[94:97], v[162:165], v[138:141], v[94:97]
	v_mfma_f32_16x16x32_f16 v[90:93], v[166:169], v[138:141], v[90:93]
	v_mfma_f32_16x16x32_f16 v[86:89], v[170:173], v[138:141], v[86:89]
	v_mfma_f32_16x16x32_f16 v[82:85], v[174:177], v[138:141], v[82:85]
	v_mfma_f32_16x16x32_f16 v[78:81], v[162:165], v[142:145], v[78:81]
	v_mfma_f32_16x16x32_f16 v[74:77], v[166:169], v[142:145], v[74:77]
	v_mfma_f32_16x16x32_f16 v[70:73], v[170:173], v[142:145], v[70:73]
	v_mfma_f32_16x16x32_f16 v[66:69], v[174:177], v[142:145], v[66:69]
	s_barrier
	ds_read_b128 v[146:149], v205 offset:8192
	ds_read_b128 v[150:153], v205 offset:10240
	ds_read_b128 v[154:157], v205 offset:12288
	ds_read_b128 v[158:161], v205 offset:14336
	s_add_i32 m0, s18, 0x10000
	s_add_u32 s16, s12, 0x100
	s_addc_u32 s17, s13, 0
	global_load_lds_dwordx4 v1, s[16:17]
	s_add_i32 m0, s18, 0x18000
	s_add_u32 s16, s14, 0x100
	s_addc_u32 s17, s15, 0
	global_load_lds_dwordx4 v1, s[16:17]
	s_waitcnt vmcnt(4)
	s_barrier
	s_waitcnt lgkmcnt(0)
	v_mfma_f32_16x16x32_f16 v[62:65], v[162:165], v[146:149], v[62:65]
	v_mfma_f32_16x16x32_f16 v[58:61], v[166:169], v[146:149], v[58:61]
	v_mfma_f32_16x16x32_f16 v[54:57], v[170:173], v[146:149], v[54:57]
	v_mfma_f32_16x16x32_f16 v[50:53], v[174:177], v[146:149], v[50:53]
	v_mfma_f32_16x16x32_f16 v[46:49], v[162:165], v[150:153], v[46:49]
	v_mfma_f32_16x16x32_f16 v[42:45], v[166:169], v[150:153], v[42:45]
	v_mfma_f32_16x16x32_f16 v[38:41], v[170:173], v[150:153], v[38:41]
	v_mfma_f32_16x16x32_f16 v[34:37], v[174:177], v[150:153], v[34:37]
	v_mfma_f32_16x16x32_f16 v[30:33], v[162:165], v[154:157], v[30:33]
	v_mfma_f32_16x16x32_f16 v[26:29], v[166:169], v[154:157], v[26:29]
	v_mfma_f32_16x16x32_f16 v[22:25], v[170:173], v[154:157], v[22:25]
	v_mfma_f32_16x16x32_f16 v[18:21], v[174:177], v[154:157], v[18:21]
	v_mfma_f32_16x16x32_f16 v[14:17], v[162:165], v[158:161], v[14:17]
	v_mfma_f32_16x16x32_f16 v[10:13], v[166:169], v[158:161], v[10:13]
	v_mfma_f32_16x16x32_f16 v[6:9], v[170:173], v[158:161], v[6:9]
	v_mfma_f32_16x16x32_f16 v[2:5], v[174:177], v[158:161], v[2:5]
	s_barrier
	s_add_u32 s12, s12, 0x80
	s_addc_u32 s13, s13, 0
	s_add_u32 s14, s14, 0x80
	s_addc_u32 s15, s15, 0
	s_add_i32 s20, s20, -1
	s_cmp_lg_u32 s20, 0
	s_cbranch_scc1 .Lp1_loop
	ds_read_b128 v[130:133], v200 offset:0
	ds_read_b128 v[134:137], v200 offset:2048
	ds_read_b128 v[138:141], v200 offset:4096
	ds_read_b128 v[142:145], v200 offset:6144
	ds_read_b128 v[162:165], v202 offset:32768
	ds_read_b128 v[166:169], v202 offset:34816
	ds_read_b128 v[170:173], v202 offset:36864
	ds_read_b128 v[174:177], v202 offset:38912
	s_add_i32 m0, s18, 0x14000
	s_add_u32 s16, s12, 0x40080
	s_addc_u32 s17, s13, 0
	global_load_lds_dwordx4 v1, s[16:17]
	s_add_i32 m0, s18, 0x1a000
	s_add_u32 s16, s14, 0x20080
	s_addc_u32 s17, s15, 0
	global_load_lds_dwordx4 v1, s[16:17]
	s_waitcnt vmcnt(4)
	s_barrier
	s_waitcnt lgkmcnt(0)
	v_mfma_f32_16x16x32_f16 v[126:129], v[162:165], v[130:133], v[126:129]
	v_mfma_f32_16x16x32_f16 v[122:125], v[166:169], v[130:133], v[122:125]
	v_mfma_f32_16x16x32_f16 v[118:121], v[170:173], v[130:133], v[118:121]
	v_mfma_f32_16x16x32_f16 v[114:117], v[174:177], v[130:133], v[114:117]
	v_mfma_f32_16x16x32_f16 v[110:113], v[162:165], v[134:137], v[110:113]
	v_mfma_f32_16x16x32_f16 v[106:109], v[166:169], v[134:137], v[106:109]
	v_mfma_f32_16x16x32_f16 v[102:105], v[170:173], v[134:137], v[102:105]
	v_mfma_f32_16x16x32_f16 v[98:101], v[174:177], v[134:137], v[98:101]
	v_mfma_f32_16x16x32_f16 v[94:97], v[162:165], v[138:141], v[94:97]
	v_mfma_f32_16x16x32_f16 v[90:93], v[166:169], v[138:141], v[90:93]
	v_mfma_f32_16x16x32_f16 v[86:89], v[170:173], v[138:141], v[86:89]
	v_mfma_f32_16x16x32_f16 v[82:85], v[174:177], v[138:141], v[82:85]
	v_mfma_f32_16x16x32_f16 v[78:81], v[162:165], v[142:145], v[78:81]
	v_mfma_f32_16x16x32_f16 v[74:77], v[166:169], v[142:145], v[74:77]
	v_mfma_f32_16x16x32_f16 v[70:73], v[170:173], v[142:145], v[70:73]
	v_mfma_f32_16x16x32_f16 v[66:69], v[174:177], v[142:145], v[66:69]
	s_barrier
	ds_read_b128 v[146:149], v200 offset:8192
	ds_read_b128 v[150:153], v200 offset:10240
	ds_read_b128 v[154:157], v200 offset:12288
	ds_read_b128 v[158:161], v200 offset:14336
	s_add_i32 m0, s18, 0x1c000
	s_add_u32 s16, s14, 0x40080
	s_addc_u32 s17, s15, 0
	global_load_lds_dwordx4 v1, s[16:17]
	s_add_i32 m0, s18, 0x1e000
	s_add_u32 s16, s14, 0x60080
	s_addc_u32 s17, s15, 0
	global_load_lds_dwordx4 v1, s[16:17]
	s_barrier
	s_waitcnt lgkmcnt(0)
	v_mfma_f32_16x16x32_f16 v[62:65], v[162:165], v[146:149], v[62:65]
	v_mfma_f32_16x16x32_f16 v[58:61], v[166:169], v[146:149], v[58:61]
	v_mfma_f32_16x16x32_f16 v[54:57], v[170:173], v[146:149], v[54:57]
	v_mfma_f32_16x16x32_f16 v[50:53], v[174:177], v[146:149], v[50:53]
	v_mfma_f32_16x16x32_f16 v[46:49], v[162:165], v[150:153], v[46:49]
	v_mfma_f32_16x16x32_f16 v[42:45], v[166:169], v[150:153], v[42:45]
	v_mfma_f32_16x16x32_f16 v[38:41], v[170:173], v[150:153], v[38:41]
	v_mfma_f32_16x16x32_f16 v[34:37], v[174:177], v[150:153], v[34:37]
	v_mfma_f32_16x16x32_f16 v[30:33], v[162:165], v[154:157], v[30:33]
	v_mfma_f32_16x16x32_f16 v[26:29], v[166:169], v[154:157], v[26:29]
	v_mfma_f32_16x16x32_f16 v[22:25], v[170:173], v[154:157], v[22:25]
	v_mfma_f32_16x16x32_f16 v[18:21], v[174:177], v[154:157], v[18:21]
	v_mfma_f32_16x16x32_f16 v[14:17], v[162:165], v[158:161], v[14:17]
	v_mfma_f32_16x16x32_f16 v[10:13], v[166:169], v[158:161], v[10:13]
	v_mfma_f32_16x16x32_f16 v[6:9], v[170:173], v[158:161], v[6:9]
	v_mfma_f32_16x16x32_f16 v[2:5], v[174:177], v[158:161], v[2:5]
	s_barrier
	ds_read_b128 v[130:133], v201 offset:0
	ds_read_b128 v[134:137], v201 offset:2048
	ds_read_b128 v[138:141], v201 offset:4096
	ds_read_b128 v[142:145], v201 offset:6144
	ds_read_b128 v[162:165], v203 offset:32768
	ds_read_b128 v[166:169], v203 offset:34816
	ds_read_b128 v[170:173], v203 offset:36864
	ds_read_b128 v[174:177], v203 offset:38912
	s_add_i32 m0, s18, 0x12000
	s_add_u32 s16, s12, 0x20080
	s_addc_u32 s17, s13, 0
	global_load_lds_dwordx4 v1, s[16:17]
	s_add_i32 m0, s18, 0x16000
	s_add_u32 s16, s12, 0x60080
	s_addc_u32 s17, s13, 0
	global_load_lds_dwordx4 v1, s[16:17]
	s_waitcnt lgkmcnt(0)
	s_barrier
	v_mfma_f32_16x16x32_f16 v[126:129], v[162:165], v[130:133], v[126:129]
	v_mfma_f32_16x16x32_f16 v[122:125], v[166:169], v[130:133], v[122:125]
	v_mfma_f32_16x16x32_f16 v[118:121], v[170:173], v[130:133], v[118:121]
	v_mfma_f32_16x16x32_f16 v[114:117], v[174:177], v[130:133], v[114:117]
	v_mfma_f32_16x16x32_f16 v[110:113], v[162:165], v[134:137], v[110:113]
	v_mfma_f32_16x16x32_f16 v[106:109], v[166:169], v[134:137], v[106:109]
	v_mfma_f32_16x16x32_f16 v[102:105], v[170:173], v[134:137], v[102:105]
	v_mfma_f32_16x16x32_f16 v[98:101], v[174:177], v[134:137], v[98:101]
	v_mfma_f32_16x16x32_f16 v[94:97], v[162:165], v[138:141], v[94:97]
	v_mfma_f32_16x16x32_f16 v[90:93], v[166:169], v[138:141], v[90:93]
	v_mfma_f32_16x16x32_f16 v[86:89], v[170:173], v[138:141], v[86:89]
	v_mfma_f32_16x16x32_f16 v[82:85], v[174:177], v[138:141], v[82:85]
	v_mfma_f32_16x16x32_f16 v[78:81], v[162:165], v[142:145], v[78:81]
	v_mfma_f32_16x16x32_f16 v[74:77], v[166:169], v[142:145], v[74:77]
	v_mfma_f32_16x16x32_f16 v[70:73], v[170:173], v[142:145], v[70:73]
	v_mfma_f32_16x16x32_f16 v[66:69], v[174:177], v[142:145], v[66:69]
	s_barrier
	ds_read_b128 v[146:149], v201 offset:8192
	ds_read_b128 v[150:153], v201 offset:10240
	ds_read_b128 v[154:157], v201 offset:12288
	ds_read_b128 v[158:161], v201 offset:14336
	s_waitcnt vmcnt(2)
	s_barrier
	s_waitcnt lgkmcnt(0)
	v_mfma_f32_16x16x32_f16 v[62:65], v[162:165], v[146:149], v[62:65]
	v_mfma_f32_16x16x32_f16 v[58:61], v[166:169], v[146:149], v[58:61]
	v_mfma_f32_16x16x32_f16 v[54:57], v[170:173], v[146:149], v[54:57]
	v_mfma_f32_16x16x32_f16 v[50:53], v[174:177], v[146:149], v[50:53]
	v_mfma_f32_16x16x32_f16 v[46:49], v[162:165], v[150:153], v[46:49]
	v_mfma_f32_16x16x32_f16 v[42:45], v[166:169], v[150:153], v[42:45]
	v_mfma_f32_16x16x32_f16 v[38:41], v[170:173], v[150:153], v[38:41]
	v_mfma_f32_16x16x32_f16 v[34:37], v[174:177], v[150:153], v[34:37]
	v_mfma_f32_16x16x32_f16 v[30:33], v[162:165], v[154:157], v[30:33]
	v_mfma_f32_16x16x32_f16 v[26:29], v[166:169], v[154:157], v[26:29]
	v_mfma_f32_16x16x32_f16 v[22:25], v[170:173], v[154:157], v[22:25]
	v_mfma_f32_16x16x32_f16 v[18:21], v[174:177], v[154:157], v[18:21]
	v_mfma_f32_16x16x32_f16 v[14:17], v[162:165], v[158:161], v[14:17]
	v_mfma_f32_16x16x32_f16 v[10:13], v[166:169], v[158:161], v[10:13]
	v_mfma_f32_16x16x32_f16 v[6:9], v[170:173], v[158:161], v[6:9]
	v_mfma_f32_16x16x32_f16 v[2:5], v[174:177], v[158:161], v[2:5]
	s_barrier
	s_add_u32 s12, s12, 0x80
	s_addc_u32 s13, s13, 0
	s_add_u32 s14, s14, 0x80
	s_addc_u32 s15, s15, 0
	ds_read_b128 v[130:133], v204 offset:0
	ds_read_b128 v[134:137], v204 offset:2048
	ds_read_b128 v[138:141], v204 offset:4096
	ds_read_b128 v[142:145], v204 offset:6144
	ds_read_b128 v[162:165], v206 offset:32768
	ds_read_b128 v[166:169], v206 offset:34816
	ds_read_b128 v[170:173], v206 offset:36864
	ds_read_b128 v[174:177], v206 offset:38912
	s_waitcnt vmcnt(0)
	s_barrier
	s_waitcnt lgkmcnt(0)
	v_mfma_f32_16x16x32_f16 v[126:129], v[162:165], v[130:133], v[126:129]
	v_mfma_f32_16x16x32_f16 v[122:125], v[166:169], v[130:133], v[122:125]
	v_mfma_f32_16x16x32_f16 v[118:121], v[170:173], v[130:133], v[118:121]
	v_mfma_f32_16x16x32_f16 v[114:117], v[174:177], v[130:133], v[114:117]
	v_mfma_f32_16x16x32_f16 v[110:113], v[162:165], v[134:137], v[110:113]
	v_mfma_f32_16x16x32_f16 v[106:109], v[166:169], v[134:137], v[106:109]
	v_mfma_f32_16x16x32_f16 v[102:105], v[170:173], v[134:137], v[102:105]
	v_mfma_f32_16x16x32_f16 v[98:101], v[174:177], v[134:137], v[98:101]
	v_mfma_f32_16x16x32_f16 v[94:97], v[162:165], v[138:141], v[94:97]
	v_mfma_f32_16x16x32_f16 v[90:93], v[166:169], v[138:141], v[90:93]
	v_mfma_f32_16x16x32_f16 v[86:89], v[170:173], v[138:141], v[86:89]
	v_mfma_f32_16x16x32_f16 v[82:85], v[174:177], v[138:141], v[82:85]
	v_mfma_f32_16x16x32_f16 v[78:81], v[162:165], v[142:145], v[78:81]
	v_mfma_f32_16x16x32_f16 v[74:77], v[166:169], v[142:145], v[74:77]
	v_mfma_f32_16x16x32_f16 v[70:73], v[170:173], v[142:145], v[70:73]
	v_mfma_f32_16x16x32_f16 v[66:69], v[174:177], v[142:145], v[66:69]
	s_barrier
	ds_read_b128 v[146:149], v204 offset:8192
	ds_read_b128 v[150:153], v204 offset:10240
	ds_read_b128 v[154:157], v204 offset:12288
	ds_read_b128 v[158:161], v204 offset:14336
	s_barrier
	s_waitcnt lgkmcnt(0)
	v_mfma_f32_16x16x32_f16 v[62:65], v[162:165], v[146:149], v[62:65]
	v_mfma_f32_16x16x32_f16 v[58:61], v[166:169], v[146:149], v[58:61]
	v_mfma_f32_16x16x32_f16 v[54:57], v[170:173], v[146:149], v[54:57]
	v_mfma_f32_16x16x32_f16 v[50:53], v[174:177], v[146:149], v[50:53]
	v_mfma_f32_16x16x32_f16 v[46:49], v[162:165], v[150:153], v[46:49]
	v_mfma_f32_16x16x32_f16 v[42:45], v[166:169], v[150:153], v[42:45]
	v_mfma_f32_16x16x32_f16 v[38:41], v[170:173], v[150:153], v[38:41]
	v_mfma_f32_16x16x32_f16 v[34:37], v[174:177], v[150:153], v[34:37]
	v_mfma_f32_16x16x32_f16 v[30:33], v[162:165], v[154:157], v[30:33]
	v_mfma_f32_16x16x32_f16 v[26:29], v[166:169], v[154:157], v[26:29]
	v_mfma_f32_16x16x32_f16 v[22:25], v[170:173], v[154:157], v[22:25]
	v_mfma_f32_16x16x32_f16 v[18:21], v[174:177], v[154:157], v[18:21]
	v_mfma_f32_16x16x32_f16 v[14:17], v[162:165], v[158:161], v[14:17]
	v_mfma_f32_16x16x32_f16 v[10:13], v[166:169], v[158:161], v[10:13]
	v_mfma_f32_16x16x32_f16 v[6:9], v[170:173], v[158:161], v[6:9]
	v_mfma_f32_16x16x32_f16 v[2:5], v[174:177], v[158:161], v[2:5]
	s_barrier
	ds_read_b128 v[130:133], v205 offset:0
	ds_read_b128 v[134:137], v205 offset:2048
	ds_read_b128 v[138:141], v205 offset:4096
	ds_read_b128 v[142:145], v205 offset:6144
	ds_read_b128 v[162:165], v207 offset:32768
	ds_read_b128 v[166:169], v207 offset:34816
	ds_read_b128 v[170:173], v207 offset:36864
	ds_read_b128 v[174:177], v207 offset:38912
	s_waitcnt lgkmcnt(0)
	s_barrier
	v_mfma_f32_16x16x32_f16 v[126:129], v[162:165], v[130:133], v[126:129]
	v_mfma_f32_16x16x32_f16 v[122:125], v[166:169], v[130:133], v[122:125]
	v_mfma_f32_16x16x32_f16 v[118:121], v[170:173], v[130:133], v[118:121]
	v_mfma_f32_16x16x32_f16 v[114:117], v[174:177], v[130:133], v[114:117]
	v_mfma_f32_16x16x32_f16 v[110:113], v[162:165], v[134:137], v[110:113]
	v_mfma_f32_16x16x32_f16 v[106:109], v[166:169], v[134:137], v[106:109]
	v_mfma_f32_16x16x32_f16 v[102:105], v[170:173], v[134:137], v[102:105]
	v_mfma_f32_16x16x32_f16 v[98:101], v[174:177], v[134:137], v[98:101]
	v_mfma_f32_16x16x32_f16 v[94:97], v[162:165], v[138:141], v[94:97]
	v_mfma_f32_16x16x32_f16 v[90:93], v[166:169], v[138:141], v[90:93]
	v_mfma_f32_16x16x32_f16 v[86:89], v[170:173], v[138:141], v[86:89]
	v_mfma_f32_16x16x32_f16 v[82:85], v[174:177], v[138:141], v[82:85]
	v_mfma_f32_16x16x32_f16 v[78:81], v[162:165], v[142:145], v[78:81]
	v_mfma_f32_16x16x32_f16 v[74:77], v[166:169], v[142:145], v[74:77]
	v_mfma_f32_16x16x32_f16 v[70:73], v[170:173], v[142:145], v[70:73]
	v_mfma_f32_16x16x32_f16 v[66:69], v[174:177], v[142:145], v[66:69]
	s_barrier
	ds_read_b128 v[146:149], v205 offset:8192
	ds_read_b128 v[150:153], v205 offset:10240
	ds_read_b128 v[154:157], v205 offset:12288
	ds_read_b128 v[158:161], v205 offset:14336
	s_barrier
	s_waitcnt lgkmcnt(0)
	v_mfma_f32_16x16x32_f16 v[62:65], v[162:165], v[146:149], v[62:65]
	v_mfma_f32_16x16x32_f16 v[58:61], v[166:169], v[146:149], v[58:61]
	v_mfma_f32_16x16x32_f16 v[54:57], v[170:173], v[146:149], v[54:57]
	v_mfma_f32_16x16x32_f16 v[50:53], v[174:177], v[146:149], v[50:53]
	v_mfma_f32_16x16x32_f16 v[46:49], v[162:165], v[150:153], v[46:49]
	v_mfma_f32_16x16x32_f16 v[42:45], v[166:169], v[150:153], v[42:45]
	v_mfma_f32_16x16x32_f16 v[38:41], v[170:173], v[150:153], v[38:41]
	v_mfma_f32_16x16x32_f16 v[34:37], v[174:177], v[150:153], v[34:37]
	v_mfma_f32_16x16x32_f16 v[30:33], v[162:165], v[154:157], v[30:33]
	v_mfma_f32_16x16x32_f16 v[26:29], v[166:169], v[154:157], v[26:29]
	v_mfma_f32_16x16x32_f16 v[22:25], v[170:173], v[154:157], v[22:25]
	v_mfma_f32_16x16x32_f16 v[18:21], v[174:177], v[154:157], v[18:21]
	v_mfma_f32_16x16x32_f16 v[14:17], v[162:165], v[158:161], v[14:17]
	v_mfma_f32_16x16x32_f16 v[10:13], v[166:169], v[158:161], v[10:13]
	v_mfma_f32_16x16x32_f16 v[6:9], v[170:173], v[158:161], v[6:9]
	v_mfma_f32_16x16x32_f16 v[2:5], v[174:177], v[158:161], v[2:5]
	s_barrier
	s_cmp_eq_u32 s19, 1
	s_cbranch_scc1 .Lp1_skew1
	s_barrier

.Lp3_skew0:
	ds_read_b128 v[130:133], v200 offset:0
	ds_read_b128 v[134:137], v200 offset:2048
	ds_read_b128 v[138:141], v200 offset:4096
	ds_read_b128 v[142:145], v200 offset:6144
	ds_read_b128 v[162:165], v202 offset:32768
	ds_read_b128 v[166:169], v202 offset:34816
	ds_read_b128 v[170:173], v202 offset:36864
	ds_read_b128 v[174:177], v202 offset:38912
	s_add_i32 m0, s21, 0x14000
	s_add_u32 s40, s36, 0x40080
	s_addc_u32 s41, s37, 0
	global_load_lds_dwordx4 v1, s[40:41]
	s_add_i32 m0, s21, 0x1a000
	s_add_u32 s40, s38, 0x20080
	s_addc_u32 s41, s39, 0
	global_load_lds_dwordx4 v1, s[40:41]
	s_barrier
	s_waitcnt lgkmcnt(0)
	v_mfma_f32_16x16x32_f16 v[126:129], v[162:165], v[130:133], 0
	v_mfma_f32_16x16x32_f16 v[122:125], v[166:169], v[130:133], 0
	v_mfma_f32_16x16x32_f16 v[118:121], v[170:173], v[130:133], 0
	v_mfma_f32_16x16x32_f16 v[114:117], v[174:177], v[130:133], 0
	v_mfma_f32_16x16x32_f16 v[110:113], v[162:165], v[134:137], 0
	v_mfma_f32_16x16x32_f16 v[106:109], v[166:169], v[134:137], 0
	v_mfma_f32_16x16x32_f16 v[102:105], v[170:173], v[134:137], 0
	v_mfma_f32_16x16x32_f16 v[98:101], v[174:177], v[134:137], 0
	v_mfma_f32_16x16x32_f16 v[94:97], v[162:165], v[138:141], 0
	v_mfma_f32_16x16x32_f16 v[90:93], v[166:169], v[138:141], 0
	v_mfma_f32_16x16x32_f16 v[86:89], v[170:173], v[138:141], 0
	v_mfma_f32_16x16x32_f16 v[82:85], v[174:177], v[138:141], 0
	v_mfma_f32_16x16x32_f16 v[78:81], v[162:165], v[142:145], 0
	v_mfma_f32_16x16x32_f16 v[74:77], v[166:169], v[142:145], 0
	v_mfma_f32_16x16x32_f16 v[70:73], v[170:173], v[142:145], 0
	v_mfma_f32_16x16x32_f16 v[66:69], v[174:177], v[142:145], 0
	s_barrier
	ds_read_b128 v[146:149], v200 offset:8192
	ds_read_b128 v[150:153], v200 offset:10240
	ds_read_b128 v[154:157], v200 offset:12288
	ds_read_b128 v[158:161], v200 offset:14336
	s_add_i32 m0, s21, 0x1c000
	s_add_u32 s40, s38, 0x40080
	s_addc_u32 s41, s39, 0
	global_load_lds_dwordx4 v1, s[40:41]
	s_add_i32 m0, s21, 0x1e000
	s_add_u32 s40, s38, 0x60080
	s_addc_u32 s41, s39, 0
	global_load_lds_dwordx4 v1, s[40:41]
	s_barrier
	s_waitcnt lgkmcnt(0)
	v_mfma_f32_16x16x32_f16 v[62:65], v[162:165], v[146:149], 0
	v_mfma_f32_16x16x32_f16 v[58:61], v[166:169], v[146:149], 0
	v_mfma_f32_16x16x32_f16 v[54:57], v[170:173], v[146:149], 0
	v_mfma_f32_16x16x32_f16 v[50:53], v[174:177], v[146:149], 0
	v_mfma_f32_16x16x32_f16 v[46:49], v[162:165], v[150:153], 0
	v_mfma_f32_16x16x32_f16 v[42:45], v[166:169], v[150:153], 0
	v_mfma_f32_16x16x32_f16 v[38:41], v[170:173], v[150:153], 0
	v_mfma_f32_16x16x32_f16 v[34:37], v[174:177], v[150:153], 0
	v_mfma_f32_16x16x32_f16 v[30:33], v[162:165], v[154:157], 0
	v_mfma_f32_16x16x32_f16 v[26:29], v[166:169], v[154:157], 0
	v_mfma_f32_16x16x32_f16 v[22:25], v[170:173], v[154:157], 0
	v_mfma_f32_16x16x32_f16 v[18:21], v[174:177], v[154:157], 0
	v_mfma_f32_16x16x32_f16 v[14:17], v[162:165], v[158:161], 0
	v_mfma_f32_16x16x32_f16 v[10:13], v[166:169], v[158:161], 0
	v_mfma_f32_16x16x32_f16 v[6:9], v[170:173], v[158:161], 0
	v_mfma_f32_16x16x32_f16 v[2:5], v[174:177], v[158:161], 0
	s_barrier
	ds_read_b128 v[130:133], v201 offset:0
	ds_read_b128 v[134:137], v201 offset:2048
	ds_read_b128 v[138:141], v201 offset:4096
	ds_read_b128 v[142:145], v201 offset:6144
	ds_read_b128 v[162:165], v203 offset:32768
	ds_read_b128 v[166:169], v203 offset:34816
	ds_read_b128 v[170:173], v203 offset:36864
	ds_read_b128 v[174:177], v203 offset:38912
	s_add_i32 m0, s21, 0x12000
	s_add_u32 s40, s36, 0x20080
	s_addc_u32 s41, s37, 0
	global_load_lds_dwordx4 v1, s[40:41]
	s_add_i32 m0, s21, 0x16000
	s_add_u32 s40, s36, 0x60080
	s_addc_u32 s41, s37, 0
	global_load_lds_dwordx4 v1, s[40:41]
	s_waitcnt lgkmcnt(0)
	s_barrier
	v_mfma_f32_16x16x32_f16 v[126:129], v[162:165], v[130:133], v[126:129]
	v_mfma_f32_16x16x32_f16 v[122:125], v[166:169], v[130:133], v[122:125]
	v_mfma_f32_16x16x32_f16 v[118:121], v[170:173], v[130:133], v[118:121]
	v_mfma_f32_16x16x32_f16 v[114:117], v[174:177], v[130:133], v[114:117]
	v_mfma_f32_16x16x32_f16 v[110:113], v[162:165], v[134:137], v[110:113]
	v_mfma_f32_16x16x32_f16 v[106:109], v[166:169], v[134:137], v[106:109]
	v_mfma_f32_16x16x32_f16 v[102:105], v[170:173], v[134:137], v[102:105]
	v_mfma_f32_16x16x32_f16 v[98:101], v[174:177], v[134:137], v[98:101]
	v_mfma_f32_16x16x32_f16 v[94:97], v[162:165], v[138:141], v[94:97]
	v_mfma_f32_16x16x32_f16 v[90:93], v[166:169], v[138:141], v[90:93]
	v_mfma_f32_16x16x32_f16 v[86:89], v[170:173], v[138:141], v[86:89]
	v_mfma_f32_16x16x32_f16 v[82:85], v[174:177], v[138:141], v[82:85]
	v_mfma_f32_16x16x32_f16 v[78:81], v[162:165], v[142:145], v[78:81]
	v_mfma_f32_16x16x32_f16 v[74:77], v[166:169], v[142:145], v[74:77]
	v_mfma_f32_16x16x32_f16 v[70:73], v[170:173], v[142:145], v[70:73]
	v_mfma_f32_16x16x32_f16 v[66:69], v[174:177], v[142:145], v[66:69]
	s_barrier
	ds_read_b128 v[146:149], v201 offset:8192
	ds_read_b128 v[150:153], v201 offset:10240
	ds_read_b128 v[154:157], v201 offset:12288
	ds_read_b128 v[158:161], v201 offset:14336
	s_mov_b32 m0, s21
	s_add_u32 s40, s36, 0x100
	s_addc_u32 s41, s37, 0
	global_load_lds_dwordx4 v1, s[40:41]
	s_add_i32 m0, s21, 0x8000
	s_add_u32 s40, s38, 0x100
	s_addc_u32 s41, s39, 0
	global_load_lds_dwordx4 v1, s[40:41]
	s_waitcnt vmcnt(4)
	s_barrier
	s_waitcnt lgkmcnt(0)
	v_mfma_f32_16x16x32_f16 v[62:65], v[162:165], v[146:149], v[62:65]
	v_mfma_f32_16x16x32_f16 v[58:61], v[166:169], v[146:149], v[58:61]
	v_mfma_f32_16x16x32_f16 v[54:57], v[170:173], v[146:149], v[54:57]
	v_mfma_f32_16x16x32_f16 v[50:53], v[174:177], v[146:149], v[50:53]
	v_mfma_f32_16x16x32_f16 v[46:49], v[162:165], v[150:153], v[46:49]
	v_mfma_f32_16x16x32_f16 v[42:45], v[166:169], v[150:153], v[42:45]
	v_mfma_f32_16x16x32_f16 v[38:41], v[170:173], v[150:153], v[38:41]
	v_mfma_f32_16x16x32_f16 v[34:37], v[174:177], v[150:153], v[34:37]
	v_mfma_f32_16x16x32_f16 v[30:33], v[162:165], v[154:157], v[30:33]
	v_mfma_f32_16x16x32_f16 v[26:29], v[166:169], v[154:157], v[26:29]
	v_mfma_f32_16x16x32_f16 v[22:25], v[170:173], v[154:157], v[22:25]
	v_mfma_f32_16x16x32_f16 v[18:21], v[174:177], v[154:157], v[18:21]
	v_mfma_f32_16x16x32_f16 v[14:17], v[162:165], v[158:161], v[14:17]
	v_mfma_f32_16x16x32_f16 v[10:13], v[166:169], v[158:161], v[10:13]
	v_mfma_f32_16x16x32_f16 v[6:9], v[170:173], v[158:161], v[6:9]
	v_mfma_f32_16x16x32_f16 v[2:5], v[174:177], v[158:161], v[2:5]
	s_barrier
	s_add_u32 s36, s36, 0x80
	s_addc_u32 s37, s37, 0
	s_add_u32 s38, s38, 0x80
	s_addc_u32 s39, s39, 0
	ds_read_b128 v[130:133], v204 offset:0
	ds_read_b128 v[134:137], v204 offset:2048
	ds_read_b128 v[138:141], v204 offset:4096
	ds_read_b128 v[142:145], v204 offset:6144
	ds_read_b128 v[162:165], v206 offset:32768
	ds_read_b128 v[166:169], v206 offset:34816
	ds_read_b128 v[170:173], v206 offset:36864
	ds_read_b128 v[174:177], v206 offset:38912
	s_add_i32 m0, s21, 0x4000
	s_add_u32 s40, s36, 0x40080
	s_addc_u32 s41, s37, 0
	global_load_lds_dwordx4 v1, s[40:41]
	s_add_i32 m0, s21, 0xa000
	s_add_u32 s40, s38, 0x20080
	s_addc_u32 s41, s39, 0
	global_load_lds_dwordx4 v1, s[40:41]
	s_waitcnt vmcnt(4)
	s_barrier
	s_waitcnt lgkmcnt(0)
	v_mfma_f32_16x16x32_f16 v[126:129], v[162:165], v[130:133], v[126:129]
	v_mfma_f32_16x16x32_f16 v[122:125], v[166:169], v[130:133], v[122:125]
	v_mfma_f32_16x16x32_f16 v[118:121], v[170:173], v[130:133], v[118:121]
	v_mfma_f32_16x16x32_f16 v[114:117], v[174:177], v[130:133], v[114:117]
	v_mfma_f32_16x16x32_f16 v[110:113], v[162:165], v[134:137], v[110:113]
	v_mfma_f32_16x16x32_f16 v[106:109], v[166:169], v[134:137], v[106:109]
	v_mfma_f32_16x16x32_f16 v[102:105], v[170:173], v[134:137], v[102:105]
	v_mfma_f32_16x16x32_f16 v[98:101], v[174:177], v[134:137], v[98:101]
	v_mfma_f32_16x16x32_f16 v[94:97], v[162:165], v[138:141], v[94:97]
	v_mfma_f32_16x16x32_f16 v[90:93], v[166:169], v[138:141], v[90:93]
	v_mfma_f32_16x16x32_f16 v[86:89], v[170:173], v[138:141], v[86:89]
	v_mfma_f32_16x16x32_f16 v[82:85], v[174:177], v[138:141], v[82:85]
	v_mfma_f32_16x16x32_f16 v[78:81], v[162:165], v[142:145], v[78:81]
	v_mfma_f32_16x16x32_f16 v[74:77], v[166:169], v[142:145], v[74:77]
	v_mfma_f32_16x16x32_f16 v[70:73], v[170:173], v[142:145], v[70:73]
	v_mfma_f32_16x16x32_f16 v[66:69], v[174:177], v[142:145], v[66:69]
	s_barrier
	ds_read_b128 v[146:149], v204 offset:8192
	ds_read_b128 v[150:153], v204 offset:10240
	ds_read_b128 v[154:157], v204 offset:12288
	ds_read_b128 v[158:161], v204 offset:14336
	s_add_i32 m0, s21, 0xc000
	s_add_u32 s40, s38, 0x40080
	s_addc_u32 s41, s39, 0
	global_load_lds_dwordx4 v1, s[40:41]
	s_add_i32 m0, s21, 0xe000
	s_add_u32 s40, s38, 0x60080
	s_addc_u32 s41, s39, 0
	global_load_lds_dwordx4 v1, s[40:41]
	s_barrier
	s_waitcnt lgkmcnt(0)
	v_mfma_f32_16x16x32_f16 v[62:65], v[162:165], v[146:149], v[62:65]
	v_mfma_f32_16x16x32_f16 v[58:61], v[166:169], v[146:149], v[58:61]
	v_mfma_f32_16x16x32_f16 v[54:57], v[170:173], v[146:149], v[54:57]
	v_mfma_f32_16x16x32_f16 v[50:53], v[174:177], v[146:149], v[50:53]
	v_mfma_f32_16x16x32_f16 v[46:49], v[162:165], v[150:153], v[46:49]
	v_mfma_f32_16x16x32_f16 v[42:45], v[166:169], v[150:153], v[42:45]
	v_mfma_f32_16x16x32_f16 v[38:41], v[170:173], v[150:153], v[38:41]
	v_mfma_f32_16x16x32_f16 v[34:37], v[174:177], v[150:153], v[34:37]
	v_mfma_f32_16x16x32_f16 v[30:33], v[162:165], v[154:157], v[30:33]
	v_mfma_f32_16x16x32_f16 v[26:29], v[166:169], v[154:157], v[26:29]
	v_mfma_f32_16x16x32_f16 v[22:25], v[170:173], v[154:157], v[22:25]
	v_mfma_f32_16x16x32_f16 v[18:21], v[174:177], v[154:157], v[18:21]
	v_mfma_f32_16x16x32_f16 v[14:17], v[162:165], v[158:161], v[14:17]
	v_mfma_f32_16x16x32_f16 v[10:13], v[166:169], v[158:161], v[10:13]
	v_mfma_f32_16x16x32_f16 v[6:9], v[170:173], v[158:161], v[6:9]
	v_mfma_f32_16x16x32_f16 v[2:5], v[174:177], v[158:161], v[2:5]
	s_barrier
	ds_read_b128 v[130:133], v205 offset:0
	ds_read_b128 v[134:137], v205 offset:2048
	ds_read_b128 v[138:141], v205 offset:4096
	ds_read_b128 v[142:145], v205 offset:6144
	ds_read_b128 v[162:165], v207 offset:32768
	ds_read_b128 v[166:169], v207 offset:34816
	ds_read_b128 v[170:173], v207 offset:36864
	ds_read_b128 v[174:177], v207 offset:38912
	s_add_i32 m0, s21, 0x2000
	s_add_u32 s40, s36, 0x20080
	s_addc_u32 s41, s37, 0
	global_load_lds_dwordx4 v1, s[40:41]
	s_add_i32 m0, s21, 0x6000
	s_add_u32 s40, s36, 0x60080
	s_addc_u32 s41, s37, 0
	global_load_lds_dwordx4 v1, s[40:41]
	s_waitcnt lgkmcnt(0)
	s_barrier
	v_mfma_f32_16x16x32_f16 v[126:129], v[162:165], v[130:133], v[126:129]
	v_mfma_f32_16x16x32_f16 v[122:125], v[166:169], v[130:133], v[122:125]
	v_mfma_f32_16x16x32_f16 v[118:121], v[170:173], v[130:133], v[118:121]
	v_mfma_f32_16x16x32_f16 v[114:117], v[174:177], v[130:133], v[114:117]
	v_mfma_f32_16x16x32_f16 v[110:113], v[162:165], v[134:137], v[110:113]
	v_mfma_f32_16x16x32_f16 v[106:109], v[166:169], v[134:137], v[106:109]
	v_mfma_f32_16x16x32_f16 v[102:105], v[170:173], v[134:137], v[102:105]
	v_mfma_f32_16x16x32_f16 v[98:101], v[174:177], v[134:137], v[98:101]
	v_mfma_f32_16x16x32_f16 v[94:97], v[162:165], v[138:141], v[94:97]
	v_mfma_f32_16x16x32_f16 v[90:93], v[166:169], v[138:141], v[90:93]
	v_mfma_f32_16x16x32_f16 v[86:89], v[170:173], v[138:141], v[86:89]
	v_mfma_f32_16x16x32_f16 v[82:85], v[174:177], v[138:141], v[82:85]
	v_mfma_f32_16x16x32_f16 v[78:81], v[162:165], v[142:145], v[78:81]
	v_mfma_f32_16x16x32_f16 v[74:77], v[166:169], v[142:145], v[74:77]
	v_mfma_f32_16x16x32_f16 v[70:73], v[170:173], v[142:145], v[70:73]
	v_mfma_f32_16x16x32_f16 v[66:69], v[174:177], v[142:145], v[66:69]
	s_barrier
	ds_read_b128 v[146:149], v205 offset:8192
	ds_read_b128 v[150:153], v205 offset:10240
	ds_read_b128 v[154:157], v205 offset:12288
	ds_read_b128 v[158:161], v205 offset:14336
	s_add_i32 m0, s21, 0x10000
	s_add_u32 s40, s36, 0x100
	s_addc_u32 s41, s37, 0
	global_load_lds_dwordx4 v1, s[40:41]
	s_add_i32 m0, s21, 0x18000
	s_add_u32 s40, s38, 0x100
	s_addc_u32 s41, s39, 0
	global_load_lds_dwordx4 v1, s[40:41]
	s_waitcnt vmcnt(4)
	s_barrier
	s_waitcnt lgkmcnt(0)
	v_mfma_f32_16x16x32_f16 v[62:65], v[162:165], v[146:149], v[62:65]
	v_mfma_f32_16x16x32_f16 v[58:61], v[166:169], v[146:149], v[58:61]
	v_mfma_f32_16x16x32_f16 v[54:57], v[170:173], v[146:149], v[54:57]
	v_mfma_f32_16x16x32_f16 v[50:53], v[174:177], v[146:149], v[50:53]
	v_mfma_f32_16x16x32_f16 v[46:49], v[162:165], v[150:153], v[46:49]
	v_mfma_f32_16x16x32_f16 v[42:45], v[166:169], v[150:153], v[42:45]
	v_mfma_f32_16x16x32_f16 v[38:41], v[170:173], v[150:153], v[38:41]
	v_mfma_f32_16x16x32_f16 v[34:37], v[174:177], v[150:153], v[34:37]
	v_mfma_f32_16x16x32_f16 v[30:33], v[162:165], v[154:157], v[30:33]
	v_mfma_f32_16x16x32_f16 v[26:29], v[166:169], v[154:157], v[26:29]
	v_mfma_f32_16x16x32_f16 v[22:25], v[170:173], v[154:157], v[22:25]
	v_mfma_f32_16x16x32_f16 v[18:21], v[174:177], v[154:157], v[18:21]
	v_mfma_f32_16x16x32_f16 v[14:17], v[162:165], v[158:161], v[14:17]
	v_mfma_f32_16x16x32_f16 v[10:13], v[166:169], v[158:161], v[10:13]
	v_mfma_f32_16x16x32_f16 v[6:9], v[170:173], v[158:161], v[6:9]
	v_mfma_f32_16x16x32_f16 v[2:5], v[174:177], v[158:161], v[2:5]
	s_barrier
	s_add_u32 s36, s36, 0x80
	s_addc_u32 s37, s37, 0
	s_add_u32 s38, s38, 0x80
	s_addc_u32 s39, s39, 0
	s_movk_i32 s23, 6
.Lp3_loop:
	ds_read_b128 v[130:133], v200 offset:0
	ds_read_b128 v[134:137], v200 offset:2048
	ds_read_b128 v[138:141], v200 offset:4096
	ds_read_b128 v[142:145], v200 offset:6144
	ds_read_b128 v[162:165], v202 offset:32768
	ds_read_b128 v[166:169], v202 offset:34816
	ds_read_b128 v[170:173], v202 offset:36864
	ds_read_b128 v[174:177], v202 offset:38912
	s_add_i32 m0, s21, 0x14000
	s_add_u32 s40, s36, 0x40080
	s_addc_u32 s41, s37, 0
	global_load_lds_dwordx4 v1, s[40:41]
	s_add_i32 m0, s21, 0x1a000
	s_add_u32 s40, s38, 0x20080
	s_addc_u32 s41, s39, 0
	global_load_lds_dwordx4 v1, s[40:41]
	s_waitcnt vmcnt(4)
	s_barrier
	s_waitcnt lgkmcnt(0)
	v_mfma_f32_16x16x32_f16 v[126:129], v[162:165], v[130:133], v[126:129]
	v_mfma_f32_16x16x32_f16 v[122:125], v[166:169], v[130:133], v[122:125]
	v_mfma_f32_16x16x32_f16 v[118:121], v[170:173], v[130:133], v[118:121]
	v_mfma_f32_16x16x32_f16 v[114:117], v[174:177], v[130:133], v[114:117]
	v_mfma_f32_16x16x32_f16 v[110:113], v[162:165], v[134:137], v[110:113]
	v_mfma_f32_16x16x32_f16 v[106:109], v[166:169], v[134:137], v[106:109]
	v_mfma_f32_16x16x32_f16 v[102:105], v[170:173], v[134:137], v[102:105]
	v_mfma_f32_16x16x32_f16 v[98:101], v[174:177], v[134:137], v[98:101]
	v_mfma_f32_16x16x32_f16 v[94:97], v[162:165], v[138:141], v[94:97]
	v_mfma_f32_16x16x32_f16 v[90:93], v[166:169], v[138:141], v[90:93]
	v_mfma_f32_16x16x32_f16 v[86:89], v[170:173], v[138:141], v[86:89]
	v_mfma_f32_16x16x32_f16 v[82:85], v[174:177], v[138:141], v[82:85]
	v_mfma_f32_16x16x32_f16 v[78:81], v[162:165], v[142:145], v[78:81]
	v_mfma_f32_16x16x32_f16 v[74:77], v[166:169], v[142:145], v[74:77]
	v_mfma_f32_16x16x32_f16 v[70:73], v[170:173], v[142:145], v[70:73]
	v_mfma_f32_16x16x32_f16 v[66:69], v[174:177], v[142:145], v[66:69]
	s_barrier
	ds_read_b128 v[146:149], v200 offset:8192
	ds_read_b128 v[150:153], v200 offset:10240
	ds_read_b128 v[154:157], v200 offset:12288
	ds_read_b128 v[158:161], v200 offset:14336
	s_add_i32 m0, s21, 0x1c000
	s_add_u32 s40, s38, 0x40080
	s_addc_u32 s41, s39, 0
	global_load_lds_dwordx4 v1, s[40:41]
	s_add_i32 m0, s21, 0x1e000
	s_add_u32 s40, s38, 0x60080
	s_addc_u32 s41, s39, 0
	global_load_lds_dwordx4 v1, s[40:41]
	s_barrier
	s_waitcnt lgkmcnt(0)
	v_mfma_f32_16x16x32_f16 v[62:65], v[162:165], v[146:149], v[62:65]
	v_mfma_f32_16x16x32_f16 v[58:61], v[166:169], v[146:149], v[58:61]
	v_mfma_f32_16x16x32_f16 v[54:57], v[170:173], v[146:149], v[54:57]
	v_mfma_f32_16x16x32_f16 v[50:53], v[174:177], v[146:149], v[50:53]
	v_mfma_f32_16x16x32_f16 v[46:49], v[162:165], v[150:153], v[46:49]
	v_mfma_f32_16x16x32_f16 v[42:45], v[166:169], v[150:153], v[42:45]
	v_mfma_f32_16x16x32_f16 v[38:41], v[170:173], v[150:153], v[38:41]
	v_mfma_f32_16x16x32_f16 v[34:37], v[174:177], v[150:153], v[34:37]
	v_mfma_f32_16x16x32_f16 v[30:33], v[162:165], v[154:157], v[30:33]
	v_mfma_f32_16x16x32_f16 v[26:29], v[166:169], v[154:157], v[26:29]
	v_mfma_f32_16x16x32_f16 v[22:25], v[170:173], v[154:157], v[22:25]
	v_mfma_f32_16x16x32_f16 v[18:21], v[174:177], v[154:157], v[18:21]
	v_mfma_f32_16x16x32_f16 v[14:17], v[162:165], v[158:161], v[14:17]
	v_mfma_f32_16x16x32_f16 v[10:13], v[166:169], v[158:161], v[10:13]
	v_mfma_f32_16x16x32_f16 v[6:9], v[170:173], v[158:161], v[6:9]
	v_mfma_f32_16x16x32_f16 v[2:5], v[174:177], v[158:161], v[2:5]
	s_barrier
	ds_read_b128 v[130:133], v201 offset:0
	ds_read_b128 v[134:137], v201 offset:2048
	ds_read_b128 v[138:141], v201 offset:4096
	ds_read_b128 v[142:145], v201 offset:6144
	ds_read_b128 v[162:165], v203 offset:32768
	ds_read_b128 v[166:169], v203 offset:34816
	ds_read_b128 v[170:173], v203 offset:36864
	ds_read_b128 v[174:177], v203 offset:38912
	s_add_i32 m0, s21, 0x12000
	s_add_u32 s40, s36, 0x20080
	s_addc_u32 s41, s37, 0
	global_load_lds_dwordx4 v1, s[40:41]
	s_add_i32 m0, s21, 0x16000
	s_add_u32 s40, s36, 0x60080
	s_addc_u32 s41, s37, 0
	global_load_lds_dwordx4 v1, s[40:41]
	s_waitcnt lgkmcnt(0)
	s_barrier
	v_mfma_f32_16x16x32_f16 v[126:129], v[162:165], v[130:133], v[126:129]
	v_mfma_f32_16x16x32_f16 v[122:125], v[166:169], v[130:133], v[122:125]
	v_mfma_f32_16x16x32_f16 v[118:121], v[170:173], v[130:133], v[118:121]
	v_mfma_f32_16x16x32_f16 v[114:117], v[174:177], v[130:133], v[114:117]
	v_mfma_f32_16x16x32_f16 v[110:113], v[162:165], v[134:137], v[110:113]
	v_mfma_f32_16x16x32_f16 v[106:109], v[166:169], v[134:137], v[106:109]
	v_mfma_f32_16x16x32_f16 v[102:105], v[170:173], v[134:137], v[102:105]
	v_mfma_f32_16x16x32_f16 v[98:101], v[174:177], v[134:137], v[98:101]
	v_mfma_f32_16x16x32_f16 v[94:97], v[162:165], v[138:141], v[94:97]
	v_mfma_f32_16x16x32_f16 v[90:93], v[166:169], v[138:141], v[90:93]
	v_mfma_f32_16x16x32_f16 v[86:89], v[170:173], v[138:141], v[86:89]
	v_mfma_f32_16x16x32_f16 v[82:85], v[174:177], v[138:141], v[82:85]
	v_mfma_f32_16x16x32_f16 v[78:81], v[162:165], v[142:145], v[78:81]
	v_mfma_f32_16x16x32_f16 v[74:77], v[166:169], v[142:145], v[74:77]
	v_mfma_f32_16x16x32_f16 v[70:73], v[170:173], v[142:145], v[70:73]
	v_mfma_f32_16x16x32_f16 v[66:69], v[174:177], v[142:145], v[66:69]
	s_barrier
	ds_read_b128 v[146:149], v201 offset:8192
	ds_read_b128 v[150:153], v201 offset:10240
	ds_read_b128 v[154:157], v201 offset:12288
	ds_read_b128 v[158:161], v201 offset:14336
	s_mov_b32 m0, s21
	s_add_u32 s40, s36, 0x100
	s_addc_u32 s41, s37, 0
	global_load_lds_dwordx4 v1, s[40:41]
	s_add_i32 m0, s21, 0x8000
	s_add_u32 s40, s38, 0x100
	s_addc_u32 s41, s39, 0
	global_load_lds_dwordx4 v1, s[40:41]
	s_waitcnt vmcnt(4)
	s_barrier
	s_waitcnt lgkmcnt(0)
	v_mfma_f32_16x16x32_f16 v[62:65], v[162:165], v[146:149], v[62:65]
	v_mfma_f32_16x16x32_f16 v[58:61], v[166:169], v[146:149], v[58:61]
	v_mfma_f32_16x16x32_f16 v[54:57], v[170:173], v[146:149], v[54:57]
	v_mfma_f32_16x16x32_f16 v[50:53], v[174:177], v[146:149], v[50:53]
	v_mfma_f32_16x16x32_f16 v[46:49], v[162:165], v[150:153], v[46:49]
	v_mfma_f32_16x16x32_f16 v[42:45], v[166:169], v[150:153], v[42:45]
	v_mfma_f32_16x16x32_f16 v[38:41], v[170:173], v[150:153], v[38:41]
	v_mfma_f32_16x16x32_f16 v[34:37], v[174:177], v[150:153], v[34:37]
	v_mfma_f32_16x16x32_f16 v[30:33], v[162:165], v[154:157], v[30:33]
	v_mfma_f32_16x16x32_f16 v[26:29], v[166:169], v[154:157], v[26:29]
	v_mfma_f32_16x16x32_f16 v[22:25], v[170:173], v[154:157], v[22:25]
	v_mfma_f32_16x16x32_f16 v[18:21], v[174:177], v[154:157], v[18:21]
	v_mfma_f32_16x16x32_f16 v[14:17], v[162:165], v[158:161], v[14:17]
	v_mfma_f32_16x16x32_f16 v[10:13], v[166:169], v[158:161], v[10:13]
	v_mfma_f32_16x16x32_f16 v[6:9], v[170:173], v[158:161], v[6:9]
	v_mfma_f32_16x16x32_f16 v[2:5], v[174:177], v[158:161], v[2:5]
	s_barrier
	s_add_u32 s36, s36, 0x80
	s_addc_u32 s37, s37, 0
	s_add_u32 s38, s38, 0x80
	s_addc_u32 s39, s39, 0
	ds_read_b128 v[130:133], v204 offset:0
	ds_read_b128 v[134:137], v204 offset:2048
	ds_read_b128 v[138:141], v204 offset:4096
	ds_read_b128 v[142:145], v204 offset:6144
	ds_read_b128 v[162:165], v206 offset:32768
	ds_read_b128 v[166:169], v206 offset:34816
	ds_read_b128 v[170:173], v206 offset:36864
	ds_read_b128 v[174:177], v206 offset:38912
	s_add_i32 m0, s21, 0x4000
	s_add_u32 s40, s36, 0x40080
	s_addc_u32 s41, s37, 0
	global_load_lds_dwordx4 v1, s[40:41]
	s_add_i32 m0, s21, 0xa000
	s_add_u32 s40, s38, 0x20080
	s_addc_u32 s41, s39, 0
	global_load_lds_dwordx4 v1, s[40:41]
	s_waitcnt vmcnt(4)
	s_barrier
	s_waitcnt lgkmcnt(0)
	v_mfma_f32_16x16x32_f16 v[126:129], v[162:165], v[130:133], v[126:129]
	v_mfma_f32_16x16x32_f16 v[122:125], v[166:169], v[130:133], v[122:125]
	v_mfma_f32_16x16x32_f16 v[118:121], v[170:173], v[130:133], v[118:121]
	v_mfma_f32_16x16x32_f16 v[114:117], v[174:177], v[130:133], v[114:117]
	v_mfma_f32_16x16x32_f16 v[110:113], v[162:165], v[134:137], v[110:113]
	v_mfma_f32_16x16x32_f16 v[106:109], v[166:169], v[134:137], v[106:109]
	v_mfma_f32_16x16x32_f16 v[102:105], v[170:173], v[134:137], v[102:105]
	v_mfma_f32_16x16x32_f16 v[98:101], v[174:177], v[134:137], v[98:101]
	v_mfma_f32_16x16x32_f16 v[94:97], v[162:165], v[138:141], v[94:97]
	v_mfma_f32_16x16x32_f16 v[90:93], v[166:169], v[138:141], v[90:93]
	v_mfma_f32_16x16x32_f16 v[86:89], v[170:173], v[138:141], v[86:89]
	v_mfma_f32_16x16x32_f16 v[82:85], v[174:177], v[138:141], v[82:85]
	v_mfma_f32_16x16x32_f16 v[78:81], v[162:165], v[142:145], v[78:81]
	v_mfma_f32_16x16x32_f16 v[74:77], v[166:169], v[142:145], v[74:77]
	v_mfma_f32_16x16x32_f16 v[70:73], v[170:173], v[142:145], v[70:73]
	v_mfma_f32_16x16x32_f16 v[66:69], v[174:177], v[142:145], v[66:69]
	s_barrier
	ds_read_b128 v[146:149], v204 offset:8192
	ds_read_b128 v[150:153], v204 offset:10240
	ds_read_b128 v[154:157], v204 offset:12288
	ds_read_b128 v[158:161], v204 offset:14336
	s_add_i32 m0, s21, 0xc000
	s_add_u32 s40, s38, 0x40080
	s_addc_u32 s41, s39, 0
	global_load_lds_dwordx4 v1, s[40:41]
	s_add_i32 m0, s21, 0xe000
	s_add_u32 s40, s38, 0x60080
	s_addc_u32 s41, s39, 0
	global_load_lds_dwordx4 v1, s[40:41]
	s_barrier
	s_waitcnt lgkmcnt(0)
	v_mfma_f32_16x16x32_f16 v[62:65], v[162:165], v[146:149], v[62:65]
	v_mfma_f32_16x16x32_f16 v[58:61], v[166:169], v[146:149], v[58:61]
	v_mfma_f32_16x16x32_f16 v[54:57], v[170:173], v[146:149], v[54:57]
	v_mfma_f32_16x16x32_f16 v[50:53], v[174:177], v[146:149], v[50:53]
	v_mfma_f32_16x16x32_f16 v[46:49], v[162:165], v[150:153], v[46:49]
	v_mfma_f32_16x16x32_f16 v[42:45], v[166:169], v[150:153], v[42:45]
	v_mfma_f32_16x16x32_f16 v[38:41], v[170:173], v[150:153], v[38:41]
	v_mfma_f32_16x16x32_f16 v[34:37], v[174:177], v[150:153], v[34:37]
	v_mfma_f32_16x16x32_f16 v[30:33], v[162:165], v[154:157], v[30:33]
	v_mfma_f32_16x16x32_f16 v[26:29], v[166:169], v[154:157], v[26:29]
	v_mfma_f32_16x16x32_f16 v[22:25], v[170:173], v[154:157], v[22:25]
	v_mfma_f32_16x16x32_f16 v[18:21], v[174:177], v[154:157], v[18:21]
	v_mfma_f32_16x16x32_f16 v[14:17], v[162:165], v[158:161], v[14:17]
	v_mfma_f32_16x16x32_f16 v[10:13], v[166:169], v[158:161], v[10:13]
	v_mfma_f32_16x16x32_f16 v[6:9], v[170:173], v[158:161], v[6:9]
	v_mfma_f32_16x16x32_f16 v[2:5], v[174:177], v[158:161], v[2:5]
	s_barrier
	ds_read_b128 v[130:133], v205 offset:0
	ds_read_b128 v[134:137], v205 offset:2048
	ds_read_b128 v[138:141], v205 offset:4096
	ds_read_b128 v[142:145], v205 offset:6144
	ds_read_b128 v[162:165], v207 offset:32768
	ds_read_b128 v[166:169], v207 offset:34816
	ds_read_b128 v[170:173], v207 offset:36864
	ds_read_b128 v[174:177], v207 offset:38912
	s_add_i32 m0, s21, 0x2000
	s_add_u32 s40, s36, 0x20080
	s_addc_u32 s41, s37, 0
	global_load_lds_dwordx4 v1, s[40:41]
	s_add_i32 m0, s21, 0x6000
	s_add_u32 s40, s36, 0x60080
	s_addc_u32 s41, s37, 0
	global_load_lds_dwordx4 v1, s[40:41]
	s_waitcnt lgkmcnt(0)
	s_barrier
	v_mfma_f32_16x16x32_f16 v[126:129], v[162:165], v[130:133], v[126:129]
	v_mfma_f32_16x16x32_f16 v[122:125], v[166:169], v[130:133], v[122:125]
	v_mfma_f32_16x16x32_f16 v[118:121], v[170:173], v[130:133], v[118:121]
	v_mfma_f32_16x16x32_f16 v[114:117], v[174:177], v[130:133], v[114:117]
	v_mfma_f32_16x16x32_f16 v[110:113], v[162:165], v[134:137], v[110:113]
	v_mfma_f32_16x16x32_f16 v[106:109], v[166:169], v[134:137], v[106:109]
	v_mfma_f32_16x16x32_f16 v[102:105], v[170:173], v[134:137], v[102:105]
	v_mfma_f32_16x16x32_f16 v[98:101], v[174:177], v[134:137], v[98:101]
	v_mfma_f32_16x16x32_f16 v[94:97], v[162:165], v[138:141], v[94:97]
	v_mfma_f32_16x16x32_f16 v[90:93], v[166:169], v[138:141], v[90:93]
	v_mfma_f32_16x16x32_f16 v[86:89], v[170:173], v[138:141], v[86:89]
	v_mfma_f32_16x16x32_f16 v[82:85], v[174:177], v[138:141], v[82:85]
	v_mfma_f32_16x16x32_f16 v[78:81], v[162:165], v[142:145], v[78:81]
	v_mfma_f32_16x16x32_f16 v[74:77], v[166:169], v[142:145], v[74:77]
	v_mfma_f32_16x16x32_f16 v[70:73], v[170:173], v[142:145], v[70:73]
	v_mfma_f32_16x16x32_f16 v[66:69], v[174:177], v[142:145], v[66:69]
	s_barrier
	ds_read_b128 v[146:149], v205 offset:8192
	ds_read_b128 v[150:153], v205 offset:10240
	ds_read_b128 v[154:157], v205 offset:12288
	ds_read_b128 v[158:161], v205 offset:14336
	s_add_i32 m0, s21, 0x10000
	s_add_u32 s40, s36, 0x100
	s_addc_u32 s41, s37, 0
	global_load_lds_dwordx4 v1, s[40:41]
	s_add_i32 m0, s21, 0x18000
	s_add_u32 s40, s38, 0x100
	s_addc_u32 s41, s39, 0
	global_load_lds_dwordx4 v1, s[40:41]
	s_waitcnt vmcnt(4)
	s_barrier
	s_waitcnt lgkmcnt(0)
	v_mfma_f32_16x16x32_f16 v[62:65], v[162:165], v[146:149], v[62:65]
	v_mfma_f32_16x16x32_f16 v[58:61], v[166:169], v[146:149], v[58:61]
	v_mfma_f32_16x16x32_f16 v[54:57], v[170:173], v[146:149], v[54:57]
	v_mfma_f32_16x16x32_f16 v[50:53], v[174:177], v[146:149], v[50:53]
	v_mfma_f32_16x16x32_f16 v[46:49], v[162:165], v[150:153], v[46:49]
	v_mfma_f32_16x16x32_f16 v[42:45], v[166:169], v[150:153], v[42:45]
	v_mfma_f32_16x16x32_f16 v[38:41], v[170:173], v[150:153], v[38:41]
	v_mfma_f32_16x16x32_f16 v[34:37], v[174:177], v[150:153], v[34:37]
	v_mfma_f32_16x16x32_f16 v[30:33], v[162:165], v[154:157], v[30:33]
	v_mfma_f32_16x16x32_f16 v[26:29], v[166:169], v[154:157], v[26:29]
	v_mfma_f32_16x16x32_f16 v[22:25], v[170:173], v[154:157], v[22:25]
	v_mfma_f32_16x16x32_f16 v[18:21], v[174:177], v[154:157], v[18:21]
	v_mfma_f32_16x16x32_f16 v[14:17], v[162:165], v[158:161], v[14:17]
	v_mfma_f32_16x16x32_f16 v[10:13], v[166:169], v[158:161], v[10:13]
	v_mfma_f32_16x16x32_f16 v[6:9], v[170:173], v[158:161], v[6:9]
	v_mfma_f32_16x16x32_f16 v[2:5], v[174:177], v[158:161], v[2:5]
	s_barrier
	s_add_u32 s36, s36, 0x80
	s_addc_u32 s37, s37, 0
	s_add_u32 s38, s38, 0x80
	s_addc_u32 s39, s39, 0
	s_add_i32 s23, s23, -1
	s_cmp_lg_u32 s23, 0
	s_cbranch_scc1 .Lp3_loop
	ds_read_b128 v[130:133], v200 offset:0
	ds_read_b128 v[134:137], v200 offset:2048
	ds_read_b128 v[138:141], v200 offset:4096
	ds_read_b128 v[142:145], v200 offset:6144
	ds_read_b128 v[162:165], v202 offset:32768
	ds_read_b128 v[166:169], v202 offset:34816
	ds_read_b128 v[170:173], v202 offset:36864
	ds_read_b128 v[174:177], v202 offset:38912
	s_add_i32 m0, s21, 0x14000
	s_add_u32 s40, s36, 0x40080
	s_addc_u32 s41, s37, 0
	global_load_lds_dwordx4 v1, s[40:41]
	s_add_i32 m0, s21, 0x1a000
	s_add_u32 s40, s38, 0x20080
	s_addc_u32 s41, s39, 0
	global_load_lds_dwordx4 v1, s[40:41]
	s_waitcnt vmcnt(4)
	s_barrier
	s_waitcnt lgkmcnt(0)
	v_mfma_f32_16x16x32_f16 v[126:129], v[162:165], v[130:133], v[126:129]
	v_mfma_f32_16x16x32_f16 v[122:125], v[166:169], v[130:133], v[122:125]
	v_mfma_f32_16x16x32_f16 v[118:121], v[170:173], v[130:133], v[118:121]
	v_mfma_f32_16x16x32_f16 v[114:117], v[174:177], v[130:133], v[114:117]
	v_mfma_f32_16x16x32_f16 v[110:113], v[162:165], v[134:137], v[110:113]
	v_mfma_f32_16x16x32_f16 v[106:109], v[166:169], v[134:137], v[106:109]
	v_mfma_f32_16x16x32_f16 v[102:105], v[170:173], v[134:137], v[102:105]
	v_mfma_f32_16x16x32_f16 v[98:101], v[174:177], v[134:137], v[98:101]
	v_mfma_f32_16x16x32_f16 v[94:97], v[162:165], v[138:141], v[94:97]
	v_mfma_f32_16x16x32_f16 v[90:93], v[166:169], v[138:141], v[90:93]
	v_mfma_f32_16x16x32_f16 v[86:89], v[170:173], v[138:141], v[86:89]
	v_mfma_f32_16x16x32_f16 v[82:85], v[174:177], v[138:141], v[82:85]
	v_mfma_f32_16x16x32_f16 v[78:81], v[162:165], v[142:145], v[78:81]
	v_mfma_f32_16x16x32_f16 v[74:77], v[166:169], v[142:145], v[74:77]
	v_mfma_f32_16x16x32_f16 v[70:73], v[170:173], v[142:145], v[70:73]
	v_mfma_f32_16x16x32_f16 v[66:69], v[174:177], v[142:145], v[66:69]
	s_barrier
	ds_read_b128 v[146:149], v200 offset:8192
	ds_read_b128 v[150:153], v200 offset:10240
	ds_read_b128 v[154:157], v200 offset:12288
	ds_read_b128 v[158:161], v200 offset:14336
	s_add_i32 m0, s21, 0x1c000
	s_add_u32 s40, s38, 0x40080
	s_addc_u32 s41, s39, 0
	global_load_lds_dwordx4 v1, s[40:41]
	s_add_i32 m0, s21, 0x1e000
	s_add_u32 s40, s38, 0x60080
	s_addc_u32 s41, s39, 0
	global_load_lds_dwordx4 v1, s[40:41]
	s_barrier
	s_waitcnt lgkmcnt(0)
	v_mfma_f32_16x16x32_f16 v[62:65], v[162:165], v[146:149], v[62:65]
	v_mfma_f32_16x16x32_f16 v[58:61], v[166:169], v[146:149], v[58:61]
	v_mfma_f32_16x16x32_f16 v[54:57], v[170:173], v[146:149], v[54:57]
	v_mfma_f32_16x16x32_f16 v[50:53], v[174:177], v[146:149], v[50:53]
	v_mfma_f32_16x16x32_f16 v[46:49], v[162:165], v[150:153], v[46:49]
	v_mfma_f32_16x16x32_f16 v[42:45], v[166:169], v[150:153], v[42:45]
	v_mfma_f32_16x16x32_f16 v[38:41], v[170:173], v[150:153], v[38:41]
	v_mfma_f32_16x16x32_f16 v[34:37], v[174:177], v[150:153], v[34:37]
	v_mfma_f32_16x16x32_f16 v[30:33], v[162:165], v[154:157], v[30:33]
	v_mfma_f32_16x16x32_f16 v[26:29], v[166:169], v[154:157], v[26:29]
	v_mfma_f32_16x16x32_f16 v[22:25], v[170:173], v[154:157], v[22:25]
	v_mfma_f32_16x16x32_f16 v[18:21], v[174:177], v[154:157], v[18:21]
	v_mfma_f32_16x16x32_f16 v[14:17], v[162:165], v[158:161], v[14:17]
	v_mfma_f32_16x16x32_f16 v[10:13], v[166:169], v[158:161], v[10:13]
	v_mfma_f32_16x16x32_f16 v[6:9], v[170:173], v[158:161], v[6:9]
	v_mfma_f32_16x16x32_f16 v[2:5], v[174:177], v[158:161], v[2:5]
	s_barrier
	ds_read_b128 v[130:133], v201 offset:0
	ds_read_b128 v[134:137], v201 offset:2048
	ds_read_b128 v[138:141], v201 offset:4096
	ds_read_b128 v[142:145], v201 offset:6144
	ds_read_b128 v[162:165], v203 offset:32768
	ds_read_b128 v[166:169], v203 offset:34816
	ds_read_b128 v[170:173], v203 offset:36864
	ds_read_b128 v[174:177], v203 offset:38912
	s_add_i32 m0, s21, 0x12000
	s_add_u32 s40, s36, 0x20080
	s_addc_u32 s41, s37, 0
	global_load_lds_dwordx4 v1, s[40:41]
	s_add_i32 m0, s21, 0x16000
	s_add_u32 s40, s36, 0x60080
	s_addc_u32 s41, s37, 0
	global_load_lds_dwordx4 v1, s[40:41]
	s_waitcnt lgkmcnt(0)
	s_barrier
	v_mfma_f32_16x16x32_f16 v[126:129], v[162:165], v[130:133], v[126:129]
	v_mfma_f32_16x16x32_f16 v[122:125], v[166:169], v[130:133], v[122:125]
	v_mfma_f32_16x16x32_f16 v[118:121], v[170:173], v[130:133], v[118:121]
	v_mfma_f32_16x16x32_f16 v[114:117], v[174:177], v[130:133], v[114:117]
	v_mfma_f32_16x16x32_f16 v[110:113], v[162:165], v[134:137], v[110:113]
	v_mfma_f32_16x16x32_f16 v[106:109], v[166:169], v[134:137], v[106:109]
	v_mfma_f32_16x16x32_f16 v[102:105], v[170:173], v[134:137], v[102:105]
	v_mfma_f32_16x16x32_f16 v[98:101], v[174:177], v[134:137], v[98:101]
	v_mfma_f32_16x16x32_f16 v[94:97], v[162:165], v[138:141], v[94:97]
	v_mfma_f32_16x16x32_f16 v[90:93], v[166:169], v[138:141], v[90:93]
	v_mfma_f32_16x16x32_f16 v[86:89], v[170:173], v[138:141], v[86:89]
	v_mfma_f32_16x16x32_f16 v[82:85], v[174:177], v[138:141], v[82:85]
	v_mfma_f32_16x16x32_f16 v[78:81], v[162:165], v[142:145], v[78:81]
	v_mfma_f32_16x16x32_f16 v[74:77], v[166:169], v[142:145], v[74:77]
	v_mfma_f32_16x16x32_f16 v[70:73], v[170:173], v[142:145], v[70:73]
	v_mfma_f32_16x16x32_f16 v[66:69], v[174:177], v[142:145], v[66:69]
	s_barrier
	ds_read_b128 v[146:149], v201 offset:8192
	ds_read_b128 v[150:153], v201 offset:10240
	ds_read_b128 v[154:157], v201 offset:12288
	ds_read_b128 v[158:161], v201 offset:14336
	s_waitcnt vmcnt(2)
	s_barrier
	s_waitcnt lgkmcnt(0)
	v_mfma_f32_16x16x32_f16 v[62:65], v[162:165], v[146:149], v[62:65]
	v_mfma_f32_16x16x32_f16 v[58:61], v[166:169], v[146:149], v[58:61]
	v_mfma_f32_16x16x32_f16 v[54:57], v[170:173], v[146:149], v[54:57]
	v_mfma_f32_16x16x32_f16 v[50:53], v[174:177], v[146:149], v[50:53]
	v_mfma_f32_16x16x32_f16 v[46:49], v[162:165], v[150:153], v[46:49]
	v_mfma_f32_16x16x32_f16 v[42:45], v[166:169], v[150:153], v[42:45]
	v_mfma_f32_16x16x32_f16 v[38:41], v[170:173], v[150:153], v[38:41]
	v_mfma_f32_16x16x32_f16 v[34:37], v[174:177], v[150:153], v[34:37]
	v_mfma_f32_16x16x32_f16 v[30:33], v[162:165], v[154:157], v[30:33]
	v_mfma_f32_16x16x32_f16 v[26:29], v[166:169], v[154:157], v[26:29]
	v_mfma_f32_16x16x32_f16 v[22:25], v[170:173], v[154:157], v[22:25]
	v_mfma_f32_16x16x32_f16 v[18:21], v[174:177], v[154:157], v[18:21]
	v_mfma_f32_16x16x32_f16 v[14:17], v[162:165], v[158:161], v[14:17]
	v_mfma_f32_16x16x32_f16 v[10:13], v[166:169], v[158:161], v[10:13]
	v_mfma_f32_16x16x32_f16 v[6:9], v[170:173], v[158:161], v[6:9]
	v_mfma_f32_16x16x32_f16 v[2:5], v[174:177], v[158:161], v[2:5]
	s_barrier
	s_add_u32 s36, s36, 0x80
	s_addc_u32 s37, s37, 0
	s_add_u32 s38, s38, 0x80
	s_addc_u32 s39, s39, 0
	ds_read_b128 v[130:133], v204 offset:0
	ds_read_b128 v[134:137], v204 offset:2048
	ds_read_b128 v[138:141], v204 offset:4096
	ds_read_b128 v[142:145], v204 offset:6144
	ds_read_b128 v[162:165], v206 offset:32768
	ds_read_b128 v[166:169], v206 offset:34816
	ds_read_b128 v[170:173], v206 offset:36864
	ds_read_b128 v[174:177], v206 offset:38912
	s_waitcnt vmcnt(0)
	s_barrier
	s_waitcnt lgkmcnt(0)
	v_mfma_f32_16x16x32_f16 v[126:129], v[162:165], v[130:133], v[126:129]
	v_mfma_f32_16x16x32_f16 v[122:125], v[166:169], v[130:133], v[122:125]
	v_mfma_f32_16x16x32_f16 v[118:121], v[170:173], v[130:133], v[118:121]
	v_mfma_f32_16x16x32_f16 v[114:117], v[174:177], v[130:133], v[114:117]
	v_mfma_f32_16x16x32_f16 v[110:113], v[162:165], v[134:137], v[110:113]
	v_mfma_f32_16x16x32_f16 v[106:109], v[166:169], v[134:137], v[106:109]
	v_mfma_f32_16x16x32_f16 v[102:105], v[170:173], v[134:137], v[102:105]
	v_mfma_f32_16x16x32_f16 v[98:101], v[174:177], v[134:137], v[98:101]
	v_mfma_f32_16x16x32_f16 v[94:97], v[162:165], v[138:141], v[94:97]
	v_mfma_f32_16x16x32_f16 v[90:93], v[166:169], v[138:141], v[90:93]
	v_mfma_f32_16x16x32_f16 v[86:89], v[170:173], v[138:141], v[86:89]
	v_mfma_f32_16x16x32_f16 v[82:85], v[174:177], v[138:141], v[82:85]
	v_mfma_f32_16x16x32_f16 v[78:81], v[162:165], v[142:145], v[78:81]
	v_mfma_f32_16x16x32_f16 v[74:77], v[166:169], v[142:145], v[74:77]
	v_mfma_f32_16x16x32_f16 v[70:73], v[170:173], v[142:145], v[70:73]
	v_mfma_f32_16x16x32_f16 v[66:69], v[174:177], v[142:145], v[66:69]
	s_barrier
	ds_read_b128 v[146:149], v204 offset:8192
	ds_read_b128 v[150:153], v204 offset:10240
	ds_read_b128 v[154:157], v204 offset:12288
	ds_read_b128 v[158:161], v204 offset:14336
	s_barrier
	s_waitcnt lgkmcnt(0)
	v_mfma_f32_16x16x32_f16 v[62:65], v[162:165], v[146:149], v[62:65]
	v_mfma_f32_16x16x32_f16 v[58:61], v[166:169], v[146:149], v[58:61]
	v_mfma_f32_16x16x32_f16 v[54:57], v[170:173], v[146:149], v[54:57]
	v_mfma_f32_16x16x32_f16 v[50:53], v[174:177], v[146:149], v[50:53]
	v_mfma_f32_16x16x32_f16 v[46:49], v[162:165], v[150:153], v[46:49]
	v_mfma_f32_16x16x32_f16 v[42:45], v[166:169], v[150:153], v[42:45]
	v_mfma_f32_16x16x32_f16 v[38:41], v[170:173], v[150:153], v[38:41]
	v_mfma_f32_16x16x32_f16 v[34:37], v[174:177], v[150:153], v[34:37]
	v_mfma_f32_16x16x32_f16 v[30:33], v[162:165], v[154:157], v[30:33]
	v_mfma_f32_16x16x32_f16 v[26:29], v[166:169], v[154:157], v[26:29]
	v_mfma_f32_16x16x32_f16 v[22:25], v[170:173], v[154:157], v[22:25]
	v_mfma_f32_16x16x32_f16 v[18:21], v[174:177], v[154:157], v[18:21]
	v_mfma_f32_16x16x32_f16 v[14:17], v[162:165], v[158:161], v[14:17]
	v_mfma_f32_16x16x32_f16 v[10:13], v[166:169], v[158:161], v[10:13]
	v_mfma_f32_16x16x32_f16 v[6:9], v[170:173], v[158:161], v[6:9]
	v_mfma_f32_16x16x32_f16 v[2:5], v[174:177], v[158:161], v[2:5]
	s_barrier
	ds_read_b128 v[130:133], v205 offset:0
	ds_read_b128 v[134:137], v205 offset:2048
	ds_read_b128 v[138:141], v205 offset:4096
	ds_read_b128 v[142:145], v205 offset:6144
	ds_read_b128 v[162:165], v207 offset:32768
	ds_read_b128 v[166:169], v207 offset:34816
	ds_read_b128 v[170:173], v207 offset:36864
	ds_read_b128 v[174:177], v207 offset:38912
	s_waitcnt lgkmcnt(0)
	s_barrier
	v_mfma_f32_16x16x32_f16 v[126:129], v[162:165], v[130:133], v[126:129]
	v_mfma_f32_16x16x32_f16 v[122:125], v[166:169], v[130:133], v[122:125]
	v_mfma_f32_16x16x32_f16 v[118:121], v[170:173], v[130:133], v[118:121]
	v_mfma_f32_16x16x32_f16 v[114:117], v[174:177], v[130:133], v[114:117]
	v_mfma_f32_16x16x32_f16 v[110:113], v[162:165], v[134:137], v[110:113]
	v_mfma_f32_16x16x32_f16 v[106:109], v[166:169], v[134:137], v[106:109]
	v_mfma_f32_16x16x32_f16 v[102:105], v[170:173], v[134:137], v[102:105]
	v_mfma_f32_16x16x32_f16 v[98:101], v[174:177], v[134:137], v[98:101]
	v_mfma_f32_16x16x32_f16 v[94:97], v[162:165], v[138:141], v[94:97]
	v_mfma_f32_16x16x32_f16 v[90:93], v[166:169], v[138:141], v[90:93]
	v_mfma_f32_16x16x32_f16 v[86:89], v[170:173], v[138:141], v[86:89]
	v_mfma_f32_16x16x32_f16 v[82:85], v[174:177], v[138:141], v[82:85]
	v_mfma_f32_16x16x32_f16 v[78:81], v[162:165], v[142:145], v[78:81]
	v_mfma_f32_16x16x32_f16 v[74:77], v[166:169], v[142:145], v[74:77]
	v_mfma_f32_16x16x32_f16 v[70:73], v[170:173], v[142:145], v[70:73]
	v_mfma_f32_16x16x32_f16 v[66:69], v[174:177], v[142:145], v[66:69]
	s_barrier
	ds_read_b128 v[146:149], v205 offset:8192
	ds_read_b128 v[150:153], v205 offset:10240
	ds_read_b128 v[154:157], v205 offset:12288
	ds_read_b128 v[158:161], v205 offset:14336
	s_barrier
	s_waitcnt lgkmcnt(0)
	v_mfma_f32_16x16x32_f16 v[62:65], v[162:165], v[146:149], v[62:65]
	v_mfma_f32_16x16x32_f16 v[58:61], v[166:169], v[146:149], v[58:61]
	v_mfma_f32_16x16x32_f16 v[54:57], v[170:173], v[146:149], v[54:57]
	v_mfma_f32_16x16x32_f16 v[50:53], v[174:177], v[146:149], v[50:53]
	v_mfma_f32_16x16x32_f16 v[46:49], v[162:165], v[150:153], v[46:49]
	v_mfma_f32_16x16x32_f16 v[42:45], v[166:169], v[150:153], v[42:45]
	v_mfma_f32_16x16x32_f16 v[38:41], v[170:173], v[150:153], v[38:41]
	v_mfma_f32_16x16x32_f16 v[34:37], v[174:177], v[150:153], v[34:37]
	v_mfma_f32_16x16x32_f16 v[30:33], v[162:165], v[154:157], v[30:33]
	v_mfma_f32_16x16x32_f16 v[26:29], v[166:169], v[154:157], v[26:29]
	v_mfma_f32_16x16x32_f16 v[22:25], v[170:173], v[154:157], v[22:25]
	v_mfma_f32_16x16x32_f16 v[18:21], v[174:177], v[154:157], v[18:21]
	v_mfma_f32_16x16x32_f16 v[14:17], v[162:165], v[158:161], v[14:17]
	v_mfma_f32_16x16x32_f16 v[10:13], v[166:169], v[158:161], v[10:13]
	v_mfma_f32_16x16x32_f16 v[6:9], v[170:173], v[158:161], v[6:9]
	v_mfma_f32_16x16x32_f16 v[2:5], v[174:177], v[158:161], v[2:5]
	s_barrier
	s_cmp_eq_u32 s22, 1
	s_cbranch_scc1 .Lp3_skew1
	s_barrier

.Lp4_skew0:
	ds_read_b128 v[130:133], v188 offset:0
	ds_read_b128 v[134:137], v188 offset:2048
	ds_read_b128 v[138:141], v188 offset:4096
	ds_read_b128 v[142:145], v188 offset:6144
	ds_read_b128 v[162:165], v190 offset:32768
	ds_read_b128 v[166:169], v190 offset:34816
	ds_read_b128 v[170:173], v190 offset:36864
	ds_read_b128 v[174:177], v190 offset:38912
	s_add_u32 s22, s20, 0x80
	s_add_i32 m0, s19, 0x14000
	v_lshl_add_u64 v[196:197], v[224:225], 0, s[22:23]
	global_load_lds_dwordx4 v[196:197], off
	s_add_u32 s22, s20, 0x20080
	s_add_i32 m0, s19, 0x1a000
	v_lshl_add_u64 v[198:199], v[228:229], 0, s[22:23]
	global_load_lds_dwordx4 v[198:199], off
	s_barrier
	s_waitcnt lgkmcnt(0)
	v_mfma_f32_16x16x32_f16 v[126:129], v[162:165], v[130:133], 0
	v_mfma_f32_16x16x32_f16 v[122:125], v[166:169], v[130:133], 0
	v_mfma_f32_16x16x32_f16 v[118:121], v[170:173], v[130:133], 0
	v_mfma_f32_16x16x32_f16 v[114:117], v[174:177], v[130:133], 0
	v_mfma_f32_16x16x32_f16 v[110:113], v[162:165], v[134:137], 0
	v_mfma_f32_16x16x32_f16 v[106:109], v[166:169], v[134:137], 0
	v_mfma_f32_16x16x32_f16 v[102:105], v[170:173], v[134:137], 0
	v_mfma_f32_16x16x32_f16 v[98:101], v[174:177], v[134:137], 0
	v_mfma_f32_16x16x32_f16 v[94:97], v[162:165], v[138:141], 0
	v_mfma_f32_16x16x32_f16 v[90:93], v[166:169], v[138:141], 0
	v_mfma_f32_16x16x32_f16 v[86:89], v[170:173], v[138:141], 0
	v_mfma_f32_16x16x32_f16 v[82:85], v[174:177], v[138:141], 0
	v_mfma_f32_16x16x32_f16 v[78:81], v[162:165], v[142:145], 0
	v_mfma_f32_16x16x32_f16 v[74:77], v[166:169], v[142:145], 0
	v_mfma_f32_16x16x32_f16 v[70:73], v[170:173], v[142:145], 0
	v_mfma_f32_16x16x32_f16 v[66:69], v[174:177], v[142:145], 0
	s_barrier
	ds_read_b128 v[146:149], v188 offset:8192
	ds_read_b128 v[150:153], v188 offset:10240
	ds_read_b128 v[154:157], v188 offset:12288
	ds_read_b128 v[158:161], v188 offset:14336
	s_add_u32 s22, s20, 0x40080
	s_add_i32 m0, s19, 0x1c000
	v_lshl_add_u64 v[196:197], v[228:229], 0, s[22:23]
	global_load_lds_dwordx4 v[196:197], off
	s_add_u32 s22, s20, 0x60080
	s_add_i32 m0, s19, 0x1e000
	v_lshl_add_u64 v[198:199], v[228:229], 0, s[22:23]
	global_load_lds_dwordx4 v[198:199], off
	s_barrier
	s_waitcnt lgkmcnt(0)
	v_mfma_f32_16x16x32_f16 v[62:65], v[162:165], v[146:149], 0
	v_mfma_f32_16x16x32_f16 v[58:61], v[166:169], v[146:149], 0
	v_mfma_f32_16x16x32_f16 v[54:57], v[170:173], v[146:149], 0
	v_mfma_f32_16x16x32_f16 v[50:53], v[174:177], v[146:149], 0
	v_mfma_f32_16x16x32_f16 v[46:49], v[162:165], v[150:153], 0
	v_mfma_f32_16x16x32_f16 v[42:45], v[166:169], v[150:153], 0
	v_mfma_f32_16x16x32_f16 v[38:41], v[170:173], v[150:153], 0
	v_mfma_f32_16x16x32_f16 v[34:37], v[174:177], v[150:153], 0
	v_mfma_f32_16x16x32_f16 v[30:33], v[162:165], v[154:157], 0
	v_mfma_f32_16x16x32_f16 v[26:29], v[166:169], v[154:157], 0
	v_mfma_f32_16x16x32_f16 v[22:25], v[170:173], v[154:157], 0
	v_mfma_f32_16x16x32_f16 v[18:21], v[174:177], v[154:157], 0
	v_mfma_f32_16x16x32_f16 v[14:17], v[162:165], v[158:161], 0
	v_mfma_f32_16x16x32_f16 v[10:13], v[166:169], v[158:161], 0
	v_mfma_f32_16x16x32_f16 v[6:9], v[170:173], v[158:161], 0
	v_mfma_f32_16x16x32_f16 v[2:5], v[174:177], v[158:161], 0
	s_barrier
	ds_read_b128 v[130:133], v189 offset:0
	ds_read_b128 v[134:137], v189 offset:2048
	ds_read_b128 v[138:141], v189 offset:4096
	ds_read_b128 v[142:145], v189 offset:6144
	ds_read_b128 v[162:165], v191 offset:32768
	ds_read_b128 v[166:169], v191 offset:34816
	ds_read_b128 v[170:173], v191 offset:36864
	ds_read_b128 v[174:177], v191 offset:38912
	s_add_u32 s22, s20, 0x80
	s_add_i32 m0, s19, 0x12000
	v_lshl_add_u64 v[196:197], v[220:221], 0, s[22:23]
	global_load_lds_dwordx4 v[196:197], off
	s_add_u32 s22, s20, 0x80
	s_add_i32 m0, s19, 0x16000
	v_lshl_add_u64 v[198:199], v[226:227], 0, s[22:23]
	global_load_lds_dwordx4 v[198:199], off
	s_waitcnt lgkmcnt(0)
	s_barrier
	v_mfma_f32_16x16x32_f16 v[126:129], v[162:165], v[130:133], v[126:129]
	v_mfma_f32_16x16x32_f16 v[122:125], v[166:169], v[130:133], v[122:125]
	v_mfma_f32_16x16x32_f16 v[118:121], v[170:173], v[130:133], v[118:121]
	v_mfma_f32_16x16x32_f16 v[114:117], v[174:177], v[130:133], v[114:117]
	v_mfma_f32_16x16x32_f16 v[110:113], v[162:165], v[134:137], v[110:113]
	v_mfma_f32_16x16x32_f16 v[106:109], v[166:169], v[134:137], v[106:109]
	v_mfma_f32_16x16x32_f16 v[102:105], v[170:173], v[134:137], v[102:105]
	v_mfma_f32_16x16x32_f16 v[98:101], v[174:177], v[134:137], v[98:101]
	v_mfma_f32_16x16x32_f16 v[94:97], v[162:165], v[138:141], v[94:97]
	v_mfma_f32_16x16x32_f16 v[90:93], v[166:169], v[138:141], v[90:93]
	v_mfma_f32_16x16x32_f16 v[86:89], v[170:173], v[138:141], v[86:89]
	v_mfma_f32_16x16x32_f16 v[82:85], v[174:177], v[138:141], v[82:85]
	v_mfma_f32_16x16x32_f16 v[78:81], v[162:165], v[142:145], v[78:81]
	v_mfma_f32_16x16x32_f16 v[74:77], v[166:169], v[142:145], v[74:77]
	v_mfma_f32_16x16x32_f16 v[70:73], v[170:173], v[142:145], v[70:73]
	v_mfma_f32_16x16x32_f16 v[66:69], v[174:177], v[142:145], v[66:69]
	s_barrier
	ds_read_b128 v[146:149], v189 offset:8192
	ds_read_b128 v[150:153], v189 offset:10240
	ds_read_b128 v[154:157], v189 offset:12288
	ds_read_b128 v[158:161], v189 offset:14336
	s_add_u32 s22, s20, 0x100
	s_mov_b32 m0, s19
	v_lshl_add_u64 v[196:197], v[218:219], 0, s[22:23]
	global_load_lds_dwordx4 v[196:197], off
	s_add_u32 s22, s20, 0x100
	s_add_i32 m0, s19, 0x8000
	v_lshl_add_u64 v[198:199], v[228:229], 0, s[22:23]
	global_load_lds_dwordx4 v[198:199], off
	s_waitcnt vmcnt(4)
	s_barrier
	s_waitcnt lgkmcnt(0)
	v_mfma_f32_16x16x32_f16 v[62:65], v[162:165], v[146:149], v[62:65]
	v_mfma_f32_16x16x32_f16 v[58:61], v[166:169], v[146:149], v[58:61]
	v_mfma_f32_16x16x32_f16 v[54:57], v[170:173], v[146:149], v[54:57]
	v_mfma_f32_16x16x32_f16 v[50:53], v[174:177], v[146:149], v[50:53]
	v_mfma_f32_16x16x32_f16 v[46:49], v[162:165], v[150:153], v[46:49]
	v_mfma_f32_16x16x32_f16 v[42:45], v[166:169], v[150:153], v[42:45]
	v_mfma_f32_16x16x32_f16 v[38:41], v[170:173], v[150:153], v[38:41]
	v_mfma_f32_16x16x32_f16 v[34:37], v[174:177], v[150:153], v[34:37]
	v_mfma_f32_16x16x32_f16 v[30:33], v[162:165], v[154:157], v[30:33]
	v_mfma_f32_16x16x32_f16 v[26:29], v[166:169], v[154:157], v[26:29]
	v_mfma_f32_16x16x32_f16 v[22:25], v[170:173], v[154:157], v[22:25]
	v_mfma_f32_16x16x32_f16 v[18:21], v[174:177], v[154:157], v[18:21]
	v_mfma_f32_16x16x32_f16 v[14:17], v[162:165], v[158:161], v[14:17]
	v_mfma_f32_16x16x32_f16 v[10:13], v[166:169], v[158:161], v[10:13]
	v_mfma_f32_16x16x32_f16 v[6:9], v[170:173], v[158:161], v[6:9]
	v_mfma_f32_16x16x32_f16 v[2:5], v[174:177], v[158:161], v[2:5]
	s_barrier
	s_add_u32 s20, s20, 0x80
	ds_read_b128 v[130:133], v192 offset:0
	ds_read_b128 v[134:137], v192 offset:2048
	ds_read_b128 v[138:141], v192 offset:4096
	ds_read_b128 v[142:145], v192 offset:6144
	ds_read_b128 v[162:165], v194 offset:32768
	ds_read_b128 v[166:169], v194 offset:34816
	ds_read_b128 v[170:173], v194 offset:36864
	ds_read_b128 v[174:177], v194 offset:38912
	s_add_u32 s22, s20, 0x80
	s_add_i32 m0, s19, 0x4000
	v_lshl_add_u64 v[196:197], v[224:225], 0, s[22:23]
	global_load_lds_dwordx4 v[196:197], off
	s_add_u32 s22, s20, 0x20080
	s_add_i32 m0, s19, 0xa000
	v_lshl_add_u64 v[198:199], v[228:229], 0, s[22:23]
	global_load_lds_dwordx4 v[198:199], off
	s_waitcnt vmcnt(4)
	s_barrier
	s_waitcnt lgkmcnt(0)
	v_mfma_f32_16x16x32_f16 v[126:129], v[162:165], v[130:133], v[126:129]
	v_mfma_f32_16x16x32_f16 v[122:125], v[166:169], v[130:133], v[122:125]
	v_mfma_f32_16x16x32_f16 v[118:121], v[170:173], v[130:133], v[118:121]
	v_mfma_f32_16x16x32_f16 v[114:117], v[174:177], v[130:133], v[114:117]
	v_mfma_f32_16x16x32_f16 v[110:113], v[162:165], v[134:137], v[110:113]
	v_mfma_f32_16x16x32_f16 v[106:109], v[166:169], v[134:137], v[106:109]
	v_mfma_f32_16x16x32_f16 v[102:105], v[170:173], v[134:137], v[102:105]
	v_mfma_f32_16x16x32_f16 v[98:101], v[174:177], v[134:137], v[98:101]
	v_mfma_f32_16x16x32_f16 v[94:97], v[162:165], v[138:141], v[94:97]
	v_mfma_f32_16x16x32_f16 v[90:93], v[166:169], v[138:141], v[90:93]
	v_mfma_f32_16x16x32_f16 v[86:89], v[170:173], v[138:141], v[86:89]
	v_mfma_f32_16x16x32_f16 v[82:85], v[174:177], v[138:141], v[82:85]
	v_mfma_f32_16x16x32_f16 v[78:81], v[162:165], v[142:145], v[78:81]
	v_mfma_f32_16x16x32_f16 v[74:77], v[166:169], v[142:145], v[74:77]
	v_mfma_f32_16x16x32_f16 v[70:73], v[170:173], v[142:145], v[70:73]
	v_mfma_f32_16x16x32_f16 v[66:69], v[174:177], v[142:145], v[66:69]
	s_barrier
	ds_read_b128 v[146:149], v192 offset:8192
	ds_read_b128 v[150:153], v192 offset:10240
	ds_read_b128 v[154:157], v192 offset:12288
	ds_read_b128 v[158:161], v192 offset:14336
	s_add_u32 s22, s20, 0x40080
	s_add_i32 m0, s19, 0xc000
	v_lshl_add_u64 v[196:197], v[228:229], 0, s[22:23]
	global_load_lds_dwordx4 v[196:197], off
	s_add_u32 s22, s20, 0x60080
	s_add_i32 m0, s19, 0xe000
	v_lshl_add_u64 v[198:199], v[228:229], 0, s[22:23]
	global_load_lds_dwordx4 v[198:199], off
	s_barrier
	s_waitcnt lgkmcnt(0)
	v_mfma_f32_16x16x32_f16 v[62:65], v[162:165], v[146:149], v[62:65]
	v_mfma_f32_16x16x32_f16 v[58:61], v[166:169], v[146:149], v[58:61]
	v_mfma_f32_16x16x32_f16 v[54:57], v[170:173], v[146:149], v[54:57]
	v_mfma_f32_16x16x32_f16 v[50:53], v[174:177], v[146:149], v[50:53]
	v_mfma_f32_16x16x32_f16 v[46:49], v[162:165], v[150:153], v[46:49]
	v_mfma_f32_16x16x32_f16 v[42:45], v[166:169], v[150:153], v[42:45]
	v_mfma_f32_16x16x32_f16 v[38:41], v[170:173], v[150:153], v[38:41]
	v_mfma_f32_16x16x32_f16 v[34:37], v[174:177], v[150:153], v[34:37]
	v_mfma_f32_16x16x32_f16 v[30:33], v[162:165], v[154:157], v[30:33]
	v_mfma_f32_16x16x32_f16 v[26:29], v[166:169], v[154:157], v[26:29]
	v_mfma_f32_16x16x32_f16 v[22:25], v[170:173], v[154:157], v[22:25]
	v_mfma_f32_16x16x32_f16 v[18:21], v[174:177], v[154:157], v[18:21]
	v_mfma_f32_16x16x32_f16 v[14:17], v[162:165], v[158:161], v[14:17]
	v_mfma_f32_16x16x32_f16 v[10:13], v[166:169], v[158:161], v[10:13]
	v_mfma_f32_16x16x32_f16 v[6:9], v[170:173], v[158:161], v[6:9]
	v_mfma_f32_16x16x32_f16 v[2:5], v[174:177], v[158:161], v[2:5]
	s_barrier
	ds_read_b128 v[130:133], v193 offset:0
	ds_read_b128 v[134:137], v193 offset:2048
	ds_read_b128 v[138:141], v193 offset:4096
	ds_read_b128 v[142:145], v193 offset:6144
	ds_read_b128 v[162:165], v195 offset:32768
	ds_read_b128 v[166:169], v195 offset:34816
	ds_read_b128 v[170:173], v195 offset:36864
	ds_read_b128 v[174:177], v195 offset:38912
	s_add_u32 s22, s20, 0x80
	s_add_i32 m0, s19, 0x2000
	v_lshl_add_u64 v[196:197], v[220:221], 0, s[22:23]
	global_load_lds_dwordx4 v[196:197], off
	s_add_u32 s22, s20, 0x80
	s_add_i32 m0, s19, 0x6000
	v_lshl_add_u64 v[198:199], v[226:227], 0, s[22:23]
	global_load_lds_dwordx4 v[198:199], off
	s_waitcnt lgkmcnt(0)
	s_barrier
	v_mfma_f32_16x16x32_f16 v[126:129], v[162:165], v[130:133], v[126:129]
	v_mfma_f32_16x16x32_f16 v[122:125], v[166:169], v[130:133], v[122:125]
	v_mfma_f32_16x16x32_f16 v[118:121], v[170:173], v[130:133], v[118:121]
	v_mfma_f32_16x16x32_f16 v[114:117], v[174:177], v[130:133], v[114:117]
	v_mfma_f32_16x16x32_f16 v[110:113], v[162:165], v[134:137], v[110:113]
	v_mfma_f32_16x16x32_f16 v[106:109], v[166:169], v[134:137], v[106:109]
	v_mfma_f32_16x16x32_f16 v[102:105], v[170:173], v[134:137], v[102:105]
	v_mfma_f32_16x16x32_f16 v[98:101], v[174:177], v[134:137], v[98:101]
	v_mfma_f32_16x16x32_f16 v[94:97], v[162:165], v[138:141], v[94:97]
	v_mfma_f32_16x16x32_f16 v[90:93], v[166:169], v[138:141], v[90:93]
	v_mfma_f32_16x16x32_f16 v[86:89], v[170:173], v[138:141], v[86:89]
	v_mfma_f32_16x16x32_f16 v[82:85], v[174:177], v[138:141], v[82:85]
	v_mfma_f32_16x16x32_f16 v[78:81], v[162:165], v[142:145], v[78:81]
	v_mfma_f32_16x16x32_f16 v[74:77], v[166:169], v[142:145], v[74:77]
	v_mfma_f32_16x16x32_f16 v[70:73], v[170:173], v[142:145], v[70:73]
	v_mfma_f32_16x16x32_f16 v[66:69], v[174:177], v[142:145], v[66:69]
	s_barrier
	ds_read_b128 v[146:149], v193 offset:8192
	ds_read_b128 v[150:153], v193 offset:10240
	ds_read_b128 v[154:157], v193 offset:12288
	ds_read_b128 v[158:161], v193 offset:14336
	s_add_u32 s22, s20, 0x100
	s_add_i32 m0, s19, 0x10000
	v_lshl_add_u64 v[196:197], v[218:219], 0, s[22:23]
	global_load_lds_dwordx4 v[196:197], off
	s_add_u32 s22, s20, 0x100
	s_add_i32 m0, s19, 0x18000
	v_lshl_add_u64 v[198:199], v[228:229], 0, s[22:23]
	global_load_lds_dwordx4 v[198:199], off
	s_waitcnt vmcnt(4)
	s_barrier
	s_waitcnt lgkmcnt(0)
	v_mfma_f32_16x16x32_f16 v[62:65], v[162:165], v[146:149], v[62:65]
	v_mfma_f32_16x16x32_f16 v[58:61], v[166:169], v[146:149], v[58:61]
	v_mfma_f32_16x16x32_f16 v[54:57], v[170:173], v[146:149], v[54:57]
	v_mfma_f32_16x16x32_f16 v[50:53], v[174:177], v[146:149], v[50:53]
	v_mfma_f32_16x16x32_f16 v[46:49], v[162:165], v[150:153], v[46:49]
	v_mfma_f32_16x16x32_f16 v[42:45], v[166:169], v[150:153], v[42:45]
	v_mfma_f32_16x16x32_f16 v[38:41], v[170:173], v[150:153], v[38:41]
	v_mfma_f32_16x16x32_f16 v[34:37], v[174:177], v[150:153], v[34:37]
	v_mfma_f32_16x16x32_f16 v[30:33], v[162:165], v[154:157], v[30:33]
	v_mfma_f32_16x16x32_f16 v[26:29], v[166:169], v[154:157], v[26:29]
	v_mfma_f32_16x16x32_f16 v[22:25], v[170:173], v[154:157], v[22:25]
	v_mfma_f32_16x16x32_f16 v[18:21], v[174:177], v[154:157], v[18:21]
	v_mfma_f32_16x16x32_f16 v[14:17], v[162:165], v[158:161], v[14:17]
	v_mfma_f32_16x16x32_f16 v[10:13], v[166:169], v[158:161], v[10:13]
	v_mfma_f32_16x16x32_f16 v[6:9], v[170:173], v[158:161], v[6:9]
	v_mfma_f32_16x16x32_f16 v[2:5], v[174:177], v[158:161], v[2:5]
	s_barrier
	s_add_u32 s20, s20, 0x80
	s_movk_i32 s33, 6
.Lp4_loop:
	ds_read_b128 v[130:133], v188 offset:0
	ds_read_b128 v[134:137], v188 offset:2048
	ds_read_b128 v[138:141], v188 offset:4096
	ds_read_b128 v[142:145], v188 offset:6144
	ds_read_b128 v[162:165], v190 offset:32768
	ds_read_b128 v[166:169], v190 offset:34816
	ds_read_b128 v[170:173], v190 offset:36864
	ds_read_b128 v[174:177], v190 offset:38912
	s_add_u32 s22, s20, 0x80
	s_add_i32 m0, s19, 0x14000
	v_lshl_add_u64 v[196:197], v[224:225], 0, s[22:23]
	global_load_lds_dwordx4 v[196:197], off
	s_add_u32 s22, s20, 0x20080
	s_add_i32 m0, s19, 0x1a000
	v_lshl_add_u64 v[198:199], v[228:229], 0, s[22:23]
	global_load_lds_dwordx4 v[198:199], off
	s_waitcnt vmcnt(4)
	s_barrier
	s_waitcnt lgkmcnt(0)
	v_mfma_f32_16x16x32_f16 v[126:129], v[162:165], v[130:133], v[126:129]
	v_mfma_f32_16x16x32_f16 v[122:125], v[166:169], v[130:133], v[122:125]
	v_mfma_f32_16x16x32_f16 v[118:121], v[170:173], v[130:133], v[118:121]
	v_mfma_f32_16x16x32_f16 v[114:117], v[174:177], v[130:133], v[114:117]
	v_mfma_f32_16x16x32_f16 v[110:113], v[162:165], v[134:137], v[110:113]
	v_mfma_f32_16x16x32_f16 v[106:109], v[166:169], v[134:137], v[106:109]
	v_mfma_f32_16x16x32_f16 v[102:105], v[170:173], v[134:137], v[102:105]
	v_mfma_f32_16x16x32_f16 v[98:101], v[174:177], v[134:137], v[98:101]
	v_mfma_f32_16x16x32_f16 v[94:97], v[162:165], v[138:141], v[94:97]
	v_mfma_f32_16x16x32_f16 v[90:93], v[166:169], v[138:141], v[90:93]
	v_mfma_f32_16x16x32_f16 v[86:89], v[170:173], v[138:141], v[86:89]
	v_mfma_f32_16x16x32_f16 v[82:85], v[174:177], v[138:141], v[82:85]
	v_mfma_f32_16x16x32_f16 v[78:81], v[162:165], v[142:145], v[78:81]
	v_mfma_f32_16x16x32_f16 v[74:77], v[166:169], v[142:145], v[74:77]
	v_mfma_f32_16x16x32_f16 v[70:73], v[170:173], v[142:145], v[70:73]
	v_mfma_f32_16x16x32_f16 v[66:69], v[174:177], v[142:145], v[66:69]
	s_barrier
	ds_read_b128 v[146:149], v188 offset:8192
	ds_read_b128 v[150:153], v188 offset:10240
	ds_read_b128 v[154:157], v188 offset:12288
	ds_read_b128 v[158:161], v188 offset:14336
	s_add_u32 s22, s20, 0x40080
	s_add_i32 m0, s19, 0x1c000
	v_lshl_add_u64 v[196:197], v[228:229], 0, s[22:23]
	global_load_lds_dwordx4 v[196:197], off
	s_add_u32 s22, s20, 0x60080
	s_add_i32 m0, s19, 0x1e000
	v_lshl_add_u64 v[198:199], v[228:229], 0, s[22:23]
	global_load_lds_dwordx4 v[198:199], off
	s_barrier
	s_waitcnt lgkmcnt(0)
	v_mfma_f32_16x16x32_f16 v[62:65], v[162:165], v[146:149], v[62:65]
	v_mfma_f32_16x16x32_f16 v[58:61], v[166:169], v[146:149], v[58:61]
	v_mfma_f32_16x16x32_f16 v[54:57], v[170:173], v[146:149], v[54:57]
	v_mfma_f32_16x16x32_f16 v[50:53], v[174:177], v[146:149], v[50:53]
	v_mfma_f32_16x16x32_f16 v[46:49], v[162:165], v[150:153], v[46:49]
	v_mfma_f32_16x16x32_f16 v[42:45], v[166:169], v[150:153], v[42:45]
	v_mfma_f32_16x16x32_f16 v[38:41], v[170:173], v[150:153], v[38:41]
	v_mfma_f32_16x16x32_f16 v[34:37], v[174:177], v[150:153], v[34:37]
	v_mfma_f32_16x16x32_f16 v[30:33], v[162:165], v[154:157], v[30:33]
	v_mfma_f32_16x16x32_f16 v[26:29], v[166:169], v[154:157], v[26:29]
	v_mfma_f32_16x16x32_f16 v[22:25], v[170:173], v[154:157], v[22:25]
	v_mfma_f32_16x16x32_f16 v[18:21], v[174:177], v[154:157], v[18:21]
	v_mfma_f32_16x16x32_f16 v[14:17], v[162:165], v[158:161], v[14:17]
	v_mfma_f32_16x16x32_f16 v[10:13], v[166:169], v[158:161], v[10:13]
	v_mfma_f32_16x16x32_f16 v[6:9], v[170:173], v[158:161], v[6:9]
	v_mfma_f32_16x16x32_f16 v[2:5], v[174:177], v[158:161], v[2:5]
	s_barrier
	ds_read_b128 v[130:133], v189 offset:0
	ds_read_b128 v[134:137], v189 offset:2048
	ds_read_b128 v[138:141], v189 offset:4096
	ds_read_b128 v[142:145], v189 offset:6144
	ds_read_b128 v[162:165], v191 offset:32768
	ds_read_b128 v[166:169], v191 offset:34816
	ds_read_b128 v[170:173], v191 offset:36864
	ds_read_b128 v[174:177], v191 offset:38912
	s_add_u32 s22, s20, 0x80
	s_add_i32 m0, s19, 0x12000
	v_lshl_add_u64 v[196:197], v[220:221], 0, s[22:23]
	global_load_lds_dwordx4 v[196:197], off
	s_add_u32 s22, s20, 0x80
	s_add_i32 m0, s19, 0x16000
	v_lshl_add_u64 v[198:199], v[226:227], 0, s[22:23]
	global_load_lds_dwordx4 v[198:199], off
	s_waitcnt lgkmcnt(0)
	s_barrier
	v_mfma_f32_16x16x32_f16 v[126:129], v[162:165], v[130:133], v[126:129]
	v_mfma_f32_16x16x32_f16 v[122:125], v[166:169], v[130:133], v[122:125]
	v_mfma_f32_16x16x32_f16 v[118:121], v[170:173], v[130:133], v[118:121]
	v_mfma_f32_16x16x32_f16 v[114:117], v[174:177], v[130:133], v[114:117]
	v_mfma_f32_16x16x32_f16 v[110:113], v[162:165], v[134:137], v[110:113]
	v_mfma_f32_16x16x32_f16 v[106:109], v[166:169], v[134:137], v[106:109]
	v_mfma_f32_16x16x32_f16 v[102:105], v[170:173], v[134:137], v[102:105]
	v_mfma_f32_16x16x32_f16 v[98:101], v[174:177], v[134:137], v[98:101]
	v_mfma_f32_16x16x32_f16 v[94:97], v[162:165], v[138:141], v[94:97]
	v_mfma_f32_16x16x32_f16 v[90:93], v[166:169], v[138:141], v[90:93]
	v_mfma_f32_16x16x32_f16 v[86:89], v[170:173], v[138:141], v[86:89]
	v_mfma_f32_16x16x32_f16 v[82:85], v[174:177], v[138:141], v[82:85]
	v_mfma_f32_16x16x32_f16 v[78:81], v[162:165], v[142:145], v[78:81]
	v_mfma_f32_16x16x32_f16 v[74:77], v[166:169], v[142:145], v[74:77]
	v_mfma_f32_16x16x32_f16 v[70:73], v[170:173], v[142:145], v[70:73]
	v_mfma_f32_16x16x32_f16 v[66:69], v[174:177], v[142:145], v[66:69]
	s_barrier
	ds_read_b128 v[146:149], v189 offset:8192
	ds_read_b128 v[150:153], v189 offset:10240
	ds_read_b128 v[154:157], v189 offset:12288
	ds_read_b128 v[158:161], v189 offset:14336
	s_add_u32 s22, s20, 0x100
	s_mov_b32 m0, s19
	v_lshl_add_u64 v[196:197], v[218:219], 0, s[22:23]
	global_load_lds_dwordx4 v[196:197], off
	s_add_u32 s22, s20, 0x100
	s_add_i32 m0, s19, 0x8000
	v_lshl_add_u64 v[198:199], v[228:229], 0, s[22:23]
	global_load_lds_dwordx4 v[198:199], off
	s_waitcnt vmcnt(4)
	s_barrier
	s_waitcnt lgkmcnt(0)
	v_mfma_f32_16x16x32_f16 v[62:65], v[162:165], v[146:149], v[62:65]
	v_mfma_f32_16x16x32_f16 v[58:61], v[166:169], v[146:149], v[58:61]
	v_mfma_f32_16x16x32_f16 v[54:57], v[170:173], v[146:149], v[54:57]
	v_mfma_f32_16x16x32_f16 v[50:53], v[174:177], v[146:149], v[50:53]
	v_mfma_f32_16x16x32_f16 v[46:49], v[162:165], v[150:153], v[46:49]
	v_mfma_f32_16x16x32_f16 v[42:45], v[166:169], v[150:153], v[42:45]
	v_mfma_f32_16x16x32_f16 v[38:41], v[170:173], v[150:153], v[38:41]
	v_mfma_f32_16x16x32_f16 v[34:37], v[174:177], v[150:153], v[34:37]
	v_mfma_f32_16x16x32_f16 v[30:33], v[162:165], v[154:157], v[30:33]
	v_mfma_f32_16x16x32_f16 v[26:29], v[166:169], v[154:157], v[26:29]
	v_mfma_f32_16x16x32_f16 v[22:25], v[170:173], v[154:157], v[22:25]
	v_mfma_f32_16x16x32_f16 v[18:21], v[174:177], v[154:157], v[18:21]
	v_mfma_f32_16x16x32_f16 v[14:17], v[162:165], v[158:161], v[14:17]
	v_mfma_f32_16x16x32_f16 v[10:13], v[166:169], v[158:161], v[10:13]
	v_mfma_f32_16x16x32_f16 v[6:9], v[170:173], v[158:161], v[6:9]
	v_mfma_f32_16x16x32_f16 v[2:5], v[174:177], v[158:161], v[2:5]
	s_barrier
	s_add_u32 s20, s20, 0x80
	ds_read_b128 v[130:133], v192 offset:0
	ds_read_b128 v[134:137], v192 offset:2048
	ds_read_b128 v[138:141], v192 offset:4096
	ds_read_b128 v[142:145], v192 offset:6144
	ds_read_b128 v[162:165], v194 offset:32768
	ds_read_b128 v[166:169], v194 offset:34816
	ds_read_b128 v[170:173], v194 offset:36864
	ds_read_b128 v[174:177], v194 offset:38912
	s_add_u32 s22, s20, 0x80
	s_add_i32 m0, s19, 0x4000
	v_lshl_add_u64 v[196:197], v[224:225], 0, s[22:23]
	global_load_lds_dwordx4 v[196:197], off
	s_add_u32 s22, s20, 0x20080
	s_add_i32 m0, s19, 0xa000
	v_lshl_add_u64 v[198:199], v[228:229], 0, s[22:23]
	global_load_lds_dwordx4 v[198:199], off
	s_waitcnt vmcnt(4)
	s_barrier
	s_waitcnt lgkmcnt(0)
	v_mfma_f32_16x16x32_f16 v[126:129], v[162:165], v[130:133], v[126:129]
	v_mfma_f32_16x16x32_f16 v[122:125], v[166:169], v[130:133], v[122:125]
	v_mfma_f32_16x16x32_f16 v[118:121], v[170:173], v[130:133], v[118:121]
	v_mfma_f32_16x16x32_f16 v[114:117], v[174:177], v[130:133], v[114:117]
	v_mfma_f32_16x16x32_f16 v[110:113], v[162:165], v[134:137], v[110:113]
	v_mfma_f32_16x16x32_f16 v[106:109], v[166:169], v[134:137], v[106:109]
	v_mfma_f32_16x16x32_f16 v[102:105], v[170:173], v[134:137], v[102:105]
	v_mfma_f32_16x16x32_f16 v[98:101], v[174:177], v[134:137], v[98:101]
	v_mfma_f32_16x16x32_f16 v[94:97], v[162:165], v[138:141], v[94:97]
	v_mfma_f32_16x16x32_f16 v[90:93], v[166:169], v[138:141], v[90:93]
	v_mfma_f32_16x16x32_f16 v[86:89], v[170:173], v[138:141], v[86:89]
	v_mfma_f32_16x16x32_f16 v[82:85], v[174:177], v[138:141], v[82:85]
	v_mfma_f32_16x16x32_f16 v[78:81], v[162:165], v[142:145], v[78:81]
	v_mfma_f32_16x16x32_f16 v[74:77], v[166:169], v[142:145], v[74:77]
	v_mfma_f32_16x16x32_f16 v[70:73], v[170:173], v[142:145], v[70:73]
	v_mfma_f32_16x16x32_f16 v[66:69], v[174:177], v[142:145], v[66:69]
	s_barrier
	ds_read_b128 v[146:149], v192 offset:8192
	ds_read_b128 v[150:153], v192 offset:10240
	ds_read_b128 v[154:157], v192 offset:12288
	ds_read_b128 v[158:161], v192 offset:14336
	s_add_u32 s22, s20, 0x40080
	s_add_i32 m0, s19, 0xc000
	v_lshl_add_u64 v[196:197], v[228:229], 0, s[22:23]
	global_load_lds_dwordx4 v[196:197], off
	s_add_u32 s22, s20, 0x60080
	s_add_i32 m0, s19, 0xe000
	v_lshl_add_u64 v[198:199], v[228:229], 0, s[22:23]
	global_load_lds_dwordx4 v[198:199], off
	s_barrier
	s_waitcnt lgkmcnt(0)
	v_mfma_f32_16x16x32_f16 v[62:65], v[162:165], v[146:149], v[62:65]
	v_mfma_f32_16x16x32_f16 v[58:61], v[166:169], v[146:149], v[58:61]
	v_mfma_f32_16x16x32_f16 v[54:57], v[170:173], v[146:149], v[54:57]
	v_mfma_f32_16x16x32_f16 v[50:53], v[174:177], v[146:149], v[50:53]
	v_mfma_f32_16x16x32_f16 v[46:49], v[162:165], v[150:153], v[46:49]
	v_mfma_f32_16x16x32_f16 v[42:45], v[166:169], v[150:153], v[42:45]
	v_mfma_f32_16x16x32_f16 v[38:41], v[170:173], v[150:153], v[38:41]
	v_mfma_f32_16x16x32_f16 v[34:37], v[174:177], v[150:153], v[34:37]
	v_mfma_f32_16x16x32_f16 v[30:33], v[162:165], v[154:157], v[30:33]
	v_mfma_f32_16x16x32_f16 v[26:29], v[166:169], v[154:157], v[26:29]
	v_mfma_f32_16x16x32_f16 v[22:25], v[170:173], v[154:157], v[22:25]
	v_mfma_f32_16x16x32_f16 v[18:21], v[174:177], v[154:157], v[18:21]
	v_mfma_f32_16x16x32_f16 v[14:17], v[162:165], v[158:161], v[14:17]
	v_mfma_f32_16x16x32_f16 v[10:13], v[166:169], v[158:161], v[10:13]
	v_mfma_f32_16x16x32_f16 v[6:9], v[170:173], v[158:161], v[6:9]
	v_mfma_f32_16x16x32_f16 v[2:5], v[174:177], v[158:161], v[2:5]
	s_barrier
	ds_read_b128 v[130:133], v193 offset:0
	ds_read_b128 v[134:137], v193 offset:2048
	ds_read_b128 v[138:141], v193 offset:4096
	ds_read_b128 v[142:145], v193 offset:6144
	ds_read_b128 v[162:165], v195 offset:32768
	ds_read_b128 v[166:169], v195 offset:34816
	ds_read_b128 v[170:173], v195 offset:36864
	ds_read_b128 v[174:177], v195 offset:38912
	s_add_u32 s22, s20, 0x80
	s_add_i32 m0, s19, 0x2000
	v_lshl_add_u64 v[196:197], v[220:221], 0, s[22:23]
	global_load_lds_dwordx4 v[196:197], off
	s_add_u32 s22, s20, 0x80
	s_add_i32 m0, s19, 0x6000
	v_lshl_add_u64 v[198:199], v[226:227], 0, s[22:23]
	global_load_lds_dwordx4 v[198:199], off
	s_waitcnt lgkmcnt(0)
	s_barrier
	v_mfma_f32_16x16x32_f16 v[126:129], v[162:165], v[130:133], v[126:129]
	v_mfma_f32_16x16x32_f16 v[122:125], v[166:169], v[130:133], v[122:125]
	v_mfma_f32_16x16x32_f16 v[118:121], v[170:173], v[130:133], v[118:121]
	v_mfma_f32_16x16x32_f16 v[114:117], v[174:177], v[130:133], v[114:117]
	v_mfma_f32_16x16x32_f16 v[110:113], v[162:165], v[134:137], v[110:113]
	v_mfma_f32_16x16x32_f16 v[106:109], v[166:169], v[134:137], v[106:109]
	v_mfma_f32_16x16x32_f16 v[102:105], v[170:173], v[134:137], v[102:105]
	v_mfma_f32_16x16x32_f16 v[98:101], v[174:177], v[134:137], v[98:101]
	v_mfma_f32_16x16x32_f16 v[94:97], v[162:165], v[138:141], v[94:97]
	v_mfma_f32_16x16x32_f16 v[90:93], v[166:169], v[138:141], v[90:93]
	v_mfma_f32_16x16x32_f16 v[86:89], v[170:173], v[138:141], v[86:89]
	v_mfma_f32_16x16x32_f16 v[82:85], v[174:177], v[138:141], v[82:85]
	v_mfma_f32_16x16x32_f16 v[78:81], v[162:165], v[142:145], v[78:81]
	v_mfma_f32_16x16x32_f16 v[74:77], v[166:169], v[142:145], v[74:77]
	v_mfma_f32_16x16x32_f16 v[70:73], v[170:173], v[142:145], v[70:73]
	v_mfma_f32_16x16x32_f16 v[66:69], v[174:177], v[142:145], v[66:69]
	s_barrier
	ds_read_b128 v[146:149], v193 offset:8192
	ds_read_b128 v[150:153], v193 offset:10240
	ds_read_b128 v[154:157], v193 offset:12288
	ds_read_b128 v[158:161], v193 offset:14336
	s_add_u32 s22, s20, 0x100
	s_add_i32 m0, s19, 0x10000
	v_lshl_add_u64 v[196:197], v[218:219], 0, s[22:23]
	global_load_lds_dwordx4 v[196:197], off
	s_add_u32 s22, s20, 0x100
	s_add_i32 m0, s19, 0x18000
	v_lshl_add_u64 v[198:199], v[228:229], 0, s[22:23]
	global_load_lds_dwordx4 v[198:199], off
	s_waitcnt vmcnt(4)
	s_barrier
	s_waitcnt lgkmcnt(0)
	v_mfma_f32_16x16x32_f16 v[62:65], v[162:165], v[146:149], v[62:65]
	v_mfma_f32_16x16x32_f16 v[58:61], v[166:169], v[146:149], v[58:61]
	v_mfma_f32_16x16x32_f16 v[54:57], v[170:173], v[146:149], v[54:57]
	v_mfma_f32_16x16x32_f16 v[50:53], v[174:177], v[146:149], v[50:53]
	v_mfma_f32_16x16x32_f16 v[46:49], v[162:165], v[150:153], v[46:49]
	v_mfma_f32_16x16x32_f16 v[42:45], v[166:169], v[150:153], v[42:45]
	v_mfma_f32_16x16x32_f16 v[38:41], v[170:173], v[150:153], v[38:41]
	v_mfma_f32_16x16x32_f16 v[34:37], v[174:177], v[150:153], v[34:37]
	v_mfma_f32_16x16x32_f16 v[30:33], v[162:165], v[154:157], v[30:33]
	v_mfma_f32_16x16x32_f16 v[26:29], v[166:169], v[154:157], v[26:29]
	v_mfma_f32_16x16x32_f16 v[22:25], v[170:173], v[154:157], v[22:25]
	v_mfma_f32_16x16x32_f16 v[18:21], v[174:177], v[154:157], v[18:21]
	v_mfma_f32_16x16x32_f16 v[14:17], v[162:165], v[158:161], v[14:17]
	v_mfma_f32_16x16x32_f16 v[10:13], v[166:169], v[158:161], v[10:13]
	v_mfma_f32_16x16x32_f16 v[6:9], v[170:173], v[158:161], v[6:9]
	v_mfma_f32_16x16x32_f16 v[2:5], v[174:177], v[158:161], v[2:5]
	s_barrier
	s_add_u32 s20, s20, 0x80
	s_add_i32 s33, s33, -1
	s_cmp_lg_u32 s33, 0
	s_cbranch_scc1 .Lp4_loop
	ds_read_b128 v[130:133], v188 offset:0
	ds_read_b128 v[134:137], v188 offset:2048
	ds_read_b128 v[138:141], v188 offset:4096
	ds_read_b128 v[142:145], v188 offset:6144
	ds_read_b128 v[162:165], v190 offset:32768
	ds_read_b128 v[166:169], v190 offset:34816
	ds_read_b128 v[170:173], v190 offset:36864
	ds_read_b128 v[174:177], v190 offset:38912
	s_add_u32 s22, s20, 0x80
	s_add_i32 m0, s19, 0x14000
	v_lshl_add_u64 v[196:197], v[224:225], 0, s[22:23]
	global_load_lds_dwordx4 v[196:197], off
	s_add_u32 s22, s20, 0x20080
	s_add_i32 m0, s19, 0x1a000
	v_lshl_add_u64 v[198:199], v[228:229], 0, s[22:23]
	global_load_lds_dwordx4 v[198:199], off
	s_waitcnt vmcnt(4)
	s_barrier
	s_waitcnt lgkmcnt(0)
	v_mfma_f32_16x16x32_f16 v[126:129], v[162:165], v[130:133], v[126:129]
	v_mfma_f32_16x16x32_f16 v[122:125], v[166:169], v[130:133], v[122:125]
	v_mfma_f32_16x16x32_f16 v[118:121], v[170:173], v[130:133], v[118:121]
	v_mfma_f32_16x16x32_f16 v[114:117], v[174:177], v[130:133], v[114:117]
	v_mfma_f32_16x16x32_f16 v[110:113], v[162:165], v[134:137], v[110:113]
	v_mfma_f32_16x16x32_f16 v[106:109], v[166:169], v[134:137], v[106:109]
	v_mfma_f32_16x16x32_f16 v[102:105], v[170:173], v[134:137], v[102:105]
	v_mfma_f32_16x16x32_f16 v[98:101], v[174:177], v[134:137], v[98:101]
	v_mfma_f32_16x16x32_f16 v[94:97], v[162:165], v[138:141], v[94:97]
	v_mfma_f32_16x16x32_f16 v[90:93], v[166:169], v[138:141], v[90:93]
	v_mfma_f32_16x16x32_f16 v[86:89], v[170:173], v[138:141], v[86:89]
	v_mfma_f32_16x16x32_f16 v[82:85], v[174:177], v[138:141], v[82:85]
	v_mfma_f32_16x16x32_f16 v[78:81], v[162:165], v[142:145], v[78:81]
	v_mfma_f32_16x16x32_f16 v[74:77], v[166:169], v[142:145], v[74:77]
	v_mfma_f32_16x16x32_f16 v[70:73], v[170:173], v[142:145], v[70:73]
	v_mfma_f32_16x16x32_f16 v[66:69], v[174:177], v[142:145], v[66:69]
	s_barrier
	ds_read_b128 v[146:149], v188 offset:8192
	ds_read_b128 v[150:153], v188 offset:10240
	ds_read_b128 v[154:157], v188 offset:12288
	ds_read_b128 v[158:161], v188 offset:14336
	s_add_u32 s22, s20, 0x40080
	s_add_i32 m0, s19, 0x1c000
	v_lshl_add_u64 v[196:197], v[228:229], 0, s[22:23]
	global_load_lds_dwordx4 v[196:197], off
	s_add_u32 s22, s20, 0x60080
	s_add_i32 m0, s19, 0x1e000
	v_lshl_add_u64 v[198:199], v[228:229], 0, s[22:23]
	global_load_lds_dwordx4 v[198:199], off
	s_barrier
	s_waitcnt lgkmcnt(0)
	v_mfma_f32_16x16x32_f16 v[62:65], v[162:165], v[146:149], v[62:65]
	v_mfma_f32_16x16x32_f16 v[58:61], v[166:169], v[146:149], v[58:61]
	v_mfma_f32_16x16x32_f16 v[54:57], v[170:173], v[146:149], v[54:57]
	v_mfma_f32_16x16x32_f16 v[50:53], v[174:177], v[146:149], v[50:53]
	v_mfma_f32_16x16x32_f16 v[46:49], v[162:165], v[150:153], v[46:49]
	v_mfma_f32_16x16x32_f16 v[42:45], v[166:169], v[150:153], v[42:45]
	v_mfma_f32_16x16x32_f16 v[38:41], v[170:173], v[150:153], v[38:41]
	v_mfma_f32_16x16x32_f16 v[34:37], v[174:177], v[150:153], v[34:37]
	v_mfma_f32_16x16x32_f16 v[30:33], v[162:165], v[154:157], v[30:33]
	v_mfma_f32_16x16x32_f16 v[26:29], v[166:169], v[154:157], v[26:29]
	v_mfma_f32_16x16x32_f16 v[22:25], v[170:173], v[154:157], v[22:25]
	v_mfma_f32_16x16x32_f16 v[18:21], v[174:177], v[154:157], v[18:21]
	v_mfma_f32_16x16x32_f16 v[14:17], v[162:165], v[158:161], v[14:17]
	v_mfma_f32_16x16x32_f16 v[10:13], v[166:169], v[158:161], v[10:13]
	v_mfma_f32_16x16x32_f16 v[6:9], v[170:173], v[158:161], v[6:9]
	v_mfma_f32_16x16x32_f16 v[2:5], v[174:177], v[158:161], v[2:5]
	s_barrier
	ds_read_b128 v[130:133], v189 offset:0
	ds_read_b128 v[134:137], v189 offset:2048
	ds_read_b128 v[138:141], v189 offset:4096
	ds_read_b128 v[142:145], v189 offset:6144
	ds_read_b128 v[162:165], v191 offset:32768
	ds_read_b128 v[166:169], v191 offset:34816
	ds_read_b128 v[170:173], v191 offset:36864
	ds_read_b128 v[174:177], v191 offset:38912
	s_add_u32 s22, s20, 0x80
	s_add_i32 m0, s19, 0x12000
	v_lshl_add_u64 v[196:197], v[220:221], 0, s[22:23]
	global_load_lds_dwordx4 v[196:197], off
	s_add_u32 s22, s20, 0x80
	s_add_i32 m0, s19, 0x16000
	v_lshl_add_u64 v[198:199], v[226:227], 0, s[22:23]
	global_load_lds_dwordx4 v[198:199], off
	s_waitcnt lgkmcnt(0)
	s_barrier
	v_mfma_f32_16x16x32_f16 v[126:129], v[162:165], v[130:133], v[126:129]
	v_mfma_f32_16x16x32_f16 v[122:125], v[166:169], v[130:133], v[122:125]
	v_mfma_f32_16x16x32_f16 v[118:121], v[170:173], v[130:133], v[118:121]
	v_mfma_f32_16x16x32_f16 v[114:117], v[174:177], v[130:133], v[114:117]
	v_mfma_f32_16x16x32_f16 v[110:113], v[162:165], v[134:137], v[110:113]
	v_mfma_f32_16x16x32_f16 v[106:109], v[166:169], v[134:137], v[106:109]
	v_mfma_f32_16x16x32_f16 v[102:105], v[170:173], v[134:137], v[102:105]
	v_mfma_f32_16x16x32_f16 v[98:101], v[174:177], v[134:137], v[98:101]
	v_mfma_f32_16x16x32_f16 v[94:97], v[162:165], v[138:141], v[94:97]
	v_mfma_f32_16x16x32_f16 v[90:93], v[166:169], v[138:141], v[90:93]
	v_mfma_f32_16x16x32_f16 v[86:89], v[170:173], v[138:141], v[86:89]
	v_mfma_f32_16x16x32_f16 v[82:85], v[174:177], v[138:141], v[82:85]
	v_mfma_f32_16x16x32_f16 v[78:81], v[162:165], v[142:145], v[78:81]
	v_mfma_f32_16x16x32_f16 v[74:77], v[166:169], v[142:145], v[74:77]
	v_mfma_f32_16x16x32_f16 v[70:73], v[170:173], v[142:145], v[70:73]
	v_mfma_f32_16x16x32_f16 v[66:69], v[174:177], v[142:145], v[66:69]
	s_barrier
	ds_read_b128 v[146:149], v189 offset:8192
	ds_read_b128 v[150:153], v189 offset:10240
	ds_read_b128 v[154:157], v189 offset:12288
	ds_read_b128 v[158:161], v189 offset:14336
	s_waitcnt vmcnt(2)
	s_barrier
	s_waitcnt lgkmcnt(0)
	v_mfma_f32_16x16x32_f16 v[62:65], v[162:165], v[146:149], v[62:65]
	v_mfma_f32_16x16x32_f16 v[58:61], v[166:169], v[146:149], v[58:61]
	v_mfma_f32_16x16x32_f16 v[54:57], v[170:173], v[146:149], v[54:57]
	v_mfma_f32_16x16x32_f16 v[50:53], v[174:177], v[146:149], v[50:53]
	v_mfma_f32_16x16x32_f16 v[46:49], v[162:165], v[150:153], v[46:49]
	v_mfma_f32_16x16x32_f16 v[42:45], v[166:169], v[150:153], v[42:45]
	v_mfma_f32_16x16x32_f16 v[38:41], v[170:173], v[150:153], v[38:41]
	v_mfma_f32_16x16x32_f16 v[34:37], v[174:177], v[150:153], v[34:37]
	v_mfma_f32_16x16x32_f16 v[30:33], v[162:165], v[154:157], v[30:33]
	v_mfma_f32_16x16x32_f16 v[26:29], v[166:169], v[154:157], v[26:29]
	v_mfma_f32_16x16x32_f16 v[22:25], v[170:173], v[154:157], v[22:25]
	v_mfma_f32_16x16x32_f16 v[18:21], v[174:177], v[154:157], v[18:21]
	v_mfma_f32_16x16x32_f16 v[14:17], v[162:165], v[158:161], v[14:17]
	v_mfma_f32_16x16x32_f16 v[10:13], v[166:169], v[158:161], v[10:13]
	v_mfma_f32_16x16x32_f16 v[6:9], v[170:173], v[158:161], v[6:9]
	v_mfma_f32_16x16x32_f16 v[2:5], v[174:177], v[158:161], v[2:5]
	s_barrier
	s_add_u32 s20, s20, 0x80
	ds_read_b128 v[130:133], v192 offset:0
	ds_read_b128 v[134:137], v192 offset:2048
	ds_read_b128 v[138:141], v192 offset:4096
	ds_read_b128 v[142:145], v192 offset:6144
	ds_read_b128 v[162:165], v194 offset:32768
	ds_read_b128 v[166:169], v194 offset:34816
	ds_read_b128 v[170:173], v194 offset:36864
	ds_read_b128 v[174:177], v194 offset:38912
	s_waitcnt vmcnt(0)
	s_barrier
	s_waitcnt lgkmcnt(0)
	v_mfma_f32_16x16x32_f16 v[126:129], v[162:165], v[130:133], v[126:129]
	v_mfma_f32_16x16x32_f16 v[122:125], v[166:169], v[130:133], v[122:125]
	v_mfma_f32_16x16x32_f16 v[118:121], v[170:173], v[130:133], v[118:121]
	v_mfma_f32_16x16x32_f16 v[114:117], v[174:177], v[130:133], v[114:117]
	v_mfma_f32_16x16x32_f16 v[110:113], v[162:165], v[134:137], v[110:113]
	v_mfma_f32_16x16x32_f16 v[106:109], v[166:169], v[134:137], v[106:109]
	v_mfma_f32_16x16x32_f16 v[102:105], v[170:173], v[134:137], v[102:105]
	v_mfma_f32_16x16x32_f16 v[98:101], v[174:177], v[134:137], v[98:101]
	v_mfma_f32_16x16x32_f16 v[94:97], v[162:165], v[138:141], v[94:97]
	v_mfma_f32_16x16x32_f16 v[90:93], v[166:169], v[138:141], v[90:93]
	v_mfma_f32_16x16x32_f16 v[86:89], v[170:173], v[138:141], v[86:89]
	v_mfma_f32_16x16x32_f16 v[82:85], v[174:177], v[138:141], v[82:85]
	v_mfma_f32_16x16x32_f16 v[78:81], v[162:165], v[142:145], v[78:81]
	v_mfma_f32_16x16x32_f16 v[74:77], v[166:169], v[142:145], v[74:77]
	v_mfma_f32_16x16x32_f16 v[70:73], v[170:173], v[142:145], v[70:73]
	v_mfma_f32_16x16x32_f16 v[66:69], v[174:177], v[142:145], v[66:69]
	s_barrier
	ds_read_b128 v[146:149], v192 offset:8192
	ds_read_b128 v[150:153], v192 offset:10240
	ds_read_b128 v[154:157], v192 offset:12288
	ds_read_b128 v[158:161], v192 offset:14336
	s_barrier
	s_waitcnt lgkmcnt(0)
	v_mfma_f32_16x16x32_f16 v[62:65], v[162:165], v[146:149], v[62:65]
	v_mfma_f32_16x16x32_f16 v[58:61], v[166:169], v[146:149], v[58:61]
	v_mfma_f32_16x16x32_f16 v[54:57], v[170:173], v[146:149], v[54:57]
	v_mfma_f32_16x16x32_f16 v[50:53], v[174:177], v[146:149], v[50:53]
	v_mfma_f32_16x16x32_f16 v[46:49], v[162:165], v[150:153], v[46:49]
	v_mfma_f32_16x16x32_f16 v[42:45], v[166:169], v[150:153], v[42:45]
	v_mfma_f32_16x16x32_f16 v[38:41], v[170:173], v[150:153], v[38:41]
	v_mfma_f32_16x16x32_f16 v[34:37], v[174:177], v[150:153], v[34:37]
	v_mfma_f32_16x16x32_f16 v[30:33], v[162:165], v[154:157], v[30:33]
	v_mfma_f32_16x16x32_f16 v[26:29], v[166:169], v[154:157], v[26:29]
	v_mfma_f32_16x16x32_f16 v[22:25], v[170:173], v[154:157], v[22:25]
	v_mfma_f32_16x16x32_f16 v[18:21], v[174:177], v[154:157], v[18:21]
	v_mfma_f32_16x16x32_f16 v[14:17], v[162:165], v[158:161], v[14:17]
	v_mfma_f32_16x16x32_f16 v[10:13], v[166:169], v[158:161], v[10:13]
	v_mfma_f32_16x16x32_f16 v[6:9], v[170:173], v[158:161], v[6:9]
	v_mfma_f32_16x16x32_f16 v[2:5], v[174:177], v[158:161], v[2:5]
	s_barrier
	ds_read_b128 v[130:133], v193 offset:0
	ds_read_b128 v[134:137], v193 offset:2048
	ds_read_b128 v[138:141], v193 offset:4096
	ds_read_b128 v[142:145], v193 offset:6144
	ds_read_b128 v[162:165], v195 offset:32768
	ds_read_b128 v[166:169], v195 offset:34816
	ds_read_b128 v[170:173], v195 offset:36864
	ds_read_b128 v[174:177], v195 offset:38912
	s_waitcnt lgkmcnt(0)
	s_barrier
	v_mfma_f32_16x16x32_f16 v[126:129], v[162:165], v[130:133], v[126:129]
	v_mfma_f32_16x16x32_f16 v[122:125], v[166:169], v[130:133], v[122:125]
	v_mfma_f32_16x16x32_f16 v[118:121], v[170:173], v[130:133], v[118:121]
	v_mfma_f32_16x16x32_f16 v[114:117], v[174:177], v[130:133], v[114:117]
	v_mfma_f32_16x16x32_f16 v[110:113], v[162:165], v[134:137], v[110:113]
	v_mfma_f32_16x16x32_f16 v[106:109], v[166:169], v[134:137], v[106:109]
	v_mfma_f32_16x16x32_f16 v[102:105], v[170:173], v[134:137], v[102:105]
	v_mfma_f32_16x16x32_f16 v[98:101], v[174:177], v[134:137], v[98:101]
	v_mfma_f32_16x16x32_f16 v[94:97], v[162:165], v[138:141], v[94:97]
	v_mfma_f32_16x16x32_f16 v[90:93], v[166:169], v[138:141], v[90:93]
	v_mfma_f32_16x16x32_f16 v[86:89], v[170:173], v[138:141], v[86:89]
	v_mfma_f32_16x16x32_f16 v[82:85], v[174:177], v[138:141], v[82:85]
	v_mfma_f32_16x16x32_f16 v[78:81], v[162:165], v[142:145], v[78:81]
	v_mfma_f32_16x16x32_f16 v[74:77], v[166:169], v[142:145], v[74:77]
	v_mfma_f32_16x16x32_f16 v[70:73], v[170:173], v[142:145], v[70:73]
	v_mfma_f32_16x16x32_f16 v[66:69], v[174:177], v[142:145], v[66:69]
	s_barrier
	ds_read_b128 v[146:149], v193 offset:8192
	ds_read_b128 v[150:153], v193 offset:10240
	ds_read_b128 v[154:157], v193 offset:12288
	ds_read_b128 v[158:161], v193 offset:14336
	s_barrier
	s_waitcnt lgkmcnt(0)
	v_mfma_f32_16x16x32_f16 v[62:65], v[162:165], v[146:149], v[62:65]
	v_mfma_f32_16x16x32_f16 v[58:61], v[166:169], v[146:149], v[58:61]
	v_mfma_f32_16x16x32_f16 v[54:57], v[170:173], v[146:149], v[54:57]
	v_mfma_f32_16x16x32_f16 v[50:53], v[174:177], v[146:149], v[50:53]
	v_mfma_f32_16x16x32_f16 v[46:49], v[162:165], v[150:153], v[46:49]
	v_mfma_f32_16x16x32_f16 v[42:45], v[166:169], v[150:153], v[42:45]
	v_mfma_f32_16x16x32_f16 v[38:41], v[170:173], v[150:153], v[38:41]
	v_mfma_f32_16x16x32_f16 v[34:37], v[174:177], v[150:153], v[34:37]
	v_mfma_f32_16x16x32_f16 v[30:33], v[162:165], v[154:157], v[30:33]
	v_mfma_f32_16x16x32_f16 v[26:29], v[166:169], v[154:157], v[26:29]
	v_mfma_f32_16x16x32_f16 v[22:25], v[170:173], v[154:157], v[22:25]
	v_mfma_f32_16x16x32_f16 v[18:21], v[174:177], v[154:157], v[18:21]
	v_mfma_f32_16x16x32_f16 v[14:17], v[162:165], v[158:161], v[14:17]
	v_mfma_f32_16x16x32_f16 v[10:13], v[166:169], v[158:161], v[10:13]
	v_mfma_f32_16x16x32_f16 v[6:9], v[170:173], v[158:161], v[6:9]
	v_mfma_f32_16x16x32_f16 v[2:5], v[174:177], v[158:161], v[2:5]
	s_barrier
	s_cmp_eq_u32 s29, 1
	s_cbranch_scc1 .Lp4_skew1
	s_barrier

.Lp5_skew0:
	ds_read_b128 v[130:133], v200 offset:0
	ds_read_b128 v[134:137], v200 offset:2048
	ds_read_b128 v[138:141], v200 offset:4096
	ds_read_b128 v[142:145], v200 offset:6144
	ds_read_b128 v[162:165], v202 offset:32768
	ds_read_b128 v[166:169], v202 offset:34816
	ds_read_b128 v[170:173], v202 offset:36864
	ds_read_b128 v[174:177], v202 offset:38912
	s_add_i32 m0, s21, 0x14000
	s_add_u32 s40, s36, 0xb0080
	s_addc_u32 s41, s37, 0
	global_load_lds_dwordx4 v1, s[40:41]
	s_add_i32 m0, s21, 0x1a000
	s_add_u32 s40, s38, 0x58080
	s_addc_u32 s41, s39, 0
	global_load_lds_dwordx4 v1, s[40:41]
	s_barrier
	s_waitcnt lgkmcnt(0)
	v_mfma_f32_16x16x32_f16 v[126:129], v[162:165], v[130:133], 0
	v_mfma_f32_16x16x32_f16 v[122:125], v[166:169], v[130:133], 0
	v_mfma_f32_16x16x32_f16 v[118:121], v[170:173], v[130:133], 0
	v_mfma_f32_16x16x32_f16 v[114:117], v[174:177], v[130:133], 0
	v_mfma_f32_16x16x32_f16 v[110:113], v[162:165], v[134:137], 0
	v_mfma_f32_16x16x32_f16 v[106:109], v[166:169], v[134:137], 0
	v_mfma_f32_16x16x32_f16 v[102:105], v[170:173], v[134:137], 0
	v_mfma_f32_16x16x32_f16 v[98:101], v[174:177], v[134:137], 0
	v_mfma_f32_16x16x32_f16 v[94:97], v[162:165], v[138:141], 0
	v_mfma_f32_16x16x32_f16 v[90:93], v[166:169], v[138:141], 0
	v_mfma_f32_16x16x32_f16 v[86:89], v[170:173], v[138:141], 0
	v_mfma_f32_16x16x32_f16 v[82:85], v[174:177], v[138:141], 0
	v_mfma_f32_16x16x32_f16 v[78:81], v[162:165], v[142:145], 0
	v_mfma_f32_16x16x32_f16 v[74:77], v[166:169], v[142:145], 0
	v_mfma_f32_16x16x32_f16 v[70:73], v[170:173], v[142:145], 0
	v_mfma_f32_16x16x32_f16 v[66:69], v[174:177], v[142:145], 0
	s_barrier
	ds_read_b128 v[146:149], v200 offset:8192
	ds_read_b128 v[150:153], v200 offset:10240
	ds_read_b128 v[154:157], v200 offset:12288
	ds_read_b128 v[158:161], v200 offset:14336
	s_add_i32 m0, s21, 0x1c000
	s_add_u32 s40, s38, 0xb0080
	s_addc_u32 s41, s39, 0
	global_load_lds_dwordx4 v1, s[40:41]
	s_add_i32 m0, s21, 0x1e000
	s_add_u32 s40, s38, 0x108080
	s_addc_u32 s41, s39, 0
	global_load_lds_dwordx4 v1, s[40:41]
	s_barrier
	s_waitcnt lgkmcnt(0)
	v_mfma_f32_16x16x32_f16 v[62:65], v[162:165], v[146:149], 0
	v_mfma_f32_16x16x32_f16 v[58:61], v[166:169], v[146:149], 0
	v_mfma_f32_16x16x32_f16 v[54:57], v[170:173], v[146:149], 0
	v_mfma_f32_16x16x32_f16 v[50:53], v[174:177], v[146:149], 0
	v_mfma_f32_16x16x32_f16 v[46:49], v[162:165], v[150:153], 0
	v_mfma_f32_16x16x32_f16 v[42:45], v[166:169], v[150:153], 0
	v_mfma_f32_16x16x32_f16 v[38:41], v[170:173], v[150:153], 0
	v_mfma_f32_16x16x32_f16 v[34:37], v[174:177], v[150:153], 0
	v_mfma_f32_16x16x32_f16 v[30:33], v[162:165], v[154:157], 0
	v_mfma_f32_16x16x32_f16 v[26:29], v[166:169], v[154:157], 0
	v_mfma_f32_16x16x32_f16 v[22:25], v[170:173], v[154:157], 0
	v_mfma_f32_16x16x32_f16 v[18:21], v[174:177], v[154:157], 0
	v_mfma_f32_16x16x32_f16 v[14:17], v[162:165], v[158:161], 0
	v_mfma_f32_16x16x32_f16 v[10:13], v[166:169], v[158:161], 0
	v_mfma_f32_16x16x32_f16 v[6:9], v[170:173], v[158:161], 0
	v_mfma_f32_16x16x32_f16 v[2:5], v[174:177], v[158:161], 0
	s_barrier
	ds_read_b128 v[130:133], v201 offset:0
	ds_read_b128 v[134:137], v201 offset:2048
	ds_read_b128 v[138:141], v201 offset:4096
	ds_read_b128 v[142:145], v201 offset:6144
	ds_read_b128 v[162:165], v203 offset:32768
	ds_read_b128 v[166:169], v203 offset:34816
	ds_read_b128 v[170:173], v203 offset:36864
	ds_read_b128 v[174:177], v203 offset:38912
	s_add_i32 m0, s21, 0x12000
	s_add_u32 s40, s36, 0x58080
	s_addc_u32 s41, s37, 0
	global_load_lds_dwordx4 v1, s[40:41]
	s_add_i32 m0, s21, 0x16000
	s_add_u32 s40, s36, 0x108080
	s_addc_u32 s41, s37, 0
	global_load_lds_dwordx4 v1, s[40:41]
	s_waitcnt lgkmcnt(0)
	s_barrier
	v_mfma_f32_16x16x32_f16 v[126:129], v[162:165], v[130:133], v[126:129]
	v_mfma_f32_16x16x32_f16 v[122:125], v[166:169], v[130:133], v[122:125]
	v_mfma_f32_16x16x32_f16 v[118:121], v[170:173], v[130:133], v[118:121]
	v_mfma_f32_16x16x32_f16 v[114:117], v[174:177], v[130:133], v[114:117]
	v_mfma_f32_16x16x32_f16 v[110:113], v[162:165], v[134:137], v[110:113]
	v_mfma_f32_16x16x32_f16 v[106:109], v[166:169], v[134:137], v[106:109]
	v_mfma_f32_16x16x32_f16 v[102:105], v[170:173], v[134:137], v[102:105]
	v_mfma_f32_16x16x32_f16 v[98:101], v[174:177], v[134:137], v[98:101]
	v_mfma_f32_16x16x32_f16 v[94:97], v[162:165], v[138:141], v[94:97]
	v_mfma_f32_16x16x32_f16 v[90:93], v[166:169], v[138:141], v[90:93]
	v_mfma_f32_16x16x32_f16 v[86:89], v[170:173], v[138:141], v[86:89]
	v_mfma_f32_16x16x32_f16 v[82:85], v[174:177], v[138:141], v[82:85]
	v_mfma_f32_16x16x32_f16 v[78:81], v[162:165], v[142:145], v[78:81]
	v_mfma_f32_16x16x32_f16 v[74:77], v[166:169], v[142:145], v[74:77]
	v_mfma_f32_16x16x32_f16 v[70:73], v[170:173], v[142:145], v[70:73]
	v_mfma_f32_16x16x32_f16 v[66:69], v[174:177], v[142:145], v[66:69]
	s_barrier
	ds_read_b128 v[146:149], v201 offset:8192
	ds_read_b128 v[150:153], v201 offset:10240
	ds_read_b128 v[154:157], v201 offset:12288
	ds_read_b128 v[158:161], v201 offset:14336
	s_mov_b32 m0, s21
	s_add_u32 s40, s36, 0x100
	s_addc_u32 s41, s37, 0
	global_load_lds_dwordx4 v1, s[40:41]
	s_add_i32 m0, s21, 0x8000
	s_add_u32 s40, s38, 0x100
	s_addc_u32 s41, s39, 0
	global_load_lds_dwordx4 v1, s[40:41]
	s_waitcnt vmcnt(4)
	s_barrier
	s_waitcnt lgkmcnt(0)
	v_mfma_f32_16x16x32_f16 v[62:65], v[162:165], v[146:149], v[62:65]
	v_mfma_f32_16x16x32_f16 v[58:61], v[166:169], v[146:149], v[58:61]
	v_mfma_f32_16x16x32_f16 v[54:57], v[170:173], v[146:149], v[54:57]
	v_mfma_f32_16x16x32_f16 v[50:53], v[174:177], v[146:149], v[50:53]
	v_mfma_f32_16x16x32_f16 v[46:49], v[162:165], v[150:153], v[46:49]
	v_mfma_f32_16x16x32_f16 v[42:45], v[166:169], v[150:153], v[42:45]
	v_mfma_f32_16x16x32_f16 v[38:41], v[170:173], v[150:153], v[38:41]
	v_mfma_f32_16x16x32_f16 v[34:37], v[174:177], v[150:153], v[34:37]
	v_mfma_f32_16x16x32_f16 v[30:33], v[162:165], v[154:157], v[30:33]
	v_mfma_f32_16x16x32_f16 v[26:29], v[166:169], v[154:157], v[26:29]
	v_mfma_f32_16x16x32_f16 v[22:25], v[170:173], v[154:157], v[22:25]
	v_mfma_f32_16x16x32_f16 v[18:21], v[174:177], v[154:157], v[18:21]
	v_mfma_f32_16x16x32_f16 v[14:17], v[162:165], v[158:161], v[14:17]
	v_mfma_f32_16x16x32_f16 v[10:13], v[166:169], v[158:161], v[10:13]
	v_mfma_f32_16x16x32_f16 v[6:9], v[170:173], v[158:161], v[6:9]
	v_mfma_f32_16x16x32_f16 v[2:5], v[174:177], v[158:161], v[2:5]
	s_barrier
	s_add_u32 s36, s36, 0x80
	s_addc_u32 s37, s37, 0
	s_add_u32 s38, s38, 0x80
	s_addc_u32 s39, s39, 0
	ds_read_b128 v[130:133], v204 offset:0
	ds_read_b128 v[134:137], v204 offset:2048
	ds_read_b128 v[138:141], v204 offset:4096
	ds_read_b128 v[142:145], v204 offset:6144
	ds_read_b128 v[162:165], v206 offset:32768
	ds_read_b128 v[166:169], v206 offset:34816
	ds_read_b128 v[170:173], v206 offset:36864
	ds_read_b128 v[174:177], v206 offset:38912
	s_add_i32 m0, s21, 0x4000
	s_add_u32 s40, s36, 0xb0080
	s_addc_u32 s41, s37, 0
	global_load_lds_dwordx4 v1, s[40:41]
	s_add_i32 m0, s21, 0xa000
	s_add_u32 s40, s38, 0x58080
	s_addc_u32 s41, s39, 0
	global_load_lds_dwordx4 v1, s[40:41]
	s_waitcnt vmcnt(4)
	s_barrier
	s_waitcnt lgkmcnt(0)
	v_mfma_f32_16x16x32_f16 v[126:129], v[162:165], v[130:133], v[126:129]
	v_mfma_f32_16x16x32_f16 v[122:125], v[166:169], v[130:133], v[122:125]
	v_mfma_f32_16x16x32_f16 v[118:121], v[170:173], v[130:133], v[118:121]
	v_mfma_f32_16x16x32_f16 v[114:117], v[174:177], v[130:133], v[114:117]
	v_mfma_f32_16x16x32_f16 v[110:113], v[162:165], v[134:137], v[110:113]
	v_mfma_f32_16x16x32_f16 v[106:109], v[166:169], v[134:137], v[106:109]
	v_mfma_f32_16x16x32_f16 v[102:105], v[170:173], v[134:137], v[102:105]
	v_mfma_f32_16x16x32_f16 v[98:101], v[174:177], v[134:137], v[98:101]
	v_mfma_f32_16x16x32_f16 v[94:97], v[162:165], v[138:141], v[94:97]
	v_mfma_f32_16x16x32_f16 v[90:93], v[166:169], v[138:141], v[90:93]
	v_mfma_f32_16x16x32_f16 v[86:89], v[170:173], v[138:141], v[86:89]
	v_mfma_f32_16x16x32_f16 v[82:85], v[174:177], v[138:141], v[82:85]
	v_mfma_f32_16x16x32_f16 v[78:81], v[162:165], v[142:145], v[78:81]
	v_mfma_f32_16x16x32_f16 v[74:77], v[166:169], v[142:145], v[74:77]
	v_mfma_f32_16x16x32_f16 v[70:73], v[170:173], v[142:145], v[70:73]
	v_mfma_f32_16x16x32_f16 v[66:69], v[174:177], v[142:145], v[66:69]
	s_barrier
	ds_read_b128 v[146:149], v204 offset:8192
	ds_read_b128 v[150:153], v204 offset:10240
	ds_read_b128 v[154:157], v204 offset:12288
	ds_read_b128 v[158:161], v204 offset:14336
	s_add_i32 m0, s21, 0xc000
	s_add_u32 s40, s38, 0xb0080
	s_addc_u32 s41, s39, 0
	global_load_lds_dwordx4 v1, s[40:41]
	s_add_i32 m0, s21, 0xe000
	s_add_u32 s40, s38, 0x108080
	s_addc_u32 s41, s39, 0
	global_load_lds_dwordx4 v1, s[40:41]
	s_barrier
	s_waitcnt lgkmcnt(0)
	v_mfma_f32_16x16x32_f16 v[62:65], v[162:165], v[146:149], v[62:65]
	v_mfma_f32_16x16x32_f16 v[58:61], v[166:169], v[146:149], v[58:61]
	v_mfma_f32_16x16x32_f16 v[54:57], v[170:173], v[146:149], v[54:57]
	v_mfma_f32_16x16x32_f16 v[50:53], v[174:177], v[146:149], v[50:53]
	v_mfma_f32_16x16x32_f16 v[46:49], v[162:165], v[150:153], v[46:49]
	v_mfma_f32_16x16x32_f16 v[42:45], v[166:169], v[150:153], v[42:45]
	v_mfma_f32_16x16x32_f16 v[38:41], v[170:173], v[150:153], v[38:41]
	v_mfma_f32_16x16x32_f16 v[34:37], v[174:177], v[150:153], v[34:37]
	v_mfma_f32_16x16x32_f16 v[30:33], v[162:165], v[154:157], v[30:33]
	v_mfma_f32_16x16x32_f16 v[26:29], v[166:169], v[154:157], v[26:29]
	v_mfma_f32_16x16x32_f16 v[22:25], v[170:173], v[154:157], v[22:25]
	v_mfma_f32_16x16x32_f16 v[18:21], v[174:177], v[154:157], v[18:21]
	v_mfma_f32_16x16x32_f16 v[14:17], v[162:165], v[158:161], v[14:17]
	v_mfma_f32_16x16x32_f16 v[10:13], v[166:169], v[158:161], v[10:13]
	v_mfma_f32_16x16x32_f16 v[6:9], v[170:173], v[158:161], v[6:9]
	v_mfma_f32_16x16x32_f16 v[2:5], v[174:177], v[158:161], v[2:5]
	s_barrier
	ds_read_b128 v[130:133], v205 offset:0
	ds_read_b128 v[134:137], v205 offset:2048
	ds_read_b128 v[138:141], v205 offset:4096
	ds_read_b128 v[142:145], v205 offset:6144
	ds_read_b128 v[162:165], v207 offset:32768
	ds_read_b128 v[166:169], v207 offset:34816
	ds_read_b128 v[170:173], v207 offset:36864
	ds_read_b128 v[174:177], v207 offset:38912
	s_add_i32 m0, s21, 0x2000
	s_add_u32 s40, s36, 0x58080
	s_addc_u32 s41, s37, 0
	global_load_lds_dwordx4 v1, s[40:41]
	s_add_i32 m0, s21, 0x6000
	s_add_u32 s40, s36, 0x108080
	s_addc_u32 s41, s37, 0
	global_load_lds_dwordx4 v1, s[40:41]
	s_waitcnt lgkmcnt(0)
	s_barrier
	v_mfma_f32_16x16x32_f16 v[126:129], v[162:165], v[130:133], v[126:129]
	v_mfma_f32_16x16x32_f16 v[122:125], v[166:169], v[130:133], v[122:125]
	v_mfma_f32_16x16x32_f16 v[118:121], v[170:173], v[130:133], v[118:121]
	v_mfma_f32_16x16x32_f16 v[114:117], v[174:177], v[130:133], v[114:117]
	v_mfma_f32_16x16x32_f16 v[110:113], v[162:165], v[134:137], v[110:113]
	v_mfma_f32_16x16x32_f16 v[106:109], v[166:169], v[134:137], v[106:109]
	v_mfma_f32_16x16x32_f16 v[102:105], v[170:173], v[134:137], v[102:105]
	v_mfma_f32_16x16x32_f16 v[98:101], v[174:177], v[134:137], v[98:101]
	v_mfma_f32_16x16x32_f16 v[94:97], v[162:165], v[138:141], v[94:97]
	v_mfma_f32_16x16x32_f16 v[90:93], v[166:169], v[138:141], v[90:93]
	v_mfma_f32_16x16x32_f16 v[86:89], v[170:173], v[138:141], v[86:89]
	v_mfma_f32_16x16x32_f16 v[82:85], v[174:177], v[138:141], v[82:85]
	v_mfma_f32_16x16x32_f16 v[78:81], v[162:165], v[142:145], v[78:81]
	v_mfma_f32_16x16x32_f16 v[74:77], v[166:169], v[142:145], v[74:77]
	v_mfma_f32_16x16x32_f16 v[70:73], v[170:173], v[142:145], v[70:73]
	v_mfma_f32_16x16x32_f16 v[66:69], v[174:177], v[142:145], v[66:69]
	s_barrier
	ds_read_b128 v[146:149], v205 offset:8192
	ds_read_b128 v[150:153], v205 offset:10240
	ds_read_b128 v[154:157], v205 offset:12288
	ds_read_b128 v[158:161], v205 offset:14336
	s_add_i32 m0, s21, 0x10000
	s_add_u32 s40, s36, 0x100
	s_addc_u32 s41, s37, 0
	global_load_lds_dwordx4 v1, s[40:41]
	s_add_i32 m0, s21, 0x18000
	s_add_u32 s40, s38, 0x100
	s_addc_u32 s41, s39, 0
	global_load_lds_dwordx4 v1, s[40:41]
	s_waitcnt vmcnt(4)
	s_barrier
	s_waitcnt lgkmcnt(0)
	v_mfma_f32_16x16x32_f16 v[62:65], v[162:165], v[146:149], v[62:65]
	v_mfma_f32_16x16x32_f16 v[58:61], v[166:169], v[146:149], v[58:61]
	v_mfma_f32_16x16x32_f16 v[54:57], v[170:173], v[146:149], v[54:57]
	v_mfma_f32_16x16x32_f16 v[50:53], v[174:177], v[146:149], v[50:53]
	v_mfma_f32_16x16x32_f16 v[46:49], v[162:165], v[150:153], v[46:49]
	v_mfma_f32_16x16x32_f16 v[42:45], v[166:169], v[150:153], v[42:45]
	v_mfma_f32_16x16x32_f16 v[38:41], v[170:173], v[150:153], v[38:41]
	v_mfma_f32_16x16x32_f16 v[34:37], v[174:177], v[150:153], v[34:37]
	v_mfma_f32_16x16x32_f16 v[30:33], v[162:165], v[154:157], v[30:33]
	v_mfma_f32_16x16x32_f16 v[26:29], v[166:169], v[154:157], v[26:29]
	v_mfma_f32_16x16x32_f16 v[22:25], v[170:173], v[154:157], v[22:25]
	v_mfma_f32_16x16x32_f16 v[18:21], v[174:177], v[154:157], v[18:21]
	v_mfma_f32_16x16x32_f16 v[14:17], v[162:165], v[158:161], v[14:17]
	v_mfma_f32_16x16x32_f16 v[10:13], v[166:169], v[158:161], v[10:13]
	v_mfma_f32_16x16x32_f16 v[6:9], v[170:173], v[158:161], v[6:9]
	v_mfma_f32_16x16x32_f16 v[2:5], v[174:177], v[158:161], v[2:5]
	s_barrier
	s_add_u32 s36, s36, 0x80
	s_addc_u32 s37, s37, 0
	s_add_u32 s38, s38, 0x80
	s_addc_u32 s39, s39, 0
	s_movk_i32 s23, 20
.Lp5_loop:
	ds_read_b128 v[130:133], v200 offset:0
	ds_read_b128 v[134:137], v200 offset:2048
	ds_read_b128 v[138:141], v200 offset:4096
	ds_read_b128 v[142:145], v200 offset:6144
	ds_read_b128 v[162:165], v202 offset:32768
	ds_read_b128 v[166:169], v202 offset:34816
	ds_read_b128 v[170:173], v202 offset:36864
	ds_read_b128 v[174:177], v202 offset:38912
	s_add_i32 m0, s21, 0x14000
	s_add_u32 s40, s36, 0xb0080
	s_addc_u32 s41, s37, 0
	global_load_lds_dwordx4 v1, s[40:41]
	s_add_i32 m0, s21, 0x1a000
	s_add_u32 s40, s38, 0x58080
	s_addc_u32 s41, s39, 0
	global_load_lds_dwordx4 v1, s[40:41]
	s_waitcnt vmcnt(4)
	s_barrier
	s_waitcnt lgkmcnt(0)
	v_mfma_f32_16x16x32_f16 v[126:129], v[162:165], v[130:133], v[126:129]
	v_mfma_f32_16x16x32_f16 v[122:125], v[166:169], v[130:133], v[122:125]
	v_mfma_f32_16x16x32_f16 v[118:121], v[170:173], v[130:133], v[118:121]
	v_mfma_f32_16x16x32_f16 v[114:117], v[174:177], v[130:133], v[114:117]
	v_mfma_f32_16x16x32_f16 v[110:113], v[162:165], v[134:137], v[110:113]
	v_mfma_f32_16x16x32_f16 v[106:109], v[166:169], v[134:137], v[106:109]
	v_mfma_f32_16x16x32_f16 v[102:105], v[170:173], v[134:137], v[102:105]
	v_mfma_f32_16x16x32_f16 v[98:101], v[174:177], v[134:137], v[98:101]
	v_mfma_f32_16x16x32_f16 v[94:97], v[162:165], v[138:141], v[94:97]
	v_mfma_f32_16x16x32_f16 v[90:93], v[166:169], v[138:141], v[90:93]
	v_mfma_f32_16x16x32_f16 v[86:89], v[170:173], v[138:141], v[86:89]
	v_mfma_f32_16x16x32_f16 v[82:85], v[174:177], v[138:141], v[82:85]
	v_mfma_f32_16x16x32_f16 v[78:81], v[162:165], v[142:145], v[78:81]
	v_mfma_f32_16x16x32_f16 v[74:77], v[166:169], v[142:145], v[74:77]
	v_mfma_f32_16x16x32_f16 v[70:73], v[170:173], v[142:145], v[70:73]
	v_mfma_f32_16x16x32_f16 v[66:69], v[174:177], v[142:145], v[66:69]
	s_barrier
	ds_read_b128 v[146:149], v200 offset:8192
	ds_read_b128 v[150:153], v200 offset:10240
	ds_read_b128 v[154:157], v200 offset:12288
	ds_read_b128 v[158:161], v200 offset:14336
	s_add_i32 m0, s21, 0x1c000
	s_add_u32 s40, s38, 0xb0080
	s_addc_u32 s41, s39, 0
	global_load_lds_dwordx4 v1, s[40:41]
	s_add_i32 m0, s21, 0x1e000
	s_add_u32 s40, s38, 0x108080
	s_addc_u32 s41, s39, 0
	global_load_lds_dwordx4 v1, s[40:41]
	s_barrier
	s_waitcnt lgkmcnt(0)
	v_mfma_f32_16x16x32_f16 v[62:65], v[162:165], v[146:149], v[62:65]
	v_mfma_f32_16x16x32_f16 v[58:61], v[166:169], v[146:149], v[58:61]
	v_mfma_f32_16x16x32_f16 v[54:57], v[170:173], v[146:149], v[54:57]
	v_mfma_f32_16x16x32_f16 v[50:53], v[174:177], v[146:149], v[50:53]
	v_mfma_f32_16x16x32_f16 v[46:49], v[162:165], v[150:153], v[46:49]
	v_mfma_f32_16x16x32_f16 v[42:45], v[166:169], v[150:153], v[42:45]
	v_mfma_f32_16x16x32_f16 v[38:41], v[170:173], v[150:153], v[38:41]
	v_mfma_f32_16x16x32_f16 v[34:37], v[174:177], v[150:153], v[34:37]
	v_mfma_f32_16x16x32_f16 v[30:33], v[162:165], v[154:157], v[30:33]
	v_mfma_f32_16x16x32_f16 v[26:29], v[166:169], v[154:157], v[26:29]
	v_mfma_f32_16x16x32_f16 v[22:25], v[170:173], v[154:157], v[22:25]
	v_mfma_f32_16x16x32_f16 v[18:21], v[174:177], v[154:157], v[18:21]
	v_mfma_f32_16x16x32_f16 v[14:17], v[162:165], v[158:161], v[14:17]
	v_mfma_f32_16x16x32_f16 v[10:13], v[166:169], v[158:161], v[10:13]
	v_mfma_f32_16x16x32_f16 v[6:9], v[170:173], v[158:161], v[6:9]
	v_mfma_f32_16x16x32_f16 v[2:5], v[174:177], v[158:161], v[2:5]
	s_barrier
	ds_read_b128 v[130:133], v201 offset:0
	ds_read_b128 v[134:137], v201 offset:2048
	ds_read_b128 v[138:141], v201 offset:4096
	ds_read_b128 v[142:145], v201 offset:6144
	ds_read_b128 v[162:165], v203 offset:32768
	ds_read_b128 v[166:169], v203 offset:34816
	ds_read_b128 v[170:173], v203 offset:36864
	ds_read_b128 v[174:177], v203 offset:38912
	s_add_i32 m0, s21, 0x12000
	s_add_u32 s40, s36, 0x58080
	s_addc_u32 s41, s37, 0
	global_load_lds_dwordx4 v1, s[40:41]
	s_add_i32 m0, s21, 0x16000
	s_add_u32 s40, s36, 0x108080
	s_addc_u32 s41, s37, 0
	global_load_lds_dwordx4 v1, s[40:41]
	s_waitcnt lgkmcnt(0)
	s_barrier
	v_mfma_f32_16x16x32_f16 v[126:129], v[162:165], v[130:133], v[126:129]
	v_mfma_f32_16x16x32_f16 v[122:125], v[166:169], v[130:133], v[122:125]
	v_mfma_f32_16x16x32_f16 v[118:121], v[170:173], v[130:133], v[118:121]
	v_mfma_f32_16x16x32_f16 v[114:117], v[174:177], v[130:133], v[114:117]
	v_mfma_f32_16x16x32_f16 v[110:113], v[162:165], v[134:137], v[110:113]
	v_mfma_f32_16x16x32_f16 v[106:109], v[166:169], v[134:137], v[106:109]
	v_mfma_f32_16x16x32_f16 v[102:105], v[170:173], v[134:137], v[102:105]
	v_mfma_f32_16x16x32_f16 v[98:101], v[174:177], v[134:137], v[98:101]
	v_mfma_f32_16x16x32_f16 v[94:97], v[162:165], v[138:141], v[94:97]
	v_mfma_f32_16x16x32_f16 v[90:93], v[166:169], v[138:141], v[90:93]
	v_mfma_f32_16x16x32_f16 v[86:89], v[170:173], v[138:141], v[86:89]
	v_mfma_f32_16x16x32_f16 v[82:85], v[174:177], v[138:141], v[82:85]
	v_mfma_f32_16x16x32_f16 v[78:81], v[162:165], v[142:145], v[78:81]
	v_mfma_f32_16x16x32_f16 v[74:77], v[166:169], v[142:145], v[74:77]
	v_mfma_f32_16x16x32_f16 v[70:73], v[170:173], v[142:145], v[70:73]
	v_mfma_f32_16x16x32_f16 v[66:69], v[174:177], v[142:145], v[66:69]
	s_barrier
	ds_read_b128 v[146:149], v201 offset:8192
	ds_read_b128 v[150:153], v201 offset:10240
	ds_read_b128 v[154:157], v201 offset:12288
	ds_read_b128 v[158:161], v201 offset:14336
	s_mov_b32 m0, s21
	s_add_u32 s40, s36, 0x100
	s_addc_u32 s41, s37, 0
	global_load_lds_dwordx4 v1, s[40:41]
	s_add_i32 m0, s21, 0x8000
	s_add_u32 s40, s38, 0x100
	s_addc_u32 s41, s39, 0
	global_load_lds_dwordx4 v1, s[40:41]
	s_waitcnt vmcnt(4)
	s_barrier
	s_waitcnt lgkmcnt(0)
	v_mfma_f32_16x16x32_f16 v[62:65], v[162:165], v[146:149], v[62:65]
	v_mfma_f32_16x16x32_f16 v[58:61], v[166:169], v[146:149], v[58:61]
	v_mfma_f32_16x16x32_f16 v[54:57], v[170:173], v[146:149], v[54:57]
	v_mfma_f32_16x16x32_f16 v[50:53], v[174:177], v[146:149], v[50:53]
	v_mfma_f32_16x16x32_f16 v[46:49], v[162:165], v[150:153], v[46:49]
	v_mfma_f32_16x16x32_f16 v[42:45], v[166:169], v[150:153], v[42:45]
	v_mfma_f32_16x16x32_f16 v[38:41], v[170:173], v[150:153], v[38:41]
	v_mfma_f32_16x16x32_f16 v[34:37], v[174:177], v[150:153], v[34:37]
	v_mfma_f32_16x16x32_f16 v[30:33], v[162:165], v[154:157], v[30:33]
	v_mfma_f32_16x16x32_f16 v[26:29], v[166:169], v[154:157], v[26:29]
	v_mfma_f32_16x16x32_f16 v[22:25], v[170:173], v[154:157], v[22:25]
	v_mfma_f32_16x16x32_f16 v[18:21], v[174:177], v[154:157], v[18:21]
	v_mfma_f32_16x16x32_f16 v[14:17], v[162:165], v[158:161], v[14:17]
	v_mfma_f32_16x16x32_f16 v[10:13], v[166:169], v[158:161], v[10:13]
	v_mfma_f32_16x16x32_f16 v[6:9], v[170:173], v[158:161], v[6:9]
	v_mfma_f32_16x16x32_f16 v[2:5], v[174:177], v[158:161], v[2:5]
	s_barrier
	s_add_u32 s36, s36, 0x80
	s_addc_u32 s37, s37, 0
	s_add_u32 s38, s38, 0x80
	s_addc_u32 s39, s39, 0
	ds_read_b128 v[130:133], v204 offset:0
	ds_read_b128 v[134:137], v204 offset:2048
	ds_read_b128 v[138:141], v204 offset:4096
	ds_read_b128 v[142:145], v204 offset:6144
	ds_read_b128 v[162:165], v206 offset:32768
	ds_read_b128 v[166:169], v206 offset:34816
	ds_read_b128 v[170:173], v206 offset:36864
	ds_read_b128 v[174:177], v206 offset:38912
	s_add_i32 m0, s21, 0x4000
	s_add_u32 s40, s36, 0xb0080
	s_addc_u32 s41, s37, 0
	global_load_lds_dwordx4 v1, s[40:41]
	s_add_i32 m0, s21, 0xa000
	s_add_u32 s40, s38, 0x58080
	s_addc_u32 s41, s39, 0
	global_load_lds_dwordx4 v1, s[40:41]
	s_waitcnt vmcnt(4)
	s_barrier
	s_waitcnt lgkmcnt(0)
	v_mfma_f32_16x16x32_f16 v[126:129], v[162:165], v[130:133], v[126:129]
	v_mfma_f32_16x16x32_f16 v[122:125], v[166:169], v[130:133], v[122:125]
	v_mfma_f32_16x16x32_f16 v[118:121], v[170:173], v[130:133], v[118:121]
	v_mfma_f32_16x16x32_f16 v[114:117], v[174:177], v[130:133], v[114:117]
	v_mfma_f32_16x16x32_f16 v[110:113], v[162:165], v[134:137], v[110:113]
	v_mfma_f32_16x16x32_f16 v[106:109], v[166:169], v[134:137], v[106:109]
	v_mfma_f32_16x16x32_f16 v[102:105], v[170:173], v[134:137], v[102:105]
	v_mfma_f32_16x16x32_f16 v[98:101], v[174:177], v[134:137], v[98:101]
	v_mfma_f32_16x16x32_f16 v[94:97], v[162:165], v[138:141], v[94:97]
	v_mfma_f32_16x16x32_f16 v[90:93], v[166:169], v[138:141], v[90:93]
	v_mfma_f32_16x16x32_f16 v[86:89], v[170:173], v[138:141], v[86:89]
	v_mfma_f32_16x16x32_f16 v[82:85], v[174:177], v[138:141], v[82:85]
	v_mfma_f32_16x16x32_f16 v[78:81], v[162:165], v[142:145], v[78:81]
	v_mfma_f32_16x16x32_f16 v[74:77], v[166:169], v[142:145], v[74:77]
	v_mfma_f32_16x16x32_f16 v[70:73], v[170:173], v[142:145], v[70:73]
	v_mfma_f32_16x16x32_f16 v[66:69], v[174:177], v[142:145], v[66:69]
	s_barrier
	ds_read_b128 v[146:149], v204 offset:8192
	ds_read_b128 v[150:153], v204 offset:10240
	ds_read_b128 v[154:157], v204 offset:12288
	ds_read_b128 v[158:161], v204 offset:14336
	s_add_i32 m0, s21, 0xc000
	s_add_u32 s40, s38, 0xb0080
	s_addc_u32 s41, s39, 0
	global_load_lds_dwordx4 v1, s[40:41]
	s_add_i32 m0, s21, 0xe000
	s_add_u32 s40, s38, 0x108080
	s_addc_u32 s41, s39, 0
	global_load_lds_dwordx4 v1, s[40:41]
	s_barrier
	s_waitcnt lgkmcnt(0)
	v_mfma_f32_16x16x32_f16 v[62:65], v[162:165], v[146:149], v[62:65]
	v_mfma_f32_16x16x32_f16 v[58:61], v[166:169], v[146:149], v[58:61]
	v_mfma_f32_16x16x32_f16 v[54:57], v[170:173], v[146:149], v[54:57]
	v_mfma_f32_16x16x32_f16 v[50:53], v[174:177], v[146:149], v[50:53]
	v_mfma_f32_16x16x32_f16 v[46:49], v[162:165], v[150:153], v[46:49]
	v_mfma_f32_16x16x32_f16 v[42:45], v[166:169], v[150:153], v[42:45]
	v_mfma_f32_16x16x32_f16 v[38:41], v[170:173], v[150:153], v[38:41]
	v_mfma_f32_16x16x32_f16 v[34:37], v[174:177], v[150:153], v[34:37]
	v_mfma_f32_16x16x32_f16 v[30:33], v[162:165], v[154:157], v[30:33]
	v_mfma_f32_16x16x32_f16 v[26:29], v[166:169], v[154:157], v[26:29]
	v_mfma_f32_16x16x32_f16 v[22:25], v[170:173], v[154:157], v[22:25]
	v_mfma_f32_16x16x32_f16 v[18:21], v[174:177], v[154:157], v[18:21]
	v_mfma_f32_16x16x32_f16 v[14:17], v[162:165], v[158:161], v[14:17]
	v_mfma_f32_16x16x32_f16 v[10:13], v[166:169], v[158:161], v[10:13]
	v_mfma_f32_16x16x32_f16 v[6:9], v[170:173], v[158:161], v[6:9]
	v_mfma_f32_16x16x32_f16 v[2:5], v[174:177], v[158:161], v[2:5]
	s_barrier
	ds_read_b128 v[130:133], v205 offset:0
	ds_read_b128 v[134:137], v205 offset:2048
	ds_read_b128 v[138:141], v205 offset:4096
	ds_read_b128 v[142:145], v205 offset:6144
	ds_read_b128 v[162:165], v207 offset:32768
	ds_read_b128 v[166:169], v207 offset:34816
	ds_read_b128 v[170:173], v207 offset:36864
	ds_read_b128 v[174:177], v207 offset:38912
	s_add_i32 m0, s21, 0x2000
	s_add_u32 s40, s36, 0x58080
	s_addc_u32 s41, s37, 0
	global_load_lds_dwordx4 v1, s[40:41]
	s_add_i32 m0, s21, 0x6000
	s_add_u32 s40, s36, 0x108080
	s_addc_u32 s41, s37, 0
	global_load_lds_dwordx4 v1, s[40:41]
	s_waitcnt lgkmcnt(0)
	s_barrier
	v_mfma_f32_16x16x32_f16 v[126:129], v[162:165], v[130:133], v[126:129]
	v_mfma_f32_16x16x32_f16 v[122:125], v[166:169], v[130:133], v[122:125]
	v_mfma_f32_16x16x32_f16 v[118:121], v[170:173], v[130:133], v[118:121]
	v_mfma_f32_16x16x32_f16 v[114:117], v[174:177], v[130:133], v[114:117]
	v_mfma_f32_16x16x32_f16 v[110:113], v[162:165], v[134:137], v[110:113]
	v_mfma_f32_16x16x32_f16 v[106:109], v[166:169], v[134:137], v[106:109]
	v_mfma_f32_16x16x32_f16 v[102:105], v[170:173], v[134:137], v[102:105]
	v_mfma_f32_16x16x32_f16 v[98:101], v[174:177], v[134:137], v[98:101]
	v_mfma_f32_16x16x32_f16 v[94:97], v[162:165], v[138:141], v[94:97]
	v_mfma_f32_16x16x32_f16 v[90:93], v[166:169], v[138:141], v[90:93]
	v_mfma_f32_16x16x32_f16 v[86:89], v[170:173], v[138:141], v[86:89]
	v_mfma_f32_16x16x32_f16 v[82:85], v[174:177], v[138:141], v[82:85]
	v_mfma_f32_16x16x32_f16 v[78:81], v[162:165], v[142:145], v[78:81]
	v_mfma_f32_16x16x32_f16 v[74:77], v[166:169], v[142:145], v[74:77]
	v_mfma_f32_16x16x32_f16 v[70:73], v[170:173], v[142:145], v[70:73]
	v_mfma_f32_16x16x32_f16 v[66:69], v[174:177], v[142:145], v[66:69]
	s_barrier
	ds_read_b128 v[146:149], v205 offset:8192
	ds_read_b128 v[150:153], v205 offset:10240
	ds_read_b128 v[154:157], v205 offset:12288
	ds_read_b128 v[158:161], v205 offset:14336
	s_add_i32 m0, s21, 0x10000
	s_add_u32 s40, s36, 0x100
	s_addc_u32 s41, s37, 0
	global_load_lds_dwordx4 v1, s[40:41]
	s_add_i32 m0, s21, 0x18000
	s_add_u32 s40, s38, 0x100
	s_addc_u32 s41, s39, 0
	global_load_lds_dwordx4 v1, s[40:41]
	s_waitcnt vmcnt(4)
	s_barrier
	s_waitcnt lgkmcnt(0)
	v_mfma_f32_16x16x32_f16 v[62:65], v[162:165], v[146:149], v[62:65]
	v_mfma_f32_16x16x32_f16 v[58:61], v[166:169], v[146:149], v[58:61]
	v_mfma_f32_16x16x32_f16 v[54:57], v[170:173], v[146:149], v[54:57]
	v_mfma_f32_16x16x32_f16 v[50:53], v[174:177], v[146:149], v[50:53]
	v_mfma_f32_16x16x32_f16 v[46:49], v[162:165], v[150:153], v[46:49]
	v_mfma_f32_16x16x32_f16 v[42:45], v[166:169], v[150:153], v[42:45]
	v_mfma_f32_16x16x32_f16 v[38:41], v[170:173], v[150:153], v[38:41]
	v_mfma_f32_16x16x32_f16 v[34:37], v[174:177], v[150:153], v[34:37]
	v_mfma_f32_16x16x32_f16 v[30:33], v[162:165], v[154:157], v[30:33]
	v_mfma_f32_16x16x32_f16 v[26:29], v[166:169], v[154:157], v[26:29]
	v_mfma_f32_16x16x32_f16 v[22:25], v[170:173], v[154:157], v[22:25]
	v_mfma_f32_16x16x32_f16 v[18:21], v[174:177], v[154:157], v[18:21]
	v_mfma_f32_16x16x32_f16 v[14:17], v[162:165], v[158:161], v[14:17]
	v_mfma_f32_16x16x32_f16 v[10:13], v[166:169], v[158:161], v[10:13]
	v_mfma_f32_16x16x32_f16 v[6:9], v[170:173], v[158:161], v[6:9]
	v_mfma_f32_16x16x32_f16 v[2:5], v[174:177], v[158:161], v[2:5]
	s_barrier
	s_add_u32 s36, s36, 0x80
	s_addc_u32 s37, s37, 0
	s_add_u32 s38, s38, 0x80
	s_addc_u32 s39, s39, 0
	s_add_i32 s23, s23, -1
	s_cmp_lg_u32 s23, 0
	s_cbranch_scc1 .Lp5_loop
	ds_read_b128 v[130:133], v200 offset:0
	ds_read_b128 v[134:137], v200 offset:2048
	ds_read_b128 v[138:141], v200 offset:4096
	ds_read_b128 v[142:145], v200 offset:6144
	ds_read_b128 v[162:165], v202 offset:32768
	ds_read_b128 v[166:169], v202 offset:34816
	ds_read_b128 v[170:173], v202 offset:36864
	ds_read_b128 v[174:177], v202 offset:38912
	s_add_i32 m0, s21, 0x14000
	s_add_u32 s40, s36, 0xb0080
	s_addc_u32 s41, s37, 0
	global_load_lds_dwordx4 v1, s[40:41]
	s_add_i32 m0, s21, 0x1a000
	s_add_u32 s40, s38, 0x58080
	s_addc_u32 s41, s39, 0
	global_load_lds_dwordx4 v1, s[40:41]
	s_waitcnt vmcnt(4)
	s_barrier
	s_waitcnt lgkmcnt(0)
	v_mfma_f32_16x16x32_f16 v[126:129], v[162:165], v[130:133], v[126:129]
	v_mfma_f32_16x16x32_f16 v[122:125], v[166:169], v[130:133], v[122:125]
	v_mfma_f32_16x16x32_f16 v[118:121], v[170:173], v[130:133], v[118:121]
	v_mfma_f32_16x16x32_f16 v[114:117], v[174:177], v[130:133], v[114:117]
	v_mfma_f32_16x16x32_f16 v[110:113], v[162:165], v[134:137], v[110:113]
	v_mfma_f32_16x16x32_f16 v[106:109], v[166:169], v[134:137], v[106:109]
	v_mfma_f32_16x16x32_f16 v[102:105], v[170:173], v[134:137], v[102:105]
	v_mfma_f32_16x16x32_f16 v[98:101], v[174:177], v[134:137], v[98:101]
	v_mfma_f32_16x16x32_f16 v[94:97], v[162:165], v[138:141], v[94:97]
	v_mfma_f32_16x16x32_f16 v[90:93], v[166:169], v[138:141], v[90:93]
	v_mfma_f32_16x16x32_f16 v[86:89], v[170:173], v[138:141], v[86:89]
	v_mfma_f32_16x16x32_f16 v[82:85], v[174:177], v[138:141], v[82:85]
	v_mfma_f32_16x16x32_f16 v[78:81], v[162:165], v[142:145], v[78:81]
	v_mfma_f32_16x16x32_f16 v[74:77], v[166:169], v[142:145], v[74:77]
	v_mfma_f32_16x16x32_f16 v[70:73], v[170:173], v[142:145], v[70:73]
	v_mfma_f32_16x16x32_f16 v[66:69], v[174:177], v[142:145], v[66:69]
	s_barrier
	ds_read_b128 v[146:149], v200 offset:8192
	ds_read_b128 v[150:153], v200 offset:10240
	ds_read_b128 v[154:157], v200 offset:12288
	ds_read_b128 v[158:161], v200 offset:14336
	s_add_i32 m0, s21, 0x1c000
	s_add_u32 s40, s38, 0xb0080
	s_addc_u32 s41, s39, 0
	global_load_lds_dwordx4 v1, s[40:41]
	s_add_i32 m0, s21, 0x1e000
	s_add_u32 s40, s38, 0x108080
	s_addc_u32 s41, s39, 0
	global_load_lds_dwordx4 v1, s[40:41]
	s_barrier
	s_waitcnt lgkmcnt(0)
	v_mfma_f32_16x16x32_f16 v[62:65], v[162:165], v[146:149], v[62:65]
	v_mfma_f32_16x16x32_f16 v[58:61], v[166:169], v[146:149], v[58:61]
	v_mfma_f32_16x16x32_f16 v[54:57], v[170:173], v[146:149], v[54:57]
	v_mfma_f32_16x16x32_f16 v[50:53], v[174:177], v[146:149], v[50:53]
	v_mfma_f32_16x16x32_f16 v[46:49], v[162:165], v[150:153], v[46:49]
	v_mfma_f32_16x16x32_f16 v[42:45], v[166:169], v[150:153], v[42:45]
	v_mfma_f32_16x16x32_f16 v[38:41], v[170:173], v[150:153], v[38:41]
	v_mfma_f32_16x16x32_f16 v[34:37], v[174:177], v[150:153], v[34:37]
	v_mfma_f32_16x16x32_f16 v[30:33], v[162:165], v[154:157], v[30:33]
	v_mfma_f32_16x16x32_f16 v[26:29], v[166:169], v[154:157], v[26:29]
	v_mfma_f32_16x16x32_f16 v[22:25], v[170:173], v[154:157], v[22:25]
	v_mfma_f32_16x16x32_f16 v[18:21], v[174:177], v[154:157], v[18:21]
	v_mfma_f32_16x16x32_f16 v[14:17], v[162:165], v[158:161], v[14:17]
	v_mfma_f32_16x16x32_f16 v[10:13], v[166:169], v[158:161], v[10:13]
	v_mfma_f32_16x16x32_f16 v[6:9], v[170:173], v[158:161], v[6:9]
	v_mfma_f32_16x16x32_f16 v[2:5], v[174:177], v[158:161], v[2:5]
	s_barrier
	ds_read_b128 v[130:133], v201 offset:0
	ds_read_b128 v[134:137], v201 offset:2048
	ds_read_b128 v[138:141], v201 offset:4096
	ds_read_b128 v[142:145], v201 offset:6144
	ds_read_b128 v[162:165], v203 offset:32768
	ds_read_b128 v[166:169], v203 offset:34816
	ds_read_b128 v[170:173], v203 offset:36864
	ds_read_b128 v[174:177], v203 offset:38912
	s_add_i32 m0, s21, 0x12000
	s_add_u32 s40, s36, 0x58080
	s_addc_u32 s41, s37, 0
	global_load_lds_dwordx4 v1, s[40:41]
	s_add_i32 m0, s21, 0x16000
	s_add_u32 s40, s36, 0x108080
	s_addc_u32 s41, s37, 0
	global_load_lds_dwordx4 v1, s[40:41]
	s_waitcnt lgkmcnt(0)
	s_barrier
	v_mfma_f32_16x16x32_f16 v[126:129], v[162:165], v[130:133], v[126:129]
	v_mfma_f32_16x16x32_f16 v[122:125], v[166:169], v[130:133], v[122:125]
	v_mfma_f32_16x16x32_f16 v[118:121], v[170:173], v[130:133], v[118:121]
	v_mfma_f32_16x16x32_f16 v[114:117], v[174:177], v[130:133], v[114:117]
	v_mfma_f32_16x16x32_f16 v[110:113], v[162:165], v[134:137], v[110:113]
	v_mfma_f32_16x16x32_f16 v[106:109], v[166:169], v[134:137], v[106:109]
	v_mfma_f32_16x16x32_f16 v[102:105], v[170:173], v[134:137], v[102:105]
	v_mfma_f32_16x16x32_f16 v[98:101], v[174:177], v[134:137], v[98:101]
	v_mfma_f32_16x16x32_f16 v[94:97], v[162:165], v[138:141], v[94:97]
	v_mfma_f32_16x16x32_f16 v[90:93], v[166:169], v[138:141], v[90:93]
	v_mfma_f32_16x16x32_f16 v[86:89], v[170:173], v[138:141], v[86:89]
	v_mfma_f32_16x16x32_f16 v[82:85], v[174:177], v[138:141], v[82:85]
	v_mfma_f32_16x16x32_f16 v[78:81], v[162:165], v[142:145], v[78:81]
	v_mfma_f32_16x16x32_f16 v[74:77], v[166:169], v[142:145], v[74:77]
	v_mfma_f32_16x16x32_f16 v[70:73], v[170:173], v[142:145], v[70:73]
	v_mfma_f32_16x16x32_f16 v[66:69], v[174:177], v[142:145], v[66:69]
	s_barrier
	ds_read_b128 v[146:149], v201 offset:8192
	ds_read_b128 v[150:153], v201 offset:10240
	ds_read_b128 v[154:157], v201 offset:12288
	ds_read_b128 v[158:161], v201 offset:14336
	s_waitcnt vmcnt(2)
	s_barrier
	s_waitcnt lgkmcnt(0)
	v_mfma_f32_16x16x32_f16 v[62:65], v[162:165], v[146:149], v[62:65]
	v_mfma_f32_16x16x32_f16 v[58:61], v[166:169], v[146:149], v[58:61]
	v_mfma_f32_16x16x32_f16 v[54:57], v[170:173], v[146:149], v[54:57]
	v_mfma_f32_16x16x32_f16 v[50:53], v[174:177], v[146:149], v[50:53]
	v_mfma_f32_16x16x32_f16 v[46:49], v[162:165], v[150:153], v[46:49]
	v_mfma_f32_16x16x32_f16 v[42:45], v[166:169], v[150:153], v[42:45]
	v_mfma_f32_16x16x32_f16 v[38:41], v[170:173], v[150:153], v[38:41]
	v_mfma_f32_16x16x32_f16 v[34:37], v[174:177], v[150:153], v[34:37]
	v_mfma_f32_16x16x32_f16 v[30:33], v[162:165], v[154:157], v[30:33]
	v_mfma_f32_16x16x32_f16 v[26:29], v[166:169], v[154:157], v[26:29]
	v_mfma_f32_16x16x32_f16 v[22:25], v[170:173], v[154:157], v[22:25]
	v_mfma_f32_16x16x32_f16 v[18:21], v[174:177], v[154:157], v[18:21]
	v_mfma_f32_16x16x32_f16 v[14:17], v[162:165], v[158:161], v[14:17]
	v_mfma_f32_16x16x32_f16 v[10:13], v[166:169], v[158:161], v[10:13]
	v_mfma_f32_16x16x32_f16 v[6:9], v[170:173], v[158:161], v[6:9]
	v_mfma_f32_16x16x32_f16 v[2:5], v[174:177], v[158:161], v[2:5]
	s_barrier
	s_add_u32 s36, s36, 0x80
	s_addc_u32 s37, s37, 0
	s_add_u32 s38, s38, 0x80
	s_addc_u32 s39, s39, 0
	ds_read_b128 v[130:133], v204 offset:0
	ds_read_b128 v[134:137], v204 offset:2048
	ds_read_b128 v[138:141], v204 offset:4096
	ds_read_b128 v[142:145], v204 offset:6144
	ds_read_b128 v[162:165], v206 offset:32768
	ds_read_b128 v[166:169], v206 offset:34816
	ds_read_b128 v[170:173], v206 offset:36864
	ds_read_b128 v[174:177], v206 offset:38912
	s_waitcnt vmcnt(0)
	s_barrier
	s_waitcnt lgkmcnt(0)
	v_mfma_f32_16x16x32_f16 v[126:129], v[162:165], v[130:133], v[126:129]
	v_mfma_f32_16x16x32_f16 v[122:125], v[166:169], v[130:133], v[122:125]
	v_mfma_f32_16x16x32_f16 v[118:121], v[170:173], v[130:133], v[118:121]
	v_mfma_f32_16x16x32_f16 v[114:117], v[174:177], v[130:133], v[114:117]
	v_mfma_f32_16x16x32_f16 v[110:113], v[162:165], v[134:137], v[110:113]
	v_mfma_f32_16x16x32_f16 v[106:109], v[166:169], v[134:137], v[106:109]
	v_mfma_f32_16x16x32_f16 v[102:105], v[170:173], v[134:137], v[102:105]
	v_mfma_f32_16x16x32_f16 v[98:101], v[174:177], v[134:137], v[98:101]
	v_mfma_f32_16x16x32_f16 v[94:97], v[162:165], v[138:141], v[94:97]
	v_mfma_f32_16x16x32_f16 v[90:93], v[166:169], v[138:141], v[90:93]
	v_mfma_f32_16x16x32_f16 v[86:89], v[170:173], v[138:141], v[86:89]
	v_mfma_f32_16x16x32_f16 v[82:85], v[174:177], v[138:141], v[82:85]
	v_mfma_f32_16x16x32_f16 v[78:81], v[162:165], v[142:145], v[78:81]
	v_mfma_f32_16x16x32_f16 v[74:77], v[166:169], v[142:145], v[74:77]
	v_mfma_f32_16x16x32_f16 v[70:73], v[170:173], v[142:145], v[70:73]
	v_mfma_f32_16x16x32_f16 v[66:69], v[174:177], v[142:145], v[66:69]
	s_barrier
	ds_read_b128 v[146:149], v204 offset:8192
	ds_read_b128 v[150:153], v204 offset:10240
	ds_read_b128 v[154:157], v204 offset:12288
	ds_read_b128 v[158:161], v204 offset:14336
	s_barrier
	s_waitcnt lgkmcnt(0)
	v_mfma_f32_16x16x32_f16 v[62:65], v[162:165], v[146:149], v[62:65]
	v_mfma_f32_16x16x32_f16 v[58:61], v[166:169], v[146:149], v[58:61]
	v_mfma_f32_16x16x32_f16 v[54:57], v[170:173], v[146:149], v[54:57]
	v_mfma_f32_16x16x32_f16 v[50:53], v[174:177], v[146:149], v[50:53]
	v_mfma_f32_16x16x32_f16 v[46:49], v[162:165], v[150:153], v[46:49]
	v_mfma_f32_16x16x32_f16 v[42:45], v[166:169], v[150:153], v[42:45]
	v_mfma_f32_16x16x32_f16 v[38:41], v[170:173], v[150:153], v[38:41]
	v_mfma_f32_16x16x32_f16 v[34:37], v[174:177], v[150:153], v[34:37]
	v_mfma_f32_16x16x32_f16 v[30:33], v[162:165], v[154:157], v[30:33]
	v_mfma_f32_16x16x32_f16 v[26:29], v[166:169], v[154:157], v[26:29]
	v_mfma_f32_16x16x32_f16 v[22:25], v[170:173], v[154:157], v[22:25]
	v_mfma_f32_16x16x32_f16 v[18:21], v[174:177], v[154:157], v[18:21]
	v_mfma_f32_16x16x32_f16 v[14:17], v[162:165], v[158:161], v[14:17]
	v_mfma_f32_16x16x32_f16 v[10:13], v[166:169], v[158:161], v[10:13]
	v_mfma_f32_16x16x32_f16 v[6:9], v[170:173], v[158:161], v[6:9]
	v_mfma_f32_16x16x32_f16 v[2:5], v[174:177], v[158:161], v[2:5]
	s_barrier
	ds_read_b128 v[130:133], v205 offset:0
	ds_read_b128 v[134:137], v205 offset:2048
	ds_read_b128 v[138:141], v205 offset:4096
	ds_read_b128 v[142:145], v205 offset:6144
	ds_read_b128 v[162:165], v207 offset:32768
	ds_read_b128 v[166:169], v207 offset:34816
	ds_read_b128 v[170:173], v207 offset:36864
	ds_read_b128 v[174:177], v207 offset:38912
	s_waitcnt lgkmcnt(0)
	s_barrier
	v_mfma_f32_16x16x32_f16 v[126:129], v[162:165], v[130:133], v[126:129]
	v_mfma_f32_16x16x32_f16 v[122:125], v[166:169], v[130:133], v[122:125]
	v_mfma_f32_16x16x32_f16 v[118:121], v[170:173], v[130:133], v[118:121]
	v_mfma_f32_16x16x32_f16 v[114:117], v[174:177], v[130:133], v[114:117]
	v_mfma_f32_16x16x32_f16 v[110:113], v[162:165], v[134:137], v[110:113]
	v_mfma_f32_16x16x32_f16 v[106:109], v[166:169], v[134:137], v[106:109]
	v_mfma_f32_16x16x32_f16 v[102:105], v[170:173], v[134:137], v[102:105]
	v_mfma_f32_16x16x32_f16 v[98:101], v[174:177], v[134:137], v[98:101]
	v_mfma_f32_16x16x32_f16 v[94:97], v[162:165], v[138:141], v[94:97]
	v_mfma_f32_16x16x32_f16 v[90:93], v[166:169], v[138:141], v[90:93]
	v_mfma_f32_16x16x32_f16 v[86:89], v[170:173], v[138:141], v[86:89]
	v_mfma_f32_16x16x32_f16 v[82:85], v[174:177], v[138:141], v[82:85]
	v_mfma_f32_16x16x32_f16 v[78:81], v[162:165], v[142:145], v[78:81]
	v_mfma_f32_16x16x32_f16 v[74:77], v[166:169], v[142:145], v[74:77]
	v_mfma_f32_16x16x32_f16 v[70:73], v[170:173], v[142:145], v[70:73]
	v_mfma_f32_16x16x32_f16 v[66:69], v[174:177], v[142:145], v[66:69]
	s_barrier
	ds_read_b128 v[146:149], v205 offset:8192
	ds_read_b128 v[150:153], v205 offset:10240
	ds_read_b128 v[154:157], v205 offset:12288
	ds_read_b128 v[158:161], v205 offset:14336
	s_barrier
	s_waitcnt lgkmcnt(0)
	v_mfma_f32_16x16x32_f16 v[62:65], v[162:165], v[146:149], v[62:65]
	v_mfma_f32_16x16x32_f16 v[58:61], v[166:169], v[146:149], v[58:61]
	v_mfma_f32_16x16x32_f16 v[54:57], v[170:173], v[146:149], v[54:57]
	v_mfma_f32_16x16x32_f16 v[50:53], v[174:177], v[146:149], v[50:53]
	v_mfma_f32_16x16x32_f16 v[46:49], v[162:165], v[150:153], v[46:49]
	v_mfma_f32_16x16x32_f16 v[42:45], v[166:169], v[150:153], v[42:45]
	v_mfma_f32_16x16x32_f16 v[38:41], v[170:173], v[150:153], v[38:41]
	v_mfma_f32_16x16x32_f16 v[34:37], v[174:177], v[150:153], v[34:37]
	v_mfma_f32_16x16x32_f16 v[30:33], v[162:165], v[154:157], v[30:33]
	v_mfma_f32_16x16x32_f16 v[26:29], v[166:169], v[154:157], v[26:29]
	v_mfma_f32_16x16x32_f16 v[22:25], v[170:173], v[154:157], v[22:25]
	v_mfma_f32_16x16x32_f16 v[18:21], v[174:177], v[154:157], v[18:21]
	v_mfma_f32_16x16x32_f16 v[14:17], v[162:165], v[158:161], v[14:17]
	v_mfma_f32_16x16x32_f16 v[10:13], v[166:169], v[158:161], v[10:13]
	v_mfma_f32_16x16x32_f16 v[6:9], v[170:173], v[158:161], v[6:9]
	v_mfma_f32_16x16x32_f16 v[2:5], v[174:177], v[158:161], v[2:5]
	s_barrier
	s_cmp_eq_u32 s22, 1
	s_cbranch_scc1 .Lp5_skew1
	s_barrier
